# up-proj epilogue: scalar bias+w2*x FMAs merged pairwise into v_pk_fma_f32; pooldiff prologue loads batched
# speedup vs baseline: 1.0432x; 1.0049x over previous
.LBB0_563:
	s_or_b64 exec, exec, s[48:49]
	s_waitcnt lgkmcnt(0)
	s_barrier
	ds_read_b128 v[150:153], v223 offset:512
	ds_read_b128 v[154:157], v223 offset:1536
	ds_read_b128 v[162:165], v223 offset:2560
	ds_read_b128 v[138:141], v223 offset:3584
	v_mov_b32_e32 v158, 0
	v_mov_b32_e32 v159, 0
	v_mov_b32_e32 v160, 0
	v_mov_b32_e32 v161, 0
	s_and_saveexec_b64 s[48:49], s[30:31]
	v_add_u32_e32 v1, s91, v215
	ds_read_b128 v[158:161], v1 offset:512
	s_or_b64 exec, exec, s[48:49]
	v_lshl_add_u32 v1, s28, 1, v173
	v_mad_i64_i32 v[206:207], s[48:49], v1, s76, 0
	v_fmamk_f32 v1, v149, 0x3a800000, v222
	v_rsq_f32_e32 v196, v1
	v_fmamk_f32 v1, v146, 0x3a800000, v222
	v_rsq_f32_e32 v198, v1
	s_waitcnt lgkmcnt(0)
	v_fma_f32 v146, v166, v162, v138
	s_nop 4
	v_fmac_f32_dpp v146, v166, v154 row_shr:1 row_mask:0xf bank_mask:0xf
	v_fmamk_f32 v147, v148, 0x3a800000, v222
	v_fmac_f32_dpp v146, v166, v150 row_shr:2 row_mask:0xf bank_mask:0xf
	v_rsq_f32_e32 v194, v147
	v_pk_fma_f32 v[78:79], v[78:79], v[198:199], v[122:123] op_sel_hi:[1,0,1]
	v_fma_f32 v147, v167, v163, v139
	v_fmac_f32_dpp v146, v78, v154 row_shl:15 row_mask:0xf bank_mask:0xf
	v_pk_fma_f32 v[148:149], v[168:169], v[164:165], v[140:141]
	v_fmac_f32_dpp v146, v78, v150 row_shl:14 row_mask:0xf bank_mask:0xf
	v_fmac_f32_dpp v147, v167, v155 row_shr:1 row_mask:0xf bank_mask:0xf
	v_pk_fma_f32 v[80:81], v[80:81], v[198:199], v[124:125] op_sel_hi:[1,0,1]
	v_fmac_f32_dpp v147, v167, v151 row_shr:2 row_mask:0xf bank_mask:0xf
	s_nop 0
	v_fmac_f32_dpp v147, v79, v155 row_shl:15 row_mask:0xf bank_mask:0xf
	v_pk_fma_f32 v[224:225], v[130:131], v[196:197], v[122:123] op_sel_hi:[1,0,1]
	v_fmac_f32_dpp v147, v79, v151 row_shl:14 row_mask:0xf bank_mask:0xf
	v_fmac_f32_dpp v148, v168, v156 row_shr:1 row_mask:0xf bank_mask:0xf
	v_pk_fma_f32 v[130:131], v[78:79], v[162:163], v[138:139]
	v_fmac_f32_dpp v148, v168, v152 row_shr:2 row_mask:0xf bank_mask:0xf
	s_nop 0
	v_fmac_f32_dpp v148, v80, v156 row_shl:15 row_mask:0xf bank_mask:0xf
	v_pk_fma_f32 v[208:209], v[132:133], v[196:197], v[124:125] op_sel_hi:[1,0,1]
	v_fmac_f32_dpp v148, v80, v152 row_shl:14 row_mask:0xf bank_mask:0xf
	v_fmac_f32_dpp v149, v169, v157 row_shr:1 row_mask:0xf bank_mask:0xf
	v_pk_fma_f32 v[132:133], v[80:81], v[164:165], v[140:141]
	v_fmac_f32_dpp v149, v169, v153 row_shr:2 row_mask:0xf bank_mask:0xf
	s_nop 0
	v_fmac_f32_dpp v149, v81, v157 row_shl:15 row_mask:0xf bank_mask:0xf
	v_pk_fma_f32 v[134:135], v[134:135], v[194:195], v[122:123] op_sel_hi:[1,0,1]
	v_fmac_f32_dpp v149, v81, v153 row_shl:14 row_mask:0xf bank_mask:0xf
	v_pk_fma_f32 v[136:137], v[136:137], v[194:195], v[124:125] op_sel_hi:[1,0,1]
	v_fmac_f32_dpp v130, v78, v154 row_shr:1 row_mask:0xf bank_mask:0xf
	s_lshl_b32 s46, s46, 7
	v_fmac_f32_dpp v130, v78, v150 row_shr:2 row_mask:0xf bank_mask:0xf
	v_fma_f32 v78, v224, v162, v138
	v_fmac_f32_dpp v130, v224, v154 row_shl:15 row_mask:0xf bank_mask:0xf
	v_fma_f32 v138, v134, v162, v138
	v_fmac_f32_dpp v130, v224, v150 row_shl:14 row_mask:0xf bank_mask:0xf
	v_fmac_f32_dpp v131, v79, v155 row_shr:1 row_mask:0xf bank_mask:0xf
	v_or_b32_e32 v200, s46, v184
	v_fmac_f32_dpp v131, v79, v151 row_shr:2 row_mask:0xf bank_mask:0xf
	v_fma_f32 v79, v225, v163, v139
	v_fmac_f32_dpp v131, v225, v155 row_shl:15 row_mask:0xf bank_mask:0xf
	v_fma_f32 v139, v135, v163, v139
	v_fmac_f32_dpp v131, v225, v151 row_shl:14 row_mask:0xf bank_mask:0xf
	v_fmac_f32_dpp v132, v80, v156 row_shr:1 row_mask:0xf bank_mask:0xf
	v_ashrrev_i32_e32 v201, 31, v200
	v_fmac_f32_dpp v132, v80, v152 row_shr:2 row_mask:0xf bank_mask:0xf
	v_fma_f32 v80, v208, v164, v140
	v_fmac_f32_dpp v132, v208, v156 row_shl:15 row_mask:0xf bank_mask:0xf
	v_fma_f32 v140, v136, v164, v140
	v_fmac_f32_dpp v132, v208, v152 row_shl:14 row_mask:0xf bank_mask:0xf
	v_fmac_f32_dpp v133, v81, v157 row_shr:1 row_mask:0xf bank_mask:0xf
	v_lshl_add_u64 v[168:169], s[24:25], 0, v[206:207]
	v_fmac_f32_dpp v133, v81, v153 row_shr:2 row_mask:0xf bank_mask:0xf
	v_fma_f32 v81, v209, v165, v141
	v_fmac_f32_dpp v133, v209, v157 row_shl:15 row_mask:0xf bank_mask:0xf
	v_fmac_f32_e32 v141, v137, v165
	v_fmac_f32_dpp v133, v209, v153 row_shl:14 row_mask:0xf bank_mask:0xf
	v_lshl_add_u64 v[166:167], v[200:201], 2, v[168:169]
	v_fmac_f32_dpp v78, v224, v154 row_shr:1 row_mask:0xf bank_mask:0xf
	s_nop 0
	v_fmac_f32_dpp v78, v224, v150 row_shr:2 row_mask:0xf bank_mask:0xf
	s_nop 0
	v_fmac_f32_dpp v78, v134, v154 row_shl:15 row_mask:0xf bank_mask:0xf
	s_nop 0
	v_fmac_f32_dpp v78, v134, v150 row_shl:14 row_mask:0xf bank_mask:0xf
	v_fmac_f32_dpp v79, v225, v155 row_shr:1 row_mask:0xf bank_mask:0xf
	s_nop 0
	v_fmac_f32_dpp v79, v225, v151 row_shr:2 row_mask:0xf bank_mask:0xf
	s_nop 0
	v_fmac_f32_dpp v79, v135, v155 row_shl:15 row_mask:0xf bank_mask:0xf
	s_nop 0
	v_fmac_f32_dpp v79, v135, v151 row_shl:14 row_mask:0xf bank_mask:0xf
	v_fmac_f32_dpp v80, v208, v156 row_shr:1 row_mask:0xf bank_mask:0xf
	s_nop 0
	v_fmac_f32_dpp v80, v208, v152 row_shr:2 row_mask:0xf bank_mask:0xf
	s_nop 0
	v_fmac_f32_dpp v80, v136, v156 row_shl:15 row_mask:0xf bank_mask:0xf
	s_nop 0
	v_fmac_f32_dpp v80, v136, v152 row_shl:14 row_mask:0xf bank_mask:0xf
	v_fmac_f32_dpp v81, v209, v157 row_shr:1 row_mask:0xf bank_mask:0xf
	s_nop 0
	v_fmac_f32_dpp v81, v209, v153 row_shr:2 row_mask:0xf bank_mask:0xf
	s_nop 0
	v_fmac_f32_dpp v81, v137, v157 row_shl:15 row_mask:0xf bank_mask:0xf
	s_nop 0
	v_fmac_f32_dpp v81, v137, v153 row_shl:14 row_mask:0xf bank_mask:0xf
	s_nop 0
	v_fmac_f32_dpp v138, v134, v154 row_shr:1 row_mask:0xf bank_mask:0xf
	s_nop 0
	v_fmac_f32_dpp v138, v134, v150 row_shr:2 row_mask:0xf bank_mask:0xf
	s_nop 0
	v_fmac_f32_dpp v138, v158, v154 row_shl:15 row_mask:0xf bank_mask:0xf
	s_nop 0
	v_fmac_f32_dpp v138, v158, v150 row_shl:14 row_mask:0xf bank_mask:0xf
	v_fmac_f32_dpp v139, v135, v155 row_shr:1 row_mask:0xf bank_mask:0xf
	s_nop 0
	v_fmac_f32_dpp v139, v135, v151 row_shr:2 row_mask:0xf bank_mask:0xf
	s_nop 0
	v_fmac_f32_dpp v139, v159, v155 row_shl:15 row_mask:0xf bank_mask:0xf
	s_nop 0
	v_fmac_f32_dpp v139, v159, v151 row_shl:14 row_mask:0xf bank_mask:0xf
	v_fmac_f32_dpp v140, v136, v156 row_shr:1 row_mask:0xf bank_mask:0xf
	s_nop 0
	v_fmac_f32_dpp v140, v136, v152 row_shr:2 row_mask:0xf bank_mask:0xf
	s_nop 0
	v_fmac_f32_dpp v140, v160, v156 row_shl:15 row_mask:0xf bank_mask:0xf
	s_nop 0
	v_fmac_f32_dpp v140, v160, v152 row_shl:14 row_mask:0xf bank_mask:0xf
	v_fmac_f32_dpp v141, v137, v157 row_shr:1 row_mask:0xf bank_mask:0xf
	s_nop 0
	v_fmac_f32_dpp v141, v137, v153 row_shr:2 row_mask:0xf bank_mask:0xf
	s_nop 0
	v_fmac_f32_dpp v141, v161, v157 row_shl:15 row_mask:0xf bank_mask:0xf
	s_nop 0
	v_fmac_f32_dpp v141, v161, v153 row_shl:14 row_mask:0xf bank_mask:0xf
	s_and_saveexec_b64 s[48:49], s[34:35]
	s_cbranch_execz .LBB0_567
	v_add_co_u32_e32 v134, vcc, 0x2000, v166
	s_nop 1
	v_addc_co_u32_e32 v135, vcc, 0, v167, vcc
	global_store_dwordx4 v[134:135], v[138:141], off offset:3072
.LBB0_567:
	s_or_b64 exec, exec, s[48:49]
	s_nop 0
	ds_read_b128 v[150:153], v223
	ds_read_b128 v[154:157], v223 offset:1024
	ds_read_b128 v[162:165], v223 offset:2048
	ds_read_b128 v[134:137], v223 offset:3072
	v_mov_b32_e32 v158, 0
	v_mov_b32_e32 v159, 0
	v_mov_b32_e32 v160, 0
	v_mov_b32_e32 v161, 0
	s_and_saveexec_b64 s[48:49], s[30:31]
	v_add_u32_e32 v1, 0, v215
	v_add_u32_e32 v1, 0x20000, v1
	ds_read_b128 v[158:161], v1
	s_or_b64 exec, exec, s[48:49]
	v_mov_b32_e32 v195, v194
	v_mov_b32_e32 v199, v198
	v_pk_fma_f32 v[208:209], v[62:63], v[194:195], v[118:119]
	v_mov_b32_e32 v62, v196
	v_mov_b32_e32 v63, v196
	v_pk_fma_f32 v[62:63], v[52:53], v[62:63], v[120:121]
	v_pk_fma_f32 v[52:53], v[46:47], v[198:199], v[118:119]
	s_waitcnt lgkmcnt(0)
	v_pk_fma_f32 v[46:47], v[142:143], v[162:163], v[134:135]
	s_nop 4
	v_fmac_f32_dpp v46, v142, v154 row_shr:1 row_mask:0xf bank_mask:0xf
	s_nop 0
	v_fmac_f32_dpp v46, v142, v150 row_shr:2 row_mask:0xf bank_mask:0xf
	v_mov_b32_e32 v197, v196
	v_fmac_f32_dpp v46, v52, v154 row_shl:15 row_mask:0xf bank_mask:0xf
	v_mov_b32_e32 v206, v194
	v_mov_b32_e32 v207, v194
	v_fmac_f32_dpp v46, v52, v150 row_shl:14 row_mask:0xf bank_mask:0xf
	v_fmac_f32_dpp v47, v143, v155 row_shr:1 row_mask:0xf bank_mask:0xf
	v_pk_fma_f32 v[206:207], v[64:65], v[206:207], v[120:121]
	v_pk_fma_f32 v[64:65], v[50:51], v[196:197], v[118:119]
	v_mov_b32_e32 v50, v198
	v_mov_b32_e32 v51, v198
	v_fmac_f32_dpp v47, v143, v151 row_shr:2 row_mask:0xf bank_mask:0xf
	v_pk_fma_f32 v[50:51], v[48:49], v[50:51], v[120:121]
	v_fmac_f32_dpp v47, v53, v155 row_shl:15 row_mask:0xf bank_mask:0xf
	v_pk_fma_f32 v[48:49], v[144:145], v[164:165], v[136:137]
	v_fmac_f32_dpp v47, v53, v151 row_shl:14 row_mask:0xf bank_mask:0xf
	v_fmac_f32_dpp v48, v144, v156 row_shr:1 row_mask:0xf bank_mask:0xf
	v_mul_f32_e32 v1, 0xbfb8aa3b, v46
	v_fmac_f32_dpp v48, v144, v152 row_shr:2 row_mask:0xf bank_mask:0xf
	v_exp_f32_e32 v1, v1
	v_fmac_f32_dpp v48, v50, v156 row_shl:15 row_mask:0xf bank_mask:0xf
	s_nop 0
	v_fmac_f32_dpp v48, v50, v152 row_shl:14 row_mask:0xf bank_mask:0xf
	v_fmac_f32_dpp v49, v145, v157 row_shr:1 row_mask:0xf bank_mask:0xf
	v_add_f32_e32 v1, 1.0, v1
	v_fmac_f32_dpp v49, v145, v153 row_shr:2 row_mask:0xf bank_mask:0xf
	v_mul_f32_e32 v143, 0xbfb8aa3b, v48
	v_fmac_f32_dpp v49, v51, v157 row_shl:15 row_mask:0xf bank_mask:0xf
	v_rcp_f32_e32 v142, v1
	v_fmac_f32_dpp v49, v51, v153 row_shl:14 row_mask:0xf bank_mask:0xf
	v_mul_f32_e32 v1, 0xbfb8aa3b, v47
	v_exp_f32_e32 v143, v143
	v_mul_f32_e32 v144, 0xbfb8aa3b, v49
	v_exp_f32_e32 v1, v1
	v_exp_f32_e32 v145, v144
	v_add_f32_e32 v143, 1.0, v143
	v_rcp_f32_e32 v144, v143
	v_add_f32_e32 v1, 1.0, v1
	v_add_f32_e32 v143, 1.0, v145
	v_rcp_f32_e32 v145, v143
	v_rcp_f32_e32 v143, v1
	v_pk_mul_f32 v[48:49], v[148:149], v[48:49]
	v_pk_mul_f32 v[46:47], v[146:147], v[46:47]
	v_pk_mul_f32 v[48:49], v[48:49], v[144:145]
	v_pk_mul_f32 v[46:47], v[46:47], v[142:143]
	v_pk_fma_f32 v[142:143], v[52:53], v[162:163], v[134:135]
	v_fmac_f32_dpp v142, v52, v154 row_shr:1 row_mask:0xf bank_mask:0xf
	s_nop 0
	v_fmac_f32_dpp v142, v52, v150 row_shr:2 row_mask:0xf bank_mask:0xf
	v_fma_f32 v52, v50, v164, v136
	v_fmac_f32_dpp v142, v64, v154 row_shl:15 row_mask:0xf bank_mask:0xf
	s_nop 0
	v_fmac_f32_dpp v142, v64, v150 row_shl:14 row_mask:0xf bank_mask:0xf
	v_fmac_f32_dpp v143, v53, v155 row_shr:1 row_mask:0xf bank_mask:0xf
	s_nop 0
	v_fmac_f32_dpp v143, v53, v151 row_shr:2 row_mask:0xf bank_mask:0xf
	v_mul_f32_e32 v1, 0xbfb8aa3b, v142
	v_fmac_f32_dpp v143, v65, v155 row_shl:15 row_mask:0xf bank_mask:0xf
	v_exp_f32_e32 v1, v1
	v_fmac_f32_dpp v143, v65, v151 row_shl:14 row_mask:0xf bank_mask:0xf
	v_fmac_f32_dpp v52, v50, v156 row_shr:1 row_mask:0xf bank_mask:0xf
	v_fma_f32 v53, v51, v165, v137
	v_fmac_f32_dpp v52, v50, v152 row_shr:2 row_mask:0xf bank_mask:0xf
	v_add_f32_e32 v1, 1.0, v1
	v_fmac_f32_dpp v52, v62, v156 row_shl:15 row_mask:0xf bank_mask:0xf
	v_rcp_f32_e32 v50, v1
	v_fmac_f32_dpp v52, v62, v152 row_shl:14 row_mask:0xf bank_mask:0xf
	v_fmac_f32_dpp v53, v51, v157 row_shr:1 row_mask:0xf bank_mask:0xf
	v_mul_f32_e32 v1, 0xbfb8aa3b, v143
	v_fmac_f32_dpp v53, v51, v153 row_shr:2 row_mask:0xf bank_mask:0xf
	v_mul_f32_e32 v51, 0xbfb8aa3b, v52
	v_fmac_f32_dpp v53, v63, v157 row_shl:15 row_mask:0xf bank_mask:0xf
	v_exp_f32_e32 v51, v51
	v_fmac_f32_dpp v53, v63, v153 row_shl:14 row_mask:0xf bank_mask:0xf
	v_exp_f32_e32 v1, v1
	v_mul_f32_e32 v144, 0xbfb8aa3b, v53
	v_exp_f32_e32 v145, v144
	v_add_f32_e32 v51, 1.0, v51
	v_add_f32_e32 v1, 1.0, v1
	v_rcp_f32_e32 v144, v51
	v_add_f32_e32 v51, 1.0, v145
	v_rcp_f32_e32 v145, v51
	v_rcp_f32_e32 v51, v1
	v_pk_mul_f32 v[52:53], v[132:133], v[52:53]
	v_pk_mul_f32 v[130:131], v[130:131], v[142:143]
	v_pk_mul_f32 v[52:53], v[52:53], v[144:145]
	v_pk_mul_f32 v[50:51], v[130:131], v[50:51]
	v_pk_fma_f32 v[130:131], v[64:65], v[162:163], v[134:135]
	v_fmac_f32_dpp v130, v64, v154 row_shr:1 row_mask:0xf bank_mask:0xf
	s_nop 0
	v_fmac_f32_dpp v130, v64, v150 row_shr:2 row_mask:0xf bank_mask:0xf
	v_fma_f32 v64, v62, v164, v136
	v_fmac_f32_dpp v130, v208, v154 row_shl:15 row_mask:0xf bank_mask:0xf
	v_pk_fma_f32 v[134:135], v[208:209], v[162:163], v[134:135]
	v_fmac_f32_dpp v130, v208, v150 row_shl:14 row_mask:0xf bank_mask:0xf
	v_fmac_f32_dpp v131, v65, v155 row_shr:1 row_mask:0xf bank_mask:0xf
	s_nop 0
	v_fmac_f32_dpp v131, v65, v151 row_shr:2 row_mask:0xf bank_mask:0xf
	v_mul_f32_e32 v1, 0xbfb8aa3b, v130
	v_fmac_f32_dpp v131, v209, v155 row_shl:15 row_mask:0xf bank_mask:0xf
	v_exp_f32_e32 v1, v1
	v_fmac_f32_dpp v131, v209, v151 row_shl:14 row_mask:0xf bank_mask:0xf
	v_fmac_f32_dpp v64, v62, v156 row_shr:1 row_mask:0xf bank_mask:0xf
	v_fma_f32 v65, v63, v165, v137
	v_fmac_f32_dpp v64, v62, v152 row_shr:2 row_mask:0xf bank_mask:0xf
	v_add_f32_e32 v1, 1.0, v1
	v_fmac_f32_dpp v64, v206, v156 row_shl:15 row_mask:0xf bank_mask:0xf
	v_rcp_f32_e32 v62, v1
	v_fmac_f32_dpp v64, v206, v152 row_shl:14 row_mask:0xf bank_mask:0xf
	v_fmac_f32_dpp v65, v63, v157 row_shr:1 row_mask:0xf bank_mask:0xf
	v_mul_f32_e32 v1, 0xbfb8aa3b, v131
	v_fmac_f32_dpp v65, v63, v153 row_shr:2 row_mask:0xf bank_mask:0xf
	v_mul_f32_e32 v63, 0xbfb8aa3b, v64
	v_fmac_f32_dpp v65, v207, v157 row_shl:15 row_mask:0xf bank_mask:0xf
	v_exp_f32_e32 v63, v63
	v_fmac_f32_dpp v65, v207, v153 row_shl:14 row_mask:0xf bank_mask:0xf
	v_exp_f32_e32 v1, v1
	v_mul_f32_e32 v132, 0xbfb8aa3b, v65
	v_exp_f32_e32 v133, v132
	v_add_f32_e32 v63, 1.0, v63
	v_add_f32_e32 v1, 1.0, v1
	v_rcp_f32_e32 v132, v63
	v_add_f32_e32 v63, 1.0, v133
	v_rcp_f32_e32 v133, v63
	v_rcp_f32_e32 v63, v1
	v_pk_mul_f32 v[64:65], v[80:81], v[64:65]
	v_pk_mul_f32 v[78:79], v[78:79], v[130:131]
	v_pk_mul_f32 v[64:65], v[64:65], v[132:133]
	v_pk_mul_f32 v[62:63], v[78:79], v[62:63]
	v_pk_fma_f32 v[136:137], v[206:207], v[164:165], v[136:137]
	v_fmac_f32_dpp v134, v208, v154 row_shr:1 row_mask:0xf bank_mask:0xf
	s_nop 0
	v_fmac_f32_dpp v134, v208, v150 row_shr:2 row_mask:0xf bank_mask:0xf
	s_nop 0
	v_fmac_f32_dpp v134, v158, v154 row_shl:15 row_mask:0xf bank_mask:0xf
	s_nop 0
	v_fmac_f32_dpp v134, v158, v150 row_shl:14 row_mask:0xf bank_mask:0xf
	v_fmac_f32_dpp v135, v209, v155 row_shr:1 row_mask:0xf bank_mask:0xf
	s_nop 0
	v_fmac_f32_dpp v135, v209, v151 row_shr:2 row_mask:0xf bank_mask:0xf
	s_nop 0
	v_fmac_f32_dpp v135, v159, v155 row_shl:15 row_mask:0xf bank_mask:0xf
	s_nop 0
	v_fmac_f32_dpp v135, v159, v151 row_shl:14 row_mask:0xf bank_mask:0xf
	v_fmac_f32_dpp v136, v206, v156 row_shr:1 row_mask:0xf bank_mask:0xf
	s_nop 0
	v_fmac_f32_dpp v136, v206, v152 row_shr:2 row_mask:0xf bank_mask:0xf
	s_nop 0
	v_fmac_f32_dpp v136, v160, v156 row_shl:15 row_mask:0xf bank_mask:0xf
	s_nop 0
	v_fmac_f32_dpp v136, v160, v152 row_shl:14 row_mask:0xf bank_mask:0xf
	v_fmac_f32_dpp v137, v207, v157 row_shr:1 row_mask:0xf bank_mask:0xf
	s_nop 0
	v_fmac_f32_dpp v137, v207, v153 row_shr:2 row_mask:0xf bank_mask:0xf
	s_nop 0
	v_fmac_f32_dpp v137, v161, v157 row_shl:15 row_mask:0xf bank_mask:0xf
	s_nop 0
	v_fmac_f32_dpp v137, v161, v153 row_shl:14 row_mask:0xf bank_mask:0xf
	s_and_saveexec_b64 s[48:49], s[34:35]
	s_cbranch_execz .LBB0_571
	global_store_dwordx4 v[166:167], v[134:137], off
.LBB0_571:
	s_or_b64 exec, exec, s[48:49]
	v_mul_f32_e32 v1, 0xbfb8aa3b, v134
	v_exp_f32_e32 v1, v1
	v_mul_f32_e32 v78, 0xbfb8aa3b, v135
	v_mul_f32_e32 v79, 0xbfb8aa3b, v136
	v_exp_f32_e32 v80, v78
	v_add_f32_e32 v1, 1.0, v1
	v_rcp_f32_e32 v78, v1
	v_exp_f32_e32 v1, v79
	v_mul_f32_e32 v79, 0xbfb8aa3b, v137
	v_exp_f32_e32 v79, v79
	v_add_f32_e32 v130, 1.0, v80
	v_add_f32_e32 v1, 1.0, v1
	v_rcp_f32_e32 v80, v1
	v_add_f32_e32 v1, 1.0, v79
	v_rcp_f32_e32 v81, v1
	v_rcp_f32_e32 v79, v130
	v_pk_mul_f32 v[130:131], v[140:141], v[136:137]
	v_pk_mul_f32 v[132:133], v[138:139], v[134:135]
	v_pk_mul_f32 v[80:81], v[130:131], v[80:81]
	v_pk_mul_f32 v[78:79], v[132:133], v[78:79]
	v_mov_b32_e32 v134, 0
	ds_read_b128 v[142:145], v223 offset:512
	ds_read_b128 v[146:149], v223 offset:1536
	ds_read_b128 v[154:157], v223 offset:2560
	ds_read_b128 v[130:133], v223 offset:3584
	v_mov_b32_e32 v150, 0
	v_mov_b32_e32 v151, 0
	v_mov_b32_e32 v152, 0
	v_mov_b32_e32 v153, 0
	s_and_saveexec_b64 s[48:49], s[0:1]
	v_add_u32_e32 v1, s91, v216
	ds_read_b128 v[150:153], v1 offset:512
	s_or_b64 exec, exec, s[48:49]
	v_fmamk_f32 v135, v202, 0x3a800000, v222
	v_rsq_f32_e32 v160, v135
	s_waitcnt lgkmcnt(0)
	v_pk_fma_f32 v[138:139], v[126:127], v[154:155], v[130:131]
	s_nop 4
	v_fmac_f32_dpp v138, v126, v146 row_shr:1 row_mask:0xf bank_mask:0xf
	v_pk_fma_f32 v[102:103], v[102:103], v[160:161], v[122:123] op_sel_hi:[1,0,1]
	v_fmac_f32_dpp v138, v126, v142 row_shr:2 row_mask:0xf bank_mask:0xf
	s_nop 0
	v_fmac_f32_dpp v138, v102, v146 row_shl:15 row_mask:0xf bank_mask:0xf
	v_pk_fma_f32 v[140:141], v[128:129], v[156:157], v[132:133]
	v_fmac_f32_dpp v138, v102, v142 row_shl:14 row_mask:0xf bank_mask:0xf
	v_fmac_f32_dpp v139, v127, v147 row_shr:1 row_mask:0xf bank_mask:0xf
	v_fmamk_f32 v1, v204, 0x3a800000, v222
	v_fmac_f32_dpp v139, v127, v143 row_shr:2 row_mask:0xf bank_mask:0xf
	v_rsq_f32_e32 v158, v1
	v_fmac_f32_dpp v139, v103, v147 row_shl:15 row_mask:0xf bank_mask:0xf
	v_fmamk_f32 v1, v205, 0x3a800000, v222
	v_fmac_f32_dpp v139, v103, v143 row_shl:14 row_mask:0xf bank_mask:0xf
	v_fmac_f32_dpp v140, v128, v148 row_shr:1 row_mask:0xf bank_mask:0xf
	v_rsq_f32_e32 v162, v1
	v_fmac_f32_dpp v140, v128, v144 row_shr:2 row_mask:0xf bank_mask:0xf
	v_pk_fma_f32 v[104:105], v[104:105], v[160:161], v[124:125] op_sel_hi:[1,0,1]
	s_nop 0
	v_fmac_f32_dpp v140, v104, v148 row_shl:15 row_mask:0xf bank_mask:0xf
	v_pk_fma_f32 v[164:165], v[106:107], v[162:163], v[122:123] op_sel_hi:[1,0,1]
	v_fmac_f32_dpp v140, v104, v144 row_shl:14 row_mask:0xf bank_mask:0xf
	v_fmac_f32_dpp v141, v129, v149 row_shr:1 row_mask:0xf bank_mask:0xf
	v_pk_fma_f32 v[106:107], v[102:103], v[154:155], v[130:131]
	v_fmac_f32_dpp v141, v129, v145 row_shr:2 row_mask:0xf bank_mask:0xf
	s_nop 0
	v_fmac_f32_dpp v141, v105, v149 row_shl:15 row_mask:0xf bank_mask:0xf
	v_pk_fma_f32 v[136:137], v[108:109], v[162:163], v[124:125] op_sel_hi:[1,0,1]
	v_fmac_f32_dpp v141, v105, v145 row_shl:14 row_mask:0xf bank_mask:0xf
	v_pk_fma_f32 v[108:109], v[104:105], v[156:157], v[132:133]
	v_fmac_f32_dpp v106, v102, v146 row_shr:1 row_mask:0xf bank_mask:0xf
	s_nop 0
	v_fmac_f32_dpp v106, v102, v142 row_shr:2 row_mask:0xf bank_mask:0xf
	v_fma_f32 v102, v164, v154, v130
	v_fmac_f32_dpp v106, v164, v146 row_shl:15 row_mask:0xf bank_mask:0xf
	v_pk_fma_f32 v[110:111], v[110:111], v[158:159], v[122:123] op_sel_hi:[1,0,1]
	v_fmac_f32_dpp v106, v164, v142 row_shl:14 row_mask:0xf bank_mask:0xf
	v_fmac_f32_dpp v107, v103, v147 row_shr:1 row_mask:0xf bank_mask:0xf
	v_pk_fma_f32 v[112:113], v[112:113], v[158:159], v[124:125] op_sel_hi:[1,0,1]
	v_fmac_f32_dpp v107, v103, v143 row_shr:2 row_mask:0xf bank_mask:0xf
	v_fma_f32 v103, v165, v155, v131
	v_fmac_f32_dpp v107, v165, v147 row_shl:15 row_mask:0xf bank_mask:0xf
	v_pk_fma_f32 v[130:131], v[110:111], v[154:155], v[130:131]
	v_fmac_f32_dpp v107, v165, v143 row_shl:14 row_mask:0xf bank_mask:0xf
	v_fmac_f32_dpp v108, v104, v148 row_shr:1 row_mask:0xf bank_mask:0xf
	s_nop 0
	v_fmac_f32_dpp v108, v104, v144 row_shr:2 row_mask:0xf bank_mask:0xf
	v_fma_f32 v104, v136, v156, v132
	v_fmac_f32_dpp v108, v136, v148 row_shl:15 row_mask:0xf bank_mask:0xf
	v_fma_f32 v132, v112, v156, v132
	v_fmac_f32_dpp v108, v136, v144 row_shl:14 row_mask:0xf bank_mask:0xf
	v_fmac_f32_dpp v109, v105, v149 row_shr:1 row_mask:0xf bank_mask:0xf
	v_mov_b32_e32 v135, 0
	v_fmac_f32_dpp v109, v105, v145 row_shr:2 row_mask:0xf bank_mask:0xf
	v_fma_f32 v105, v137, v157, v133
	v_fmac_f32_dpp v109, v137, v149 row_shl:15 row_mask:0xf bank_mask:0xf
	v_fmac_f32_e32 v133, v113, v157
	v_fmac_f32_dpp v109, v137, v145 row_shl:14 row_mask:0xf bank_mask:0xf
	s_nop 0
	v_fmac_f32_dpp v102, v164, v146 row_shr:1 row_mask:0xf bank_mask:0xf
	s_nop 0
	v_fmac_f32_dpp v102, v164, v142 row_shr:2 row_mask:0xf bank_mask:0xf
	s_nop 0
	v_fmac_f32_dpp v102, v110, v146 row_shl:15 row_mask:0xf bank_mask:0xf
	s_nop 0
	v_fmac_f32_dpp v102, v110, v142 row_shl:14 row_mask:0xf bank_mask:0xf
	v_fmac_f32_dpp v103, v165, v147 row_shr:1 row_mask:0xf bank_mask:0xf
	s_nop 0
	v_fmac_f32_dpp v103, v165, v143 row_shr:2 row_mask:0xf bank_mask:0xf
	s_nop 0
	v_fmac_f32_dpp v103, v111, v147 row_shl:15 row_mask:0xf bank_mask:0xf
	s_nop 0
	v_fmac_f32_dpp v103, v111, v143 row_shl:14 row_mask:0xf bank_mask:0xf
	v_fmac_f32_dpp v104, v136, v148 row_shr:1 row_mask:0xf bank_mask:0xf
	s_nop 0
	v_fmac_f32_dpp v104, v136, v144 row_shr:2 row_mask:0xf bank_mask:0xf
	v_mov_b32_e32 v136, 0
	v_fmac_f32_dpp v104, v112, v148 row_shl:15 row_mask:0xf bank_mask:0xf
	s_nop 0
	v_fmac_f32_dpp v104, v112, v144 row_shl:14 row_mask:0xf bank_mask:0xf
	v_fmac_f32_dpp v105, v137, v149 row_shr:1 row_mask:0xf bank_mask:0xf
	s_nop 0
	v_fmac_f32_dpp v105, v137, v145 row_shr:2 row_mask:0xf bank_mask:0xf
	v_mov_b32_e32 v137, 0
	v_fmac_f32_dpp v105, v113, v149 row_shl:15 row_mask:0xf bank_mask:0xf
	s_nop 0
	v_fmac_f32_dpp v105, v113, v145 row_shl:14 row_mask:0xf bank_mask:0xf
	s_nop 0
	v_fmac_f32_dpp v130, v110, v146 row_shr:1 row_mask:0xf bank_mask:0xf
	s_nop 0
	v_fmac_f32_dpp v130, v110, v142 row_shr:2 row_mask:0xf bank_mask:0xf
	s_nop 0
	v_fmac_f32_dpp v130, v150, v146 row_shl:15 row_mask:0xf bank_mask:0xf
	s_nop 0
	v_fmac_f32_dpp v130, v150, v142 row_shl:14 row_mask:0xf bank_mask:0xf
	v_fmac_f32_dpp v131, v111, v147 row_shr:1 row_mask:0xf bank_mask:0xf
	s_nop 0
	v_fmac_f32_dpp v131, v111, v143 row_shr:2 row_mask:0xf bank_mask:0xf
	s_nop 0
	v_fmac_f32_dpp v131, v151, v147 row_shl:15 row_mask:0xf bank_mask:0xf
	s_nop 0
	v_fmac_f32_dpp v131, v151, v143 row_shl:14 row_mask:0xf bank_mask:0xf
	v_fmac_f32_dpp v132, v112, v148 row_shr:1 row_mask:0xf bank_mask:0xf
	s_nop 0
	v_fmac_f32_dpp v132, v112, v144 row_shr:2 row_mask:0xf bank_mask:0xf
	s_nop 0
	v_fmac_f32_dpp v132, v152, v148 row_shl:15 row_mask:0xf bank_mask:0xf
	s_nop 0
	v_fmac_f32_dpp v132, v152, v144 row_shl:14 row_mask:0xf bank_mask:0xf
	v_fmac_f32_dpp v133, v113, v149 row_shr:1 row_mask:0xf bank_mask:0xf
	s_nop 0
	v_fmac_f32_dpp v133, v113, v145 row_shr:2 row_mask:0xf bank_mask:0xf
	s_nop 0
	v_fmac_f32_dpp v133, v153, v149 row_shl:15 row_mask:0xf bank_mask:0xf
	s_nop 0
	v_fmac_f32_dpp v133, v153, v145 row_shl:14 row_mask:0xf bank_mask:0xf
	s_nop 0
	ds_read_b128 v[122:125], v223
	ds_read_b128 v[126:129], v223 offset:1024
	ds_read_b128 v[142:145], v223 offset:2048
	ds_read_b128 v[110:113], v223 offset:3072
	s_and_saveexec_b64 s[48:49], s[0:1]
	v_add_u32_e32 v1, 0, v216
	v_add_u32_e32 v1, 0x20000, v1
	ds_read_b128 v[134:137], v1
	s_or_b64 exec, exec, s[48:49]
	v_mov_b32_e32 v159, v158
	v_mov_b32_e32 v161, v160
	v_pk_fma_f32 v[148:149], v[94:95], v[158:159], v[118:119]
	v_mov_b32_e32 v94, v162
	v_mov_b32_e32 v95, v162
	v_pk_fma_f32 v[94:95], v[92:93], v[94:95], v[120:121]
	v_pk_fma_f32 v[92:93], v[86:87], v[160:161], v[118:119]
	s_waitcnt lgkmcnt(0)
	v_pk_fma_f32 v[86:87], v[114:115], v[142:143], v[110:111]
	s_nop 4
	v_fmac_f32_dpp v86, v114, v126 row_shr:1 row_mask:0xf bank_mask:0xf
	s_nop 0
	v_fmac_f32_dpp v86, v114, v122 row_shr:2 row_mask:0xf bank_mask:0xf
	v_mov_b32_e32 v163, v162
	v_fmac_f32_dpp v86, v92, v126 row_shl:15 row_mask:0xf bank_mask:0xf
	v_mov_b32_e32 v146, v158
	v_mov_b32_e32 v147, v158
	v_fmac_f32_dpp v86, v92, v122 row_shl:14 row_mask:0xf bank_mask:0xf
	v_fmac_f32_dpp v87, v115, v127 row_shr:1 row_mask:0xf bank_mask:0xf
	v_pk_fma_f32 v[146:147], v[96:97], v[146:147], v[120:121]
	v_pk_fma_f32 v[96:97], v[90:91], v[162:163], v[118:119]
	v_mov_b32_e32 v90, v160
	v_mov_b32_e32 v91, v160
	v_fmac_f32_dpp v87, v115, v123 row_shr:2 row_mask:0xf bank_mask:0xf
	v_pk_fma_f32 v[90:91], v[88:89], v[90:91], v[120:121]
	v_fmac_f32_dpp v87, v93, v127 row_shl:15 row_mask:0xf bank_mask:0xf
	v_pk_fma_f32 v[88:89], v[116:117], v[144:145], v[112:113]
	v_fmac_f32_dpp v87, v93, v123 row_shl:14 row_mask:0xf bank_mask:0xf
	v_fmac_f32_dpp v88, v116, v128 row_shr:1 row_mask:0xf bank_mask:0xf
	v_mul_f32_e32 v1, 0xbfb8aa3b, v86
	v_fmac_f32_dpp v88, v116, v124 row_shr:2 row_mask:0xf bank_mask:0xf
	v_exp_f32_e32 v1, v1
	v_fmac_f32_dpp v88, v90, v128 row_shl:15 row_mask:0xf bank_mask:0xf
	s_nop 0
	v_fmac_f32_dpp v88, v90, v124 row_shl:14 row_mask:0xf bank_mask:0xf
	v_fmac_f32_dpp v89, v117, v129 row_shr:1 row_mask:0xf bank_mask:0xf
	v_add_f32_e32 v1, 1.0, v1
	v_fmac_f32_dpp v89, v117, v125 row_shr:2 row_mask:0xf bank_mask:0xf
	v_mul_f32_e32 v115, 0xbfb8aa3b, v88
	v_fmac_f32_dpp v89, v91, v129 row_shl:15 row_mask:0xf bank_mask:0xf
	v_rcp_f32_e32 v114, v1
	v_fmac_f32_dpp v89, v91, v125 row_shl:14 row_mask:0xf bank_mask:0xf
	v_mul_f32_e32 v1, 0xbfb8aa3b, v87
	v_exp_f32_e32 v115, v115
	v_mul_f32_e32 v116, 0xbfb8aa3b, v89
	v_exp_f32_e32 v1, v1
	v_exp_f32_e32 v117, v116
	v_add_f32_e32 v115, 1.0, v115
	v_rcp_f32_e32 v116, v115
	v_add_f32_e32 v1, 1.0, v1
	v_add_f32_e32 v115, 1.0, v117
	v_rcp_f32_e32 v117, v115
	v_rcp_f32_e32 v115, v1
	v_pk_mul_f32 v[88:89], v[140:141], v[88:89]
	v_pk_mul_f32 v[86:87], v[138:139], v[86:87]
	v_pk_mul_f32 v[88:89], v[88:89], v[116:117]
	v_pk_mul_f32 v[86:87], v[86:87], v[114:115]
	v_pk_fma_f32 v[114:115], v[92:93], v[142:143], v[110:111]
	v_fmac_f32_dpp v114, v92, v126 row_shr:1 row_mask:0xf bank_mask:0xf
	s_nop 0
	v_fmac_f32_dpp v114, v92, v122 row_shr:2 row_mask:0xf bank_mask:0xf
	v_fma_f32 v92, v90, v144, v112
	v_fmac_f32_dpp v114, v96, v126 row_shl:15 row_mask:0xf bank_mask:0xf
	s_nop 0
	v_fmac_f32_dpp v114, v96, v122 row_shl:14 row_mask:0xf bank_mask:0xf
	v_fmac_f32_dpp v115, v93, v127 row_shr:1 row_mask:0xf bank_mask:0xf
	s_nop 0
	v_fmac_f32_dpp v115, v93, v123 row_shr:2 row_mask:0xf bank_mask:0xf
	v_mul_f32_e32 v1, 0xbfb8aa3b, v114
	v_fmac_f32_dpp v115, v97, v127 row_shl:15 row_mask:0xf bank_mask:0xf
	v_exp_f32_e32 v1, v1
	v_fmac_f32_dpp v115, v97, v123 row_shl:14 row_mask:0xf bank_mask:0xf
	v_fmac_f32_dpp v92, v90, v128 row_shr:1 row_mask:0xf bank_mask:0xf
	v_fma_f32 v93, v91, v145, v113
	v_fmac_f32_dpp v92, v90, v124 row_shr:2 row_mask:0xf bank_mask:0xf
	v_add_f32_e32 v1, 1.0, v1
	v_fmac_f32_dpp v92, v94, v128 row_shl:15 row_mask:0xf bank_mask:0xf
	v_rcp_f32_e32 v90, v1
	v_fmac_f32_dpp v92, v94, v124 row_shl:14 row_mask:0xf bank_mask:0xf
	v_fmac_f32_dpp v93, v91, v129 row_shr:1 row_mask:0xf bank_mask:0xf
	v_mul_f32_e32 v1, 0xbfb8aa3b, v115
	v_fmac_f32_dpp v93, v91, v125 row_shr:2 row_mask:0xf bank_mask:0xf
	v_mul_f32_e32 v91, 0xbfb8aa3b, v92
	v_fmac_f32_dpp v93, v95, v129 row_shl:15 row_mask:0xf bank_mask:0xf
	v_exp_f32_e32 v91, v91
	v_fmac_f32_dpp v93, v95, v125 row_shl:14 row_mask:0xf bank_mask:0xf
	v_exp_f32_e32 v1, v1
	v_mul_f32_e32 v116, 0xbfb8aa3b, v93
	v_exp_f32_e32 v117, v116
	v_add_f32_e32 v91, 1.0, v91
	v_add_f32_e32 v1, 1.0, v1
	v_rcp_f32_e32 v116, v91
	v_add_f32_e32 v91, 1.0, v117
	v_rcp_f32_e32 v117, v91
	v_rcp_f32_e32 v91, v1
	v_pk_mul_f32 v[92:93], v[108:109], v[92:93]
	v_pk_mul_f32 v[106:107], v[106:107], v[114:115]
	v_pk_mul_f32 v[92:93], v[92:93], v[116:117]
	v_pk_mul_f32 v[90:91], v[106:107], v[90:91]
	v_pk_fma_f32 v[106:107], v[96:97], v[142:143], v[110:111]
	v_fmac_f32_dpp v106, v96, v126 row_shr:1 row_mask:0xf bank_mask:0xf
	s_nop 0
	v_fmac_f32_dpp v106, v96, v122 row_shr:2 row_mask:0xf bank_mask:0xf
	v_fma_f32 v96, v94, v144, v112
	v_fmac_f32_dpp v106, v148, v126 row_shl:15 row_mask:0xf bank_mask:0xf
	v_fma_f32 v112, v146, v144, v112
	v_fmac_f32_dpp v106, v148, v122 row_shl:14 row_mask:0xf bank_mask:0xf
	v_fmac_f32_dpp v107, v97, v127 row_shr:1 row_mask:0xf bank_mask:0xf
	s_nop 0
	v_fmac_f32_dpp v107, v97, v123 row_shr:2 row_mask:0xf bank_mask:0xf
	v_mul_f32_e32 v1, 0xbfb8aa3b, v106
	v_fmac_f32_dpp v107, v149, v127 row_shl:15 row_mask:0xf bank_mask:0xf
	v_exp_f32_e32 v1, v1
	v_fmac_f32_dpp v107, v149, v123 row_shl:14 row_mask:0xf bank_mask:0xf
	v_fmac_f32_dpp v96, v94, v128 row_shr:1 row_mask:0xf bank_mask:0xf
	v_fma_f32 v97, v95, v145, v113
	v_fmac_f32_dpp v96, v94, v124 row_shr:2 row_mask:0xf bank_mask:0xf
	v_add_f32_e32 v1, 1.0, v1
	v_fmac_f32_dpp v96, v146, v128 row_shl:15 row_mask:0xf bank_mask:0xf
	v_rcp_f32_e32 v94, v1
	v_fmac_f32_dpp v96, v146, v124 row_shl:14 row_mask:0xf bank_mask:0xf
	v_fmac_f32_dpp v97, v95, v129 row_shr:1 row_mask:0xf bank_mask:0xf
	v_mul_f32_e32 v1, 0xbfb8aa3b, v107
	v_fmac_f32_dpp v97, v95, v125 row_shr:2 row_mask:0xf bank_mask:0xf
	v_mul_f32_e32 v95, 0xbfb8aa3b, v96
	v_fmac_f32_dpp v97, v147, v129 row_shl:15 row_mask:0xf bank_mask:0xf
	v_exp_f32_e32 v95, v95
	v_fmac_f32_dpp v97, v147, v125 row_shl:14 row_mask:0xf bank_mask:0xf
	v_exp_f32_e32 v1, v1
	v_mul_f32_e32 v108, 0xbfb8aa3b, v97
	v_exp_f32_e32 v109, v108
	v_add_f32_e32 v95, 1.0, v95
	v_add_f32_e32 v1, 1.0, v1
	v_rcp_f32_e32 v108, v95
	v_add_f32_e32 v95, 1.0, v109
	v_rcp_f32_e32 v109, v95
	v_rcp_f32_e32 v95, v1
	v_pk_mul_f32 v[96:97], v[104:105], v[96:97]
	v_pk_mul_f32 v[102:103], v[102:103], v[106:107]
	v_pk_mul_f32 v[96:97], v[96:97], v[108:109]
	v_pk_mul_f32 v[94:95], v[102:103], v[94:95]
	v_pk_fma_f32 v[102:103], v[148:149], v[142:143], v[110:111]
	v_fmac_f32_dpp v102, v148, v126 row_shr:1 row_mask:0xf bank_mask:0xf
	s_nop 0
	v_fmac_f32_dpp v102, v148, v122 row_shr:2 row_mask:0xf bank_mask:0xf
	v_fmac_f32_e32 v113, v147, v145
	v_fmac_f32_dpp v102, v134, v126 row_shl:15 row_mask:0xf bank_mask:0xf
	s_nop 0
	v_fmac_f32_dpp v102, v134, v122 row_shl:14 row_mask:0xf bank_mask:0xf
	v_fmac_f32_dpp v103, v149, v127 row_shr:1 row_mask:0xf bank_mask:0xf
	v_mov_b32_e32 v122, 0
	v_fmac_f32_dpp v103, v149, v123 row_shr:2 row_mask:0xf bank_mask:0xf
	v_mul_f32_e32 v1, 0xbfb8aa3b, v102
	v_fmac_f32_dpp v103, v135, v127 row_shl:15 row_mask:0xf bank_mask:0xf
	v_exp_f32_e32 v1, v1
	v_fmac_f32_dpp v103, v135, v123 row_shl:14 row_mask:0xf bank_mask:0xf
	v_fmac_f32_dpp v112, v146, v128 row_shr:1 row_mask:0xf bank_mask:0xf
	v_mov_b32_e32 v123, 0
	v_fmac_f32_dpp v112, v146, v124 row_shr:2 row_mask:0xf bank_mask:0xf
	v_add_f32_e32 v1, 1.0, v1
	v_fmac_f32_dpp v112, v136, v128 row_shl:15 row_mask:0xf bank_mask:0xf
	v_rcp_f32_e32 v106, v1
	v_fmac_f32_dpp v112, v136, v124 row_shl:14 row_mask:0xf bank_mask:0xf
	v_fmac_f32_dpp v113, v147, v129 row_shr:1 row_mask:0xf bank_mask:0xf
	v_mul_f32_e32 v1, 0xbfb8aa3b, v103
	v_fmac_f32_dpp v113, v147, v125 row_shr:2 row_mask:0xf bank_mask:0xf
	v_mul_f32_e32 v104, 0xbfb8aa3b, v112
	v_fmac_f32_dpp v113, v137, v129 row_shl:15 row_mask:0xf bank_mask:0xf
	v_exp_f32_e32 v1, v1
	v_fmac_f32_dpp v113, v137, v125 row_shl:14 row_mask:0xf bank_mask:0xf
	v_exp_f32_e32 v104, v104
	v_mul_f32_e32 v105, 0xbfb8aa3b, v113
	v_exp_f32_e32 v105, v105
	v_add_f32_e32 v1, 1.0, v1
	v_add_f32_e32 v104, 1.0, v104
	v_rcp_f32_e32 v104, v104
	v_add_f32_e32 v105, 1.0, v105
	v_rcp_f32_e32 v105, v105
	v_rcp_f32_e32 v107, v1
	v_pk_mul_f32 v[108:109], v[132:133], v[112:113]
	v_pk_mul_f32 v[102:103], v[130:131], v[102:103]
	v_pk_mul_f32 v[104:105], v[108:109], v[104:105]
	v_pk_mul_f32 v[102:103], v[102:103], v[106:107]
	v_mov_b32_e32 v124, 0
	ds_read_b128 v[114:117], v223 offset:528
	ds_read_b128 v[118:121], v223 offset:1552
	ds_read_b128 v[126:129], v223 offset:2576
	ds_read_b128 v[106:109], v223 offset:3600
	v_mov_b32_e32 v125, 0
	s_and_saveexec_b64 s[48:49], s[30:31]
	v_add_u32_e32 v1, s91, v217
	ds_read_b128 v[122:125], v1 offset:512
	s_or_b64 exec, exec, s[48:49]
	v_mov_b32_e32 v110, v194
	v_mov_b32_e32 v111, v194
	v_pk_fma_f32 v[76:77], v[76:77], v[110:111], v[56:57]
	v_mov_b32_e32 v110, v196
	v_mov_b32_e32 v111, v196
	v_pk_fma_f32 v[130:131], v[72:73], v[110:111], v[56:57]
	s_waitcnt lgkmcnt(0)
	v_pk_fma_f32 v[110:111], v[98:99], v[126:127], v[106:107]
	s_nop 4
	v_fmac_f32_dpp v110, v98, v118 row_shr:1 row_mask:0xf bank_mask:0xf
	v_pk_fma_f32 v[66:67], v[66:67], v[198:199], v[54:55]
	v_fmac_f32_dpp v110, v98, v114 row_shr:2 row_mask:0xf bank_mask:0xf
	s_nop 0
	v_fmac_f32_dpp v110, v66, v118 row_shl:15 row_mask:0xf bank_mask:0xf
	v_pk_fma_f32 v[112:113], v[100:101], v[128:129], v[108:109]
	v_fmac_f32_dpp v110, v66, v114 row_shl:14 row_mask:0xf bank_mask:0xf
	v_fmac_f32_dpp v111, v99, v119 row_shr:1 row_mask:0xf bank_mask:0xf
	v_pk_fma_f32 v[132:133], v[70:71], v[196:197], v[54:55]
	v_fmac_f32_dpp v111, v99, v115 row_shr:2 row_mask:0xf bank_mask:0xf
	v_mov_b32_e32 v70, v198
	v_fmac_f32_dpp v111, v67, v119 row_shl:15 row_mask:0xf bank_mask:0xf
	v_mov_b32_e32 v71, v198
	v_fmac_f32_dpp v111, v67, v115 row_shl:14 row_mask:0xf bank_mask:0xf
	v_fmac_f32_dpp v112, v100, v120 row_shr:1 row_mask:0xf bank_mask:0xf
	v_pk_fma_f32 v[68:69], v[68:69], v[70:71], v[56:57]
	v_fmac_f32_dpp v112, v100, v116 row_shr:2 row_mask:0xf bank_mask:0xf
	s_nop 0
	v_fmac_f32_dpp v112, v68, v120 row_shl:15 row_mask:0xf bank_mask:0xf
	v_pk_fma_f32 v[70:71], v[66:67], v[126:127], v[106:107]
	v_fmac_f32_dpp v112, v68, v116 row_shl:14 row_mask:0xf bank_mask:0xf
	v_fmac_f32_dpp v113, v101, v121 row_shr:1 row_mask:0xf bank_mask:0xf
	s_nop 0
	v_fmac_f32_dpp v113, v101, v117 row_shr:2 row_mask:0xf bank_mask:0xf
	v_pk_fma_f32 v[72:73], v[68:69], v[128:129], v[108:109]
	v_fmac_f32_dpp v113, v69, v121 row_shl:15 row_mask:0xf bank_mask:0xf
	s_nop 0
	v_fmac_f32_dpp v113, v69, v117 row_shl:14 row_mask:0xf bank_mask:0xf
	v_pk_fma_f32 v[74:75], v[74:75], v[194:195], v[54:55]
	v_fmac_f32_dpp v70, v66, v118 row_shr:1 row_mask:0xf bank_mask:0xf
	s_nop 0
	v_fmac_f32_dpp v70, v66, v114 row_shr:2 row_mask:0xf bank_mask:0xf
	v_fma_f32 v66, v132, v126, v106
	v_fmac_f32_dpp v70, v132, v118 row_shl:15 row_mask:0xf bank_mask:0xf
	v_fma_f32 v106, v74, v126, v106
	v_fmac_f32_dpp v70, v132, v114 row_shl:14 row_mask:0xf bank_mask:0xf
	v_fmac_f32_dpp v71, v67, v119 row_shr:1 row_mask:0xf bank_mask:0xf
	s_nop 0
	v_fmac_f32_dpp v71, v67, v115 row_shr:2 row_mask:0xf bank_mask:0xf
	v_fma_f32 v67, v133, v127, v107
	v_fmac_f32_dpp v71, v133, v119 row_shl:15 row_mask:0xf bank_mask:0xf
	v_fma_f32 v107, v75, v127, v107
	v_fmac_f32_dpp v71, v133, v115 row_shl:14 row_mask:0xf bank_mask:0xf
	v_fmac_f32_dpp v72, v68, v120 row_shr:1 row_mask:0xf bank_mask:0xf
	s_nop 0
	v_fmac_f32_dpp v72, v68, v116 row_shr:2 row_mask:0xf bank_mask:0xf
	v_fma_f32 v68, v130, v128, v108
	v_fmac_f32_dpp v72, v130, v120 row_shl:15 row_mask:0xf bank_mask:0xf
	v_fma_f32 v108, v76, v128, v108
	v_fmac_f32_dpp v72, v130, v116 row_shl:14 row_mask:0xf bank_mask:0xf
	v_fmac_f32_dpp v73, v69, v121 row_shr:1 row_mask:0xf bank_mask:0xf
	s_nop 0
	v_fmac_f32_dpp v73, v69, v117 row_shr:2 row_mask:0xf bank_mask:0xf
	v_fma_f32 v69, v131, v129, v109
	v_fmac_f32_dpp v73, v131, v121 row_shl:15 row_mask:0xf bank_mask:0xf
	v_fmac_f32_e32 v109, v77, v129
	v_fmac_f32_dpp v73, v131, v117 row_shl:14 row_mask:0xf bank_mask:0xf
	s_nop 0
	v_fmac_f32_dpp v66, v132, v118 row_shr:1 row_mask:0xf bank_mask:0xf
	s_nop 0
	v_fmac_f32_dpp v66, v132, v114 row_shr:2 row_mask:0xf bank_mask:0xf
	s_nop 0
	v_fmac_f32_dpp v66, v74, v118 row_shl:15 row_mask:0xf bank_mask:0xf
	s_nop 0
	v_fmac_f32_dpp v66, v74, v114 row_shl:14 row_mask:0xf bank_mask:0xf
	v_fmac_f32_dpp v67, v133, v119 row_shr:1 row_mask:0xf bank_mask:0xf
	s_nop 0
	v_fmac_f32_dpp v67, v133, v115 row_shr:2 row_mask:0xf bank_mask:0xf
	s_nop 0
	v_fmac_f32_dpp v67, v75, v119 row_shl:15 row_mask:0xf bank_mask:0xf
	s_nop 0
	v_fmac_f32_dpp v67, v75, v115 row_shl:14 row_mask:0xf bank_mask:0xf
	v_fmac_f32_dpp v68, v130, v120 row_shr:1 row_mask:0xf bank_mask:0xf
	s_nop 0
	v_fmac_f32_dpp v68, v130, v116 row_shr:2 row_mask:0xf bank_mask:0xf
	s_nop 0
	v_fmac_f32_dpp v68, v76, v120 row_shl:15 row_mask:0xf bank_mask:0xf
	s_nop 0
	v_fmac_f32_dpp v68, v76, v116 row_shl:14 row_mask:0xf bank_mask:0xf
	v_fmac_f32_dpp v69, v131, v121 row_shr:1 row_mask:0xf bank_mask:0xf
	s_nop 0
	v_fmac_f32_dpp v69, v131, v117 row_shr:2 row_mask:0xf bank_mask:0xf
	s_nop 0
	v_fmac_f32_dpp v69, v77, v121 row_shl:15 row_mask:0xf bank_mask:0xf
	s_nop 0
	v_fmac_f32_dpp v69, v77, v117 row_shl:14 row_mask:0xf bank_mask:0xf
	s_nop 0
	v_fmac_f32_dpp v106, v74, v118 row_shr:1 row_mask:0xf bank_mask:0xf
	s_nop 0
	v_fmac_f32_dpp v106, v74, v114 row_shr:2 row_mask:0xf bank_mask:0xf
	s_nop 0
	v_fmac_f32_dpp v106, v122, v118 row_shl:15 row_mask:0xf bank_mask:0xf
	s_nop 0
	v_fmac_f32_dpp v106, v122, v114 row_shl:14 row_mask:0xf bank_mask:0xf
	v_fmac_f32_dpp v107, v75, v119 row_shr:1 row_mask:0xf bank_mask:0xf
	s_nop 0
	v_fmac_f32_dpp v107, v75, v115 row_shr:2 row_mask:0xf bank_mask:0xf
	s_nop 0
	v_fmac_f32_dpp v107, v123, v119 row_shl:15 row_mask:0xf bank_mask:0xf
	s_nop 0
	v_fmac_f32_dpp v107, v123, v115 row_shl:14 row_mask:0xf bank_mask:0xf
	v_fmac_f32_dpp v108, v76, v120 row_shr:1 row_mask:0xf bank_mask:0xf
	s_nop 0
	v_fmac_f32_dpp v108, v76, v116 row_shr:2 row_mask:0xf bank_mask:0xf
	s_nop 0
	v_fmac_f32_dpp v108, v124, v120 row_shl:15 row_mask:0xf bank_mask:0xf
	s_nop 0
	v_fmac_f32_dpp v108, v124, v116 row_shl:14 row_mask:0xf bank_mask:0xf
	v_fmac_f32_dpp v109, v77, v121 row_shr:1 row_mask:0xf bank_mask:0xf
	s_nop 0
	v_fmac_f32_dpp v109, v77, v117 row_shr:2 row_mask:0xf bank_mask:0xf
	s_nop 0
	v_fmac_f32_dpp v109, v125, v121 row_shl:15 row_mask:0xf bank_mask:0xf
	s_nop 0
	v_fmac_f32_dpp v109, v125, v117 row_shl:14 row_mask:0xf bank_mask:0xf
	s_and_saveexec_b64 s[48:49], s[34:35]
	s_cbranch_execz .LBB0_579
	v_or_b32_e32 v74, 4, v200
	v_ashrrev_i32_e32 v75, 31, v74
	v_lshl_add_u64 v[74:75], v[74:75], 2, v[168:169]
	v_add_co_u32_e32 v74, vcc, 0x2000, v74
	s_nop 1
	v_addc_co_u32_e32 v75, vcc, 0, v75, vcc
	global_store_dwordx4 v[74:75], v[106:109], off offset:3072
.LBB0_579:
	s_or_b64 exec, exec, s[48:49]
	s_nop 0
	ds_read_b128 v[98:101], v223 offset:16
	ds_read_b128 v[114:117], v223 offset:1040
	ds_read_b128 v[122:125], v223 offset:2064
	ds_read_b128 v[74:77], v223 offset:3088
	v_mov_b32_e32 v118, 0
	v_mov_b32_e32 v119, 0
	v_mov_b32_e32 v120, 0
	v_mov_b32_e32 v121, 0
	s_and_saveexec_b64 s[48:49], s[30:31]
	v_add_u32_e32 v1, 0, v217
	v_add_u32_e32 v1, 0x20000, v1
	ds_read_b128 v[118:121], v1
	s_or_b64 exec, exec, s[48:49]
	v_pk_fma_f32 v[128:129], v[42:43], v[194:195], v[30:31]
	v_mov_b32_e32 v42, v196
	v_mov_b32_e32 v43, v196
	v_pk_fma_f32 v[42:43], v[40:41], v[42:43], v[32:33]
	v_pk_fma_f32 v[40:41], v[34:35], v[198:199], v[30:31]
	s_waitcnt lgkmcnt(0)
	v_pk_fma_f32 v[34:35], v[82:83], v[122:123], v[74:75]
	s_nop 4
	v_fmac_f32_dpp v34, v82, v114 row_shr:1 row_mask:0xf bank_mask:0xf
	s_nop 0
	v_fmac_f32_dpp v34, v82, v98 row_shr:2 row_mask:0xf bank_mask:0xf
	v_mov_b32_e32 v126, v194
	v_fmac_f32_dpp v34, v40, v114 row_shl:15 row_mask:0xf bank_mask:0xf
	v_mov_b32_e32 v127, v194
	v_fmac_f32_dpp v34, v40, v98 row_shl:14 row_mask:0xf bank_mask:0xf
	v_fmac_f32_dpp v35, v83, v115 row_shr:1 row_mask:0xf bank_mask:0xf
	v_pk_fma_f32 v[126:127], v[44:45], v[126:127], v[32:33]
	v_pk_fma_f32 v[44:45], v[38:39], v[196:197], v[30:31]
	v_mov_b32_e32 v38, v198
	v_mov_b32_e32 v39, v198
	v_fmac_f32_dpp v35, v83, v99 row_shr:2 row_mask:0xf bank_mask:0xf
	v_pk_fma_f32 v[38:39], v[36:37], v[38:39], v[32:33]
	v_fmac_f32_dpp v35, v41, v115 row_shl:15 row_mask:0xf bank_mask:0xf
	v_pk_fma_f32 v[36:37], v[84:85], v[124:125], v[76:77]
	v_fmac_f32_dpp v35, v41, v99 row_shl:14 row_mask:0xf bank_mask:0xf
	v_fmac_f32_dpp v36, v84, v116 row_shr:1 row_mask:0xf bank_mask:0xf
	v_mul_f32_e32 v1, 0xbfb8aa3b, v34
	v_fmac_f32_dpp v36, v84, v100 row_shr:2 row_mask:0xf bank_mask:0xf
	v_exp_f32_e32 v1, v1
	v_fmac_f32_dpp v36, v38, v116 row_shl:15 row_mask:0xf bank_mask:0xf
	s_nop 0
	v_fmac_f32_dpp v36, v38, v100 row_shl:14 row_mask:0xf bank_mask:0xf
	v_fmac_f32_dpp v37, v85, v117 row_shr:1 row_mask:0xf bank_mask:0xf
	v_add_f32_e32 v1, 1.0, v1
	v_fmac_f32_dpp v37, v85, v101 row_shr:2 row_mask:0xf bank_mask:0xf
	v_mul_f32_e32 v83, 0xbfb8aa3b, v36
	v_fmac_f32_dpp v37, v39, v117 row_shl:15 row_mask:0xf bank_mask:0xf
	v_rcp_f32_e32 v82, v1
	v_fmac_f32_dpp v37, v39, v101 row_shl:14 row_mask:0xf bank_mask:0xf
	v_mul_f32_e32 v1, 0xbfb8aa3b, v35
	v_exp_f32_e32 v83, v83
	v_mul_f32_e32 v84, 0xbfb8aa3b, v37
	v_exp_f32_e32 v1, v1
	v_exp_f32_e32 v85, v84
	v_add_f32_e32 v83, 1.0, v83
	v_rcp_f32_e32 v84, v83
	v_add_f32_e32 v1, 1.0, v1
	v_add_f32_e32 v83, 1.0, v85
	v_rcp_f32_e32 v85, v83
	v_rcp_f32_e32 v83, v1
	v_pk_mul_f32 v[36:37], v[112:113], v[36:37]
	v_pk_mul_f32 v[34:35], v[110:111], v[34:35]
	v_pk_mul_f32 v[36:37], v[36:37], v[84:85]
	v_pk_mul_f32 v[34:35], v[34:35], v[82:83]
	v_pk_fma_f32 v[82:83], v[40:41], v[122:123], v[74:75]
	v_fmac_f32_dpp v82, v40, v114 row_shr:1 row_mask:0xf bank_mask:0xf
	s_nop 0
	v_fmac_f32_dpp v82, v40, v98 row_shr:2 row_mask:0xf bank_mask:0xf
	v_fma_f32 v40, v38, v124, v76
	v_fmac_f32_dpp v82, v44, v114 row_shl:15 row_mask:0xf bank_mask:0xf
	s_nop 0
	v_fmac_f32_dpp v82, v44, v98 row_shl:14 row_mask:0xf bank_mask:0xf
	v_fmac_f32_dpp v83, v41, v115 row_shr:1 row_mask:0xf bank_mask:0xf
	s_nop 0
	v_fmac_f32_dpp v83, v41, v99 row_shr:2 row_mask:0xf bank_mask:0xf
	v_mul_f32_e32 v1, 0xbfb8aa3b, v82
	v_fmac_f32_dpp v83, v45, v115 row_shl:15 row_mask:0xf bank_mask:0xf
	v_exp_f32_e32 v1, v1
	v_fmac_f32_dpp v83, v45, v99 row_shl:14 row_mask:0xf bank_mask:0xf
	v_fmac_f32_dpp v40, v38, v116 row_shr:1 row_mask:0xf bank_mask:0xf
	v_fma_f32 v41, v39, v125, v77
	v_fmac_f32_dpp v40, v38, v100 row_shr:2 row_mask:0xf bank_mask:0xf
	v_add_f32_e32 v1, 1.0, v1
	v_fmac_f32_dpp v40, v42, v116 row_shl:15 row_mask:0xf bank_mask:0xf
	v_rcp_f32_e32 v38, v1
	v_fmac_f32_dpp v40, v42, v100 row_shl:14 row_mask:0xf bank_mask:0xf
	v_fmac_f32_dpp v41, v39, v117 row_shr:1 row_mask:0xf bank_mask:0xf
	v_mul_f32_e32 v1, 0xbfb8aa3b, v83
	v_fmac_f32_dpp v41, v39, v101 row_shr:2 row_mask:0xf bank_mask:0xf
	v_mul_f32_e32 v39, 0xbfb8aa3b, v40
	v_fmac_f32_dpp v41, v43, v117 row_shl:15 row_mask:0xf bank_mask:0xf
	v_exp_f32_e32 v39, v39
	v_fmac_f32_dpp v41, v43, v101 row_shl:14 row_mask:0xf bank_mask:0xf
	v_exp_f32_e32 v1, v1
	v_mul_f32_e32 v84, 0xbfb8aa3b, v41
	v_exp_f32_e32 v85, v84
	v_add_f32_e32 v39, 1.0, v39
	v_add_f32_e32 v1, 1.0, v1
	v_rcp_f32_e32 v84, v39
	v_add_f32_e32 v39, 1.0, v85
	v_rcp_f32_e32 v85, v39
	v_rcp_f32_e32 v39, v1
	v_pk_mul_f32 v[40:41], v[72:73], v[40:41]
	v_pk_mul_f32 v[70:71], v[70:71], v[82:83]
	v_pk_mul_f32 v[40:41], v[40:41], v[84:85]
	v_pk_mul_f32 v[38:39], v[70:71], v[38:39]
	v_pk_fma_f32 v[70:71], v[44:45], v[122:123], v[74:75]
	v_fmac_f32_dpp v70, v44, v114 row_shr:1 row_mask:0xf bank_mask:0xf
	s_nop 0
	v_fmac_f32_dpp v70, v44, v98 row_shr:2 row_mask:0xf bank_mask:0xf
	v_fma_f32 v44, v42, v124, v76
	v_fmac_f32_dpp v70, v128, v114 row_shl:15 row_mask:0xf bank_mask:0xf
	v_pk_fma_f32 v[74:75], v[128:129], v[122:123], v[74:75]
	v_fmac_f32_dpp v70, v128, v98 row_shl:14 row_mask:0xf bank_mask:0xf
	v_fmac_f32_dpp v71, v45, v115 row_shr:1 row_mask:0xf bank_mask:0xf
	s_nop 0
	v_fmac_f32_dpp v71, v45, v99 row_shr:2 row_mask:0xf bank_mask:0xf
	v_mul_f32_e32 v1, 0xbfb8aa3b, v70
	v_fmac_f32_dpp v71, v129, v115 row_shl:15 row_mask:0xf bank_mask:0xf
	v_exp_f32_e32 v1, v1
	v_fmac_f32_dpp v71, v129, v99 row_shl:14 row_mask:0xf bank_mask:0xf
	v_fmac_f32_dpp v44, v42, v116 row_shr:1 row_mask:0xf bank_mask:0xf
	v_fma_f32 v45, v43, v125, v77
	v_fmac_f32_dpp v44, v42, v100 row_shr:2 row_mask:0xf bank_mask:0xf
	v_add_f32_e32 v1, 1.0, v1
	v_fmac_f32_dpp v44, v126, v116 row_shl:15 row_mask:0xf bank_mask:0xf
	v_rcp_f32_e32 v42, v1
	v_fmac_f32_dpp v44, v126, v100 row_shl:14 row_mask:0xf bank_mask:0xf
	v_fmac_f32_dpp v45, v43, v117 row_shr:1 row_mask:0xf bank_mask:0xf
	v_mul_f32_e32 v1, 0xbfb8aa3b, v71
	v_fmac_f32_dpp v45, v43, v101 row_shr:2 row_mask:0xf bank_mask:0xf
	v_mul_f32_e32 v43, 0xbfb8aa3b, v44
	v_fmac_f32_dpp v45, v127, v117 row_shl:15 row_mask:0xf bank_mask:0xf
	v_exp_f32_e32 v43, v43
	v_fmac_f32_dpp v45, v127, v101 row_shl:14 row_mask:0xf bank_mask:0xf
	v_exp_f32_e32 v1, v1
	v_mul_f32_e32 v72, 0xbfb8aa3b, v45
	v_exp_f32_e32 v73, v72
	v_add_f32_e32 v43, 1.0, v43
	v_add_f32_e32 v1, 1.0, v1
	v_rcp_f32_e32 v72, v43
	v_add_f32_e32 v43, 1.0, v73
	v_rcp_f32_e32 v73, v43
	v_rcp_f32_e32 v43, v1
	v_pk_mul_f32 v[44:45], v[68:69], v[44:45]
	v_pk_mul_f32 v[66:67], v[66:67], v[70:71]
	v_pk_mul_f32 v[44:45], v[44:45], v[72:73]
	v_pk_mul_f32 v[42:43], v[66:67], v[42:43]
	v_pk_fma_f32 v[76:77], v[126:127], v[124:125], v[76:77]
	v_fmac_f32_dpp v74, v128, v114 row_shr:1 row_mask:0xf bank_mask:0xf
	s_nop 0
	v_fmac_f32_dpp v74, v128, v98 row_shr:2 row_mask:0xf bank_mask:0xf
	s_nop 0
	v_fmac_f32_dpp v74, v118, v114 row_shl:15 row_mask:0xf bank_mask:0xf
	s_nop 0
	v_fmac_f32_dpp v74, v118, v98 row_shl:14 row_mask:0xf bank_mask:0xf
	v_fmac_f32_dpp v75, v129, v115 row_shr:1 row_mask:0xf bank_mask:0xf
	s_nop 0
	v_fmac_f32_dpp v75, v129, v99 row_shr:2 row_mask:0xf bank_mask:0xf
	s_nop 0
	v_fmac_f32_dpp v75, v119, v115 row_shl:15 row_mask:0xf bank_mask:0xf
	s_nop 0
	v_fmac_f32_dpp v75, v119, v99 row_shl:14 row_mask:0xf bank_mask:0xf
	v_fmac_f32_dpp v76, v126, v116 row_shr:1 row_mask:0xf bank_mask:0xf
	s_nop 0
	v_fmac_f32_dpp v76, v126, v100 row_shr:2 row_mask:0xf bank_mask:0xf
	s_nop 0
	v_fmac_f32_dpp v76, v120, v116 row_shl:15 row_mask:0xf bank_mask:0xf
	s_nop 0
	v_fmac_f32_dpp v76, v120, v100 row_shl:14 row_mask:0xf bank_mask:0xf
	v_fmac_f32_dpp v77, v127, v117 row_shr:1 row_mask:0xf bank_mask:0xf
	s_nop 0
	v_fmac_f32_dpp v77, v127, v101 row_shr:2 row_mask:0xf bank_mask:0xf
	s_nop 0
	v_fmac_f32_dpp v77, v121, v117 row_shl:15 row_mask:0xf bank_mask:0xf
	s_nop 0
	v_fmac_f32_dpp v77, v121, v101 row_shl:14 row_mask:0xf bank_mask:0xf
	s_and_saveexec_b64 s[48:49], s[34:35]
	s_cbranch_execz .LBB0_583
	global_store_dwordx4 v[166:167], v[74:77], off offset:16
.LBB0_583:
	s_or_b64 exec, exec, s[48:49]
	v_mul_f32_e32 v1, 0xbfb8aa3b, v74
	v_exp_f32_e32 v1, v1
	v_mul_f32_e32 v66, 0xbfb8aa3b, v75
	v_mul_f32_e32 v67, 0xbfb8aa3b, v76
	v_exp_f32_e32 v68, v66
	v_add_f32_e32 v1, 1.0, v1
	v_rcp_f32_e32 v66, v1
	v_exp_f32_e32 v1, v67
	v_mul_f32_e32 v67, 0xbfb8aa3b, v77
	v_exp_f32_e32 v67, v67
	v_add_f32_e32 v70, 1.0, v68
	v_add_f32_e32 v1, 1.0, v1
	v_rcp_f32_e32 v68, v1
	v_add_f32_e32 v1, 1.0, v67
	v_rcp_f32_e32 v69, v1
	v_rcp_f32_e32 v67, v70
	v_pk_mul_f32 v[70:71], v[108:109], v[76:77]
	v_pk_mul_f32 v[72:73], v[106:107], v[74:75]
	v_pk_mul_f32 v[68:69], v[70:71], v[68:69]
	v_pk_mul_f32 v[66:67], v[72:73], v[66:67]
	v_mov_b32_e32 v74, 0
	ds_read_b128 v[98:101], v223 offset:528
	ds_read_b128 v[106:109], v223 offset:1552
	ds_read_b128 v[114:117], v223 offset:2576
	ds_read_b128 v[70:73], v223 offset:3600
	v_mov_b32_e32 v110, 0
	v_mov_b32_e32 v111, 0
	v_mov_b32_e32 v112, 0
	v_mov_b32_e32 v113, 0
	s_and_saveexec_b64 s[48:49], s[0:1]
	v_add_u32_e32 v1, s91, v218
	ds_read_b128 v[110:113], v1 offset:512
	s_or_b64 exec, exec, s[48:49]
	s_waitcnt lgkmcnt(0)
	v_pk_fma_f32 v[82:83], v[58:59], v[114:115], v[70:71]
	s_nop 4
	v_fmac_f32_dpp v82, v58, v106 row_shr:1 row_mask:0xf bank_mask:0xf
	v_pk_fma_f32 v[14:15], v[14:15], v[160:161], v[54:55]
	v_fmac_f32_dpp v82, v58, v98 row_shr:2 row_mask:0xf bank_mask:0xf
	s_nop 0
	v_fmac_f32_dpp v82, v14, v106 row_shl:15 row_mask:0xf bank_mask:0xf
	v_pk_fma_f32 v[84:85], v[60:61], v[116:117], v[72:73]
	v_fmac_f32_dpp v82, v14, v98 row_shl:14 row_mask:0xf bank_mask:0xf
	v_fmac_f32_dpp v83, v59, v107 row_shr:1 row_mask:0xf bank_mask:0xf
	v_mov_b32_e32 v122, v160
	v_fmac_f32_dpp v83, v59, v99 row_shr:2 row_mask:0xf bank_mask:0xf
	v_mov_b32_e32 v123, v160
	v_fmac_f32_dpp v83, v15, v107 row_shl:15 row_mask:0xf bank_mask:0xf
	v_pk_fma_f32 v[16:17], v[16:17], v[122:123], v[56:57]
	v_fmac_f32_dpp v83, v15, v99 row_shl:14 row_mask:0xf bank_mask:0xf
	v_fmac_f32_dpp v84, v60, v108 row_shr:1 row_mask:0xf bank_mask:0xf
	s_nop 0
	v_fmac_f32_dpp v84, v60, v100 row_shr:2 row_mask:0xf bank_mask:0xf
	v_pk_fma_f32 v[124:125], v[18:19], v[162:163], v[54:55]
	v_fmac_f32_dpp v84, v16, v108 row_shl:15 row_mask:0xf bank_mask:0xf
	v_pk_fma_f32 v[18:19], v[14:15], v[114:115], v[70:71]
	v_fmac_f32_dpp v84, v16, v100 row_shl:14 row_mask:0xf bank_mask:0xf
	v_fmac_f32_dpp v85, v61, v109 row_shr:1 row_mask:0xf bank_mask:0xf
	s_nop 0
	v_fmac_f32_dpp v85, v61, v101 row_shr:2 row_mask:0xf bank_mask:0xf
	v_mov_b32_e32 v120, v162
	v_fmac_f32_dpp v85, v17, v109 row_shl:15 row_mask:0xf bank_mask:0xf
	v_mov_b32_e32 v121, v162
	v_fmac_f32_dpp v85, v17, v101 row_shl:14 row_mask:0xf bank_mask:0xf
	v_pk_fma_f32 v[76:77], v[20:21], v[120:121], v[56:57]
	v_fmac_f32_dpp v18, v14, v106 row_shr:1 row_mask:0xf bank_mask:0xf
	v_pk_fma_f32 v[20:21], v[16:17], v[116:117], v[72:73]
	v_fmac_f32_dpp v18, v14, v98 row_shr:2 row_mask:0xf bank_mask:0xf
	s_nop 0
	v_fmac_f32_dpp v18, v124, v106 row_shl:15 row_mask:0xf bank_mask:0xf
	v_fma_f32 v14, v124, v114, v70
	v_fmac_f32_dpp v18, v124, v98 row_shl:14 row_mask:0xf bank_mask:0xf
	v_fmac_f32_dpp v19, v15, v107 row_shr:1 row_mask:0xf bank_mask:0xf
	v_pk_fma_f32 v[22:23], v[22:23], v[158:159], v[54:55]
	v_fmac_f32_dpp v19, v15, v99 row_shr:2 row_mask:0xf bank_mask:0xf
	v_fma_f32 v15, v125, v115, v71
	v_fmac_f32_dpp v19, v125, v107 row_shl:15 row_mask:0xf bank_mask:0xf
	v_mov_b32_e32 v118, v158
	v_fmac_f32_dpp v19, v125, v99 row_shl:14 row_mask:0xf bank_mask:0xf
	v_fmac_f32_dpp v20, v16, v108 row_shr:1 row_mask:0xf bank_mask:0xf
	v_mov_b32_e32 v119, v158
	v_fmac_f32_dpp v20, v16, v100 row_shr:2 row_mask:0xf bank_mask:0xf
	v_fma_f32 v16, v76, v116, v72
	v_fmac_f32_dpp v20, v76, v108 row_shl:15 row_mask:0xf bank_mask:0xf
	v_pk_fma_f32 v[24:25], v[24:25], v[118:119], v[56:57]
	v_fmac_f32_dpp v20, v76, v100 row_shl:14 row_mask:0xf bank_mask:0xf
	v_fmac_f32_dpp v21, v17, v109 row_shr:1 row_mask:0xf bank_mask:0xf
	v_pk_fma_f32 v[70:71], v[22:23], v[114:115], v[70:71]
	v_fmac_f32_dpp v21, v17, v101 row_shr:2 row_mask:0xf bank_mask:0xf
	v_fma_f32 v17, v77, v117, v73
	v_fmac_f32_dpp v21, v77, v109 row_shl:15 row_mask:0xf bank_mask:0xf
	s_nop 0
	v_fmac_f32_dpp v21, v77, v101 row_shl:14 row_mask:0xf bank_mask:0xf
	v_pk_fma_f32 v[72:73], v[24:25], v[116:117], v[72:73]
	v_fmac_f32_dpp v14, v124, v106 row_shr:1 row_mask:0xf bank_mask:0xf
	s_nop 0
	v_fmac_f32_dpp v14, v124, v98 row_shr:2 row_mask:0xf bank_mask:0xf
	v_mov_b32_e32 v75, 0
	v_fmac_f32_dpp v14, v22, v106 row_shl:15 row_mask:0xf bank_mask:0xf
	s_nop 0
	v_fmac_f32_dpp v14, v22, v98 row_shl:14 row_mask:0xf bank_mask:0xf
	v_fmac_f32_dpp v15, v125, v107 row_shr:1 row_mask:0xf bank_mask:0xf
	s_nop 0
	v_fmac_f32_dpp v15, v125, v99 row_shr:2 row_mask:0xf bank_mask:0xf
	s_nop 0
	v_fmac_f32_dpp v15, v23, v107 row_shl:15 row_mask:0xf bank_mask:0xf
	s_nop 0
	v_fmac_f32_dpp v15, v23, v99 row_shl:14 row_mask:0xf bank_mask:0xf
	v_fmac_f32_dpp v16, v76, v108 row_shr:1 row_mask:0xf bank_mask:0xf
	s_nop 0
	v_fmac_f32_dpp v16, v76, v100 row_shr:2 row_mask:0xf bank_mask:0xf
	v_mov_b32_e32 v76, 0
	v_fmac_f32_dpp v16, v24, v108 row_shl:15 row_mask:0xf bank_mask:0xf
	s_nop 0
	v_fmac_f32_dpp v16, v24, v100 row_shl:14 row_mask:0xf bank_mask:0xf
	v_fmac_f32_dpp v17, v77, v109 row_shr:1 row_mask:0xf bank_mask:0xf
	s_nop 0
	v_fmac_f32_dpp v17, v77, v101 row_shr:2 row_mask:0xf bank_mask:0xf
	v_mov_b32_e32 v77, 0
	v_fmac_f32_dpp v17, v25, v109 row_shl:15 row_mask:0xf bank_mask:0xf
	s_nop 0
	v_fmac_f32_dpp v17, v25, v101 row_shl:14 row_mask:0xf bank_mask:0xf
	s_nop 0
	v_fmac_f32_dpp v70, v22, v106 row_shr:1 row_mask:0xf bank_mask:0xf
	s_nop 0
	v_fmac_f32_dpp v70, v22, v98 row_shr:2 row_mask:0xf bank_mask:0xf
	s_nop 0
	v_fmac_f32_dpp v70, v110, v106 row_shl:15 row_mask:0xf bank_mask:0xf
	s_nop 0
	v_fmac_f32_dpp v70, v110, v98 row_shl:14 row_mask:0xf bank_mask:0xf
	v_fmac_f32_dpp v71, v23, v107 row_shr:1 row_mask:0xf bank_mask:0xf
	s_nop 0
	v_fmac_f32_dpp v71, v23, v99 row_shr:2 row_mask:0xf bank_mask:0xf
	s_nop 0
	v_fmac_f32_dpp v71, v111, v107 row_shl:15 row_mask:0xf bank_mask:0xf
	s_nop 0
	v_fmac_f32_dpp v71, v111, v99 row_shl:14 row_mask:0xf bank_mask:0xf
	v_fmac_f32_dpp v72, v24, v108 row_shr:1 row_mask:0xf bank_mask:0xf
	s_nop 0
	v_fmac_f32_dpp v72, v24, v100 row_shr:2 row_mask:0xf bank_mask:0xf
	s_nop 0
	v_fmac_f32_dpp v72, v112, v108 row_shl:15 row_mask:0xf bank_mask:0xf
	s_nop 0
	v_fmac_f32_dpp v72, v112, v100 row_shl:14 row_mask:0xf bank_mask:0xf
	v_fmac_f32_dpp v73, v25, v109 row_shr:1 row_mask:0xf bank_mask:0xf
	s_nop 0
	v_fmac_f32_dpp v73, v25, v101 row_shr:2 row_mask:0xf bank_mask:0xf
	s_nop 0
	v_fmac_f32_dpp v73, v113, v109 row_shl:15 row_mask:0xf bank_mask:0xf
	s_nop 0
	v_fmac_f32_dpp v73, v113, v101 row_shl:14 row_mask:0xf bank_mask:0xf
	s_nop 0
	ds_read_b128 v[54:57], v223 offset:16
	ds_read_b128 v[58:61], v223 offset:1040
	ds_read_b128 v[98:101], v223 offset:2064
	ds_read_b128 v[22:25], v223 offset:3088
	s_and_saveexec_b64 s[48:49], s[0:1]
	v_add_u32_e32 v1, 0, v218
	v_add_u32_e32 v1, 0x20000, v1
	ds_read_b128 v[74:77], v1
	s_or_b64 exec, exec, s[48:49]
	v_pk_fma_f32 v[106:107], v[8:9], v[120:121], v[32:33]
	v_pk_fma_f32 v[8:9], v[2:3], v[160:161], v[30:31]
	s_waitcnt lgkmcnt(0)
	v_pk_fma_f32 v[2:3], v[26:27], v[98:99], v[22:23]
	s_nop 4
	v_fmac_f32_dpp v2, v26, v58 row_shr:1 row_mask:0xf bank_mask:0xf
	s_nop 0
	v_fmac_f32_dpp v2, v26, v54 row_shr:2 row_mask:0xf bank_mask:0xf
	v_pk_fma_f32 v[108:109], v[6:7], v[162:163], v[30:31]
	v_fmac_f32_dpp v2, v8, v58 row_shl:15 row_mask:0xf bank_mask:0xf
	v_pk_fma_f32 v[6:7], v[4:5], v[122:123], v[32:33]
	v_fmac_f32_dpp v2, v8, v54 row_shl:14 row_mask:0xf bank_mask:0xf
	v_fmac_f32_dpp v3, v27, v59 row_shr:1 row_mask:0xf bank_mask:0xf
	v_pk_fma_f32 v[4:5], v[28:29], v[100:101], v[24:25]
	v_fmac_f32_dpp v3, v27, v55 row_shr:2 row_mask:0xf bank_mask:0xf
	v_mul_f32_e32 v1, 0xbfb8aa3b, v2
	v_fmac_f32_dpp v3, v9, v59 row_shl:15 row_mask:0xf bank_mask:0xf
	v_exp_f32_e32 v1, v1
	v_fmac_f32_dpp v3, v9, v55 row_shl:14 row_mask:0xf bank_mask:0xf
	v_fmac_f32_dpp v4, v28, v60 row_shr:1 row_mask:0xf bank_mask:0xf
	s_nop 0
	v_fmac_f32_dpp v4, v28, v56 row_shr:2 row_mask:0xf bank_mask:0xf
	v_add_f32_e32 v1, 1.0, v1
	v_fmac_f32_dpp v4, v6, v60 row_shl:15 row_mask:0xf bank_mask:0xf
	v_rcp_f32_e32 v26, v1
	v_fmac_f32_dpp v4, v6, v56 row_shl:14 row_mask:0xf bank_mask:0xf
	v_fmac_f32_dpp v5, v29, v61 row_shr:1 row_mask:0xf bank_mask:0xf
	v_mul_f32_e32 v1, 0xbfb8aa3b, v3
	v_fmac_f32_dpp v5, v29, v57 row_shr:2 row_mask:0xf bank_mask:0xf
	v_mul_f32_e32 v27, 0xbfb8aa3b, v4
	v_fmac_f32_dpp v5, v7, v61 row_shl:15 row_mask:0xf bank_mask:0xf
	v_exp_f32_e32 v27, v27
	v_fmac_f32_dpp v5, v7, v57 row_shl:14 row_mask:0xf bank_mask:0xf
	v_exp_f32_e32 v1, v1
	v_mul_f32_e32 v28, 0xbfb8aa3b, v5
	v_exp_f32_e32 v29, v28
	v_add_f32_e32 v27, 1.0, v27
	v_add_f32_e32 v1, 1.0, v1
	v_rcp_f32_e32 v28, v27
	v_add_f32_e32 v27, 1.0, v29
	v_rcp_f32_e32 v29, v27
	v_rcp_f32_e32 v27, v1
	v_pk_mul_f32 v[4:5], v[84:85], v[4:5]
	v_pk_mul_f32 v[2:3], v[82:83], v[2:3]
	v_pk_mul_f32 v[4:5], v[4:5], v[28:29]
	v_pk_mul_f32 v[2:3], v[2:3], v[26:27]
	v_pk_fma_f32 v[26:27], v[8:9], v[98:99], v[22:23]
	v_fmac_f32_dpp v26, v8, v58 row_shr:1 row_mask:0xf bank_mask:0xf
	s_nop 0
	v_fmac_f32_dpp v26, v8, v54 row_shr:2 row_mask:0xf bank_mask:0xf
	v_fma_f32 v8, v6, v100, v24
	v_fmac_f32_dpp v26, v108, v58 row_shl:15 row_mask:0xf bank_mask:0xf
	v_pk_fma_f32 v[10:11], v[10:11], v[158:159], v[30:31]
	v_fmac_f32_dpp v26, v108, v54 row_shl:14 row_mask:0xf bank_mask:0xf
	v_fmac_f32_dpp v27, v9, v59 row_shr:1 row_mask:0xf bank_mask:0xf
	v_pk_fma_f32 v[12:13], v[12:13], v[118:119], v[32:33]
	v_fmac_f32_dpp v27, v9, v55 row_shr:2 row_mask:0xf bank_mask:0xf
	v_mul_f32_e32 v1, 0xbfb8aa3b, v26
	v_fmac_f32_dpp v27, v109, v59 row_shl:15 row_mask:0xf bank_mask:0xf
	v_exp_f32_e32 v1, v1
	v_fmac_f32_dpp v27, v109, v55 row_shl:14 row_mask:0xf bank_mask:0xf
	v_fmac_f32_dpp v8, v6, v60 row_shr:1 row_mask:0xf bank_mask:0xf
	v_fma_f32 v9, v7, v101, v25
	v_fmac_f32_dpp v8, v6, v56 row_shr:2 row_mask:0xf bank_mask:0xf
	v_add_f32_e32 v1, 1.0, v1
	v_fmac_f32_dpp v8, v106, v60 row_shl:15 row_mask:0xf bank_mask:0xf
	v_rcp_f32_e32 v6, v1
	v_fmac_f32_dpp v8, v106, v56 row_shl:14 row_mask:0xf bank_mask:0xf
	v_fmac_f32_dpp v9, v7, v61 row_shr:1 row_mask:0xf bank_mask:0xf
	v_mul_f32_e32 v1, 0xbfb8aa3b, v27
	v_fmac_f32_dpp v9, v7, v57 row_shr:2 row_mask:0xf bank_mask:0xf
	v_mul_f32_e32 v7, 0xbfb8aa3b, v8
	v_fmac_f32_dpp v9, v107, v61 row_shl:15 row_mask:0xf bank_mask:0xf
	v_exp_f32_e32 v7, v7
	v_fmac_f32_dpp v9, v107, v57 row_shl:14 row_mask:0xf bank_mask:0xf
	v_exp_f32_e32 v1, v1
	v_mul_f32_e32 v28, 0xbfb8aa3b, v9
	v_exp_f32_e32 v29, v28
	v_add_f32_e32 v7, 1.0, v7
	v_add_f32_e32 v1, 1.0, v1
	v_rcp_f32_e32 v28, v7
	v_add_f32_e32 v7, 1.0, v29
	v_rcp_f32_e32 v29, v7
	v_rcp_f32_e32 v7, v1
	v_pk_mul_f32 v[8:9], v[20:21], v[8:9]
	v_pk_mul_f32 v[18:19], v[18:19], v[26:27]
	v_pk_mul_f32 v[8:9], v[8:9], v[28:29]
	v_pk_mul_f32 v[6:7], v[18:19], v[6:7]
	v_pk_fma_f32 v[18:19], v[108:109], v[98:99], v[22:23]
	v_fmac_f32_dpp v18, v108, v58 row_shr:1 row_mask:0xf bank_mask:0xf
	s_nop 0
	v_fmac_f32_dpp v18, v108, v54 row_shr:2 row_mask:0xf bank_mask:0xf
	v_pk_fma_f32 v[20:21], v[106:107], v[100:101], v[24:25]
	v_fmac_f32_dpp v18, v10, v58 row_shl:15 row_mask:0xf bank_mask:0xf
	s_nop 0
	v_fmac_f32_dpp v18, v10, v54 row_shl:14 row_mask:0xf bank_mask:0xf
	v_fmac_f32_dpp v19, v109, v59 row_shr:1 row_mask:0xf bank_mask:0xf
	v_pk_fma_f32 v[24:25], v[12:13], v[100:101], v[24:25]
	v_fmac_f32_dpp v19, v109, v55 row_shr:2 row_mask:0xf bank_mask:0xf
	v_mul_f32_e32 v1, 0xbfb8aa3b, v18
	v_fmac_f32_dpp v19, v11, v59 row_shl:15 row_mask:0xf bank_mask:0xf
	v_exp_f32_e32 v1, v1
	v_fmac_f32_dpp v19, v11, v55 row_shl:14 row_mask:0xf bank_mask:0xf
	v_fmac_f32_dpp v20, v106, v60 row_shr:1 row_mask:0xf bank_mask:0xf
	s_nop 0
	v_fmac_f32_dpp v20, v106, v56 row_shr:2 row_mask:0xf bank_mask:0xf
	v_add_f32_e32 v1, 1.0, v1
	v_fmac_f32_dpp v20, v12, v60 row_shl:15 row_mask:0xf bank_mask:0xf
	v_rcp_f32_e32 v26, v1
	v_fmac_f32_dpp v20, v12, v56 row_shl:14 row_mask:0xf bank_mask:0xf
	v_fmac_f32_dpp v21, v107, v61 row_shr:1 row_mask:0xf bank_mask:0xf
	v_mul_f32_e32 v1, 0xbfb8aa3b, v19
	v_fmac_f32_dpp v21, v107, v57 row_shr:2 row_mask:0xf bank_mask:0xf
	v_mul_f32_e32 v27, 0xbfb8aa3b, v20
	v_fmac_f32_dpp v21, v13, v61 row_shl:15 row_mask:0xf bank_mask:0xf
	v_exp_f32_e32 v27, v27
	v_fmac_f32_dpp v21, v13, v57 row_shl:14 row_mask:0xf bank_mask:0xf
	v_exp_f32_e32 v1, v1
	v_mul_f32_e32 v28, 0xbfb8aa3b, v21
	v_exp_f32_e32 v29, v28
	v_add_f32_e32 v27, 1.0, v27
	v_add_f32_e32 v1, 1.0, v1
	v_rcp_f32_e32 v28, v27
	v_add_f32_e32 v27, 1.0, v29
	v_rcp_f32_e32 v29, v27
	v_rcp_f32_e32 v27, v1
	v_pk_mul_f32 v[16:17], v[16:17], v[20:21]
	v_pk_mul_f32 v[14:15], v[14:15], v[18:19]
	v_pk_mul_f32 v[16:17], v[16:17], v[28:29]
	v_pk_mul_f32 v[14:15], v[14:15], v[26:27]
	v_pk_fma_f32 v[18:19], v[10:11], v[98:99], v[22:23]
	v_fmac_f32_dpp v18, v10, v58 row_shr:1 row_mask:0xf bank_mask:0xf
	s_nop 0
	v_fmac_f32_dpp v18, v10, v54 row_shr:2 row_mask:0xf bank_mask:0xf
	v_mov_b64_e32 v[22:23], s[66:67]
	v_fmac_f32_dpp v18, v74, v58 row_shl:15 row_mask:0xf bank_mask:0xf
	s_ashr_i32 s47, s46, 31
	v_fmac_f32_dpp v18, v74, v54 row_shl:14 row_mask:0xf bank_mask:0xf
	v_fmac_f32_dpp v19, v11, v59 row_shr:1 row_mask:0xf bank_mask:0xf
	s_andn2_b64 vcc, exec, s[4:5]
	v_fmac_f32_dpp v19, v11, v55 row_shr:2 row_mask:0xf bank_mask:0xf
	v_mul_f32_e32 v1, 0xbfb8aa3b, v18
	v_fmac_f32_dpp v19, v75, v59 row_shl:15 row_mask:0xf bank_mask:0xf
	v_exp_f32_e32 v1, v1
	v_fmac_f32_dpp v19, v75, v55 row_shl:14 row_mask:0xf bank_mask:0xf
	v_fmac_f32_dpp v24, v12, v60 row_shr:1 row_mask:0xf bank_mask:0xf
	s_mov_b64 s[4:5], -1
	v_fmac_f32_dpp v24, v12, v56 row_shr:2 row_mask:0xf bank_mask:0xf
	v_add_f32_e32 v1, 1.0, v1
	v_fmac_f32_dpp v24, v76, v60 row_shl:15 row_mask:0xf bank_mask:0xf
	v_rcp_f32_e32 v10, v1
	v_fmac_f32_dpp v24, v76, v56 row_shl:14 row_mask:0xf bank_mask:0xf
	v_fmac_f32_dpp v25, v13, v61 row_shr:1 row_mask:0xf bank_mask:0xf
	v_mul_f32_e32 v1, 0xbfb8aa3b, v19
	v_fmac_f32_dpp v25, v13, v57 row_shr:2 row_mask:0xf bank_mask:0xf
	v_mul_f32_e32 v11, 0xbfb8aa3b, v24
	v_fmac_f32_dpp v25, v77, v61 row_shl:15 row_mask:0xf bank_mask:0xf
	v_exp_f32_e32 v11, v11
	v_fmac_f32_dpp v25, v77, v57 row_shl:14 row_mask:0xf bank_mask:0xf
	v_exp_f32_e32 v1, v1
	v_mul_f32_e32 v12, 0xbfb8aa3b, v25
	v_exp_f32_e32 v13, v12
	v_add_f32_e32 v11, 1.0, v11
	v_add_f32_e32 v1, 1.0, v1
	v_rcp_f32_e32 v12, v11
	v_add_f32_e32 v11, 1.0, v13
	v_rcp_f32_e32 v13, v11
	v_rcp_f32_e32 v11, v1
	v_lshl_add_u32 v1, s28, 8, v185
	v_pk_mul_f32 v[20:21], v[72:73], v[24:25]
	v_mad_i64_i32 v[24:25], s[28:29], v1, s12, v[22:23]
	s_lshl_b64 s[28:29], s[46:47], 1
	v_pk_mul_f32 v[18:19], v[70:71], v[18:19]
	v_lshl_add_u64 v[24:25], v[24:25], 0, s[28:29]
	v_pk_mul_f32 v[12:13], v[20:21], v[12:13]
	v_pk_mul_f32 v[10:11], v[18:19], v[10:11]
	v_lshl_add_u64 v[24:25], v[24:25], 0, v[182:183]
	v_cvt_pk_bf16_f32 v18, v78, v79
	v_cvt_pk_bf16_f32 v19, v80, v81
	v_cvt_pk_bf16_f32 v20, v66, v67
	v_cvt_pk_bf16_f32 v21, v68, v69
	global_store_dwordx4 v[24:25], v[18:21], off
	v_or_b32_e32 v24, 16, v1
	v_mad_i64_i32 v[24:25], s[46:47], v24, s12, v[22:23]
	v_lshl_add_u64 v[24:25], v[24:25], 0, s[28:29]
	v_lshl_add_u64 v[24:25], v[24:25], 0, v[182:183]
	v_cvt_pk_bf16_f32 v18, v62, v63
	v_cvt_pk_bf16_f32 v19, v64, v65
	v_cvt_pk_bf16_f32 v20, v42, v43
	v_cvt_pk_bf16_f32 v21, v44, v45
	global_store_dwordx4 v[24:25], v[18:21], off
	v_or_b32_e32 v24, 32, v1
	v_mad_i64_i32 v[24:25], s[46:47], v24, s12, v[22:23]
	v_lshl_add_u64 v[24:25], v[24:25], 0, s[28:29]
	v_lshl_add_u64 v[24:25], v[24:25], 0, v[182:183]
	v_cvt_pk_bf16_f32 v18, v50, v51
	v_cvt_pk_bf16_f32 v19, v52, v53
	v_cvt_pk_bf16_f32 v20, v38, v39
	v_cvt_pk_bf16_f32 v21, v40, v41
	global_store_dwordx4 v[24:25], v[18:21], off
	v_or_b32_e32 v24, 48, v1
	v_mad_i64_i32 v[24:25], s[46:47], v24, s12, v[22:23]
	v_lshl_add_u64 v[24:25], v[24:25], 0, s[28:29]
	v_lshl_add_u64 v[24:25], v[24:25], 0, v[182:183]
	v_cvt_pk_bf16_f32 v18, v46, v47
	v_cvt_pk_bf16_f32 v19, v48, v49
	v_cvt_pk_bf16_f32 v20, v34, v35
	v_cvt_pk_bf16_f32 v21, v36, v37
	global_store_dwordx4 v[24:25], v[18:21], off
	v_add_u32_e32 v24, 0x80, v1
	s_nop 0
	v_cvt_pk_bf16_f32 v18, v102, v103
	v_cvt_pk_bf16_f32 v19, v104, v105
	v_cvt_pk_bf16_f32 v20, v10, v11
	v_mad_i64_i32 v[10:11], s[46:47], v24, s12, v[22:23]
	v_lshl_add_u64 v[10:11], v[10:11], 0, s[28:29]
	v_lshl_add_u64 v[10:11], v[10:11], 0, v[182:183]
	v_cvt_pk_bf16_f32 v21, v12, v13
	global_store_dwordx4 v[10:11], v[18:21], off
	v_cvt_pk_bf16_f32 v10, v94, v95
	v_cvt_pk_bf16_f32 v11, v96, v97
	v_cvt_pk_bf16_f32 v12, v14, v15
	v_add_u32_e32 v14, 0x90, v1
	v_mad_i64_i32 v[14:15], s[46:47], v14, s12, v[22:23]
	v_lshl_add_u64 v[14:15], v[14:15], 0, s[28:29]
	v_lshl_add_u64 v[14:15], v[14:15], 0, v[182:183]
	v_cvt_pk_bf16_f32 v13, v16, v17
	global_store_dwordx4 v[14:15], v[10:13], off
	s_nop 1
	v_cvt_pk_bf16_f32 v10, v90, v91
	v_cvt_pk_bf16_f32 v11, v92, v93
	v_cvt_pk_bf16_f32 v12, v6, v7
	v_add_u32_e32 v6, 0xa0, v1
	v_mad_i64_i32 v[6:7], s[46:47], v6, s12, v[22:23]
	v_lshl_add_u64 v[6:7], v[6:7], 0, s[28:29]
	v_lshl_add_u64 v[6:7], v[6:7], 0, v[182:183]
	v_add_u32_e32 v1, 0xb0, v1
	v_cvt_pk_bf16_f32 v13, v8, v9
	global_store_dwordx4 v[6:7], v[10:13], off
	v_cvt_pk_bf16_f32 v6, v86, v87
	v_cvt_pk_bf16_f32 v7, v88, v89
	v_cvt_pk_bf16_f32 v8, v2, v3
	v_mad_i64_i32 v[2:3], s[46:47], v1, s12, v[22:23]
	v_lshl_add_u64 v[2:3], v[2:3], 0, s[28:29]
	v_lshl_add_u64 v[2:3], v[2:3], 0, v[182:183]
	v_cvt_pk_bf16_f32 v9, v4, v5
	global_store_dwordx4 v[2:3], v[6:9], off
	s_cbranch_vccnz .LBB0_553
	s_andn2_b64 vcc, exec, s[16:17]
	s_mov_b32 s3, s40
	s_mov_b64 s[28:29], s[94:95]
	s_mov_b64 s[4:5], s[36:37]
	s_cbranch_vccnz .LBB0_590
	s_ashr_i32 s3, s40, 5
	s_mul_hi_i32 s4, s3, 0x5800
	s_mulk_i32 s3, 0x5800
	v_readlane_b32 s5, v255, 14
	s_add_u32 s28, s5, s3
	v_readlane_b32 s3, v255, 15
	s_addc_u32 s29, s3, s4
	s_mov_b32 s3, s38
	s_mov_b64 s[4:5], s[62:63]

.LBB0_829:
	global_load_dword v1, v[6:7], off
	global_load_dword v8, v[6:7], off offset:2048
	global_load_dword v10, v[4:5], off
	global_load_dword v11, v[4:5], off offset:2048
	v_add_co_u32_e32 v6, vcc, 0x1000, v4
	s_nop 1
	v_addc_co_u32_e32 v7, vcc, 0, v5, vcc
	global_load_dword v9, v[6:7], off
	global_load_dword v6, v[6:7], off offset:2048
	s_lshl_b32 s12, s95, 6
	s_and_b32 s12, s12, 0x1fc0
	v_add_u32_e32 v4, s12, v155
	v_mov_b32_e32 v5, v2
	v_cmp_lt_i32_e32 vcc, -1, v4
	s_lshl_b64 s[20:21], s[0:1], 15
	s_add_u32 s20, s3, s20
	s_addc_u32 s21, s7, s21
	s_and_b64 s[18:19], vcc, s[4:5]
	v_lshl_add_u64 v[4:5], v[4:5], 2, s[20:21]
	s_and_saveexec_b64 s[16:17], s[18:19]
	global_load_dword v7, v[4:5], off
	s_or_b64 exec, exec, s[16:17]
	s_waitcnt vmcnt(1)
	v_add_f32_e32 v9, 1.0, v9
	v_mul_f32_e32 v1, v1, v9
	ds_write2st64_b32 v3, v1, v10 offset1:16
	v_add_f32_e32 v6, 1.0, v6
	v_mul_f32_e32 v8, v8, v6
	v_add_u32_e32 v3, 0x800, v3
	ds_write2st64_b32 v3, v8, v11 offset1:16
	v_mov_b32_e32 v3, 0
	s_and_saveexec_b64 s[16:17], s[18:19]
	s_waitcnt vmcnt(0)
	v_fmamk_f32 v1, v7, 0x3a800000, v159
	v_mul_f32_e32 v3, 0x4b800000, v1
	v_cmp_gt_f32_e32 vcc, s81, v1
	s_nop 1
	v_cndmask_b32_e32 v1, v1, v3, vcc
	v_rsq_f32_e32 v1, v1
	s_nop 0
	v_mul_f32_e32 v3, 0x45800000, v1
	v_cndmask_b32_e32 v3, v1, v3, vcc
	s_or_b64 exec, exec, s[16:17]
	s_and_saveexec_b64 s[16:17], s[4:5]
	ds_write_b32 v156, v3 offset:8192

.LBB0_1323:
	s_or_b64 exec, exec, s[52:53]
	s_waitcnt lgkmcnt(0)
	s_barrier
	ds_read_b128 v[150:153], v223 offset:512
	ds_read_b128 v[154:157], v223 offset:1536
	ds_read_b128 v[162:165], v223 offset:2560
	ds_read_b128 v[138:141], v223 offset:3584
	v_mov_b32_e32 v158, 0
	v_mov_b32_e32 v159, 0
	v_mov_b32_e32 v160, 0
	v_mov_b32_e32 v161, 0
	s_and_saveexec_b64 s[52:53], s[36:37]
	v_add_u32_e32 v147, s77, v215
	ds_read_b128 v[158:161], v147 offset:512
	s_or_b64 exec, exec, s[52:53]
	v_fmamk_f32 v146, v146, 0x3a800000, v222
	v_rsq_f32_e32 v200, v146
	s_waitcnt lgkmcnt(0)
	v_fma_f32 v146, v166, v162, v138
	v_lshl_add_u32 v147, s30, 1, v1
	s_nop 4
	v_fmac_f32_dpp v146, v166, v154 row_shr:1 row_mask:0xf bank_mask:0xf
	v_mad_i64_i32 v[208:209], s[52:53], v147, s65, 0
	v_fmamk_f32 v147, v149, 0x3a800000, v222
	v_fmac_f32_dpp v146, v166, v150 row_shr:2 row_mask:0xf bank_mask:0xf
	v_rsq_f32_e32 v198, v147
	v_pk_fma_f32 v[78:79], v[78:79], v[200:201], v[122:123] op_sel_hi:[1,0,1]
	v_fma_f32 v147, v167, v163, v139
	v_fmac_f32_dpp v146, v78, v154 row_shl:15 row_mask:0xf bank_mask:0xf
	v_fmamk_f32 v148, v148, 0x3a800000, v222
	v_fmac_f32_dpp v146, v78, v150 row_shl:14 row_mask:0xf bank_mask:0xf
	v_fmac_f32_dpp v147, v167, v155 row_shr:1 row_mask:0xf bank_mask:0xf
	v_rsq_f32_e32 v196, v148
	v_fmac_f32_dpp v147, v167, v151 row_shr:2 row_mask:0xf bank_mask:0xf
	v_pk_fma_f32 v[148:149], v[168:169], v[164:165], v[140:141]
	v_fmac_f32_dpp v147, v79, v155 row_shl:15 row_mask:0xf bank_mask:0xf
	v_pk_fma_f32 v[80:81], v[80:81], v[200:201], v[124:125] op_sel_hi:[1,0,1]
	v_fmac_f32_dpp v147, v79, v151 row_shl:14 row_mask:0xf bank_mask:0xf
	v_fmac_f32_dpp v148, v168, v156 row_shr:1 row_mask:0xf bank_mask:0xf
	s_nop 0
	v_fmac_f32_dpp v148, v168, v152 row_shr:2 row_mask:0xf bank_mask:0xf
	v_pk_fma_f32 v[224:225], v[130:131], v[198:199], v[122:123] op_sel_hi:[1,0,1]
	v_fmac_f32_dpp v148, v80, v156 row_shl:15 row_mask:0xf bank_mask:0xf
	v_pk_fma_f32 v[130:131], v[78:79], v[162:163], v[138:139]
	v_fmac_f32_dpp v148, v80, v152 row_shl:14 row_mask:0xf bank_mask:0xf
	v_fmac_f32_dpp v149, v169, v157 row_shr:1 row_mask:0xf bank_mask:0xf
	s_nop 0
	v_fmac_f32_dpp v149, v169, v153 row_shr:2 row_mask:0xf bank_mask:0xf
	v_pk_fma_f32 v[210:211], v[132:133], v[198:199], v[124:125] op_sel_hi:[1,0,1]
	v_fmac_f32_dpp v149, v81, v157 row_shl:15 row_mask:0xf bank_mask:0xf
	v_pk_fma_f32 v[132:133], v[80:81], v[164:165], v[140:141]
	v_fmac_f32_dpp v149, v81, v153 row_shl:14 row_mask:0xf bank_mask:0xf
	s_nop 0
	v_fmac_f32_dpp v130, v78, v154 row_shr:1 row_mask:0xf bank_mask:0xf
	v_pk_fma_f32 v[134:135], v[134:135], v[196:197], v[122:123] op_sel_hi:[1,0,1]
	v_fmac_f32_dpp v130, v78, v150 row_shr:2 row_mask:0xf bank_mask:0xf
	v_fma_f32 v78, v224, v162, v138
	v_fmac_f32_dpp v130, v224, v154 row_shl:15 row_mask:0xf bank_mask:0xf
	v_pk_fma_f32 v[136:137], v[136:137], v[196:197], v[124:125] op_sel_hi:[1,0,1]
	v_fmac_f32_dpp v130, v224, v150 row_shl:14 row_mask:0xf bank_mask:0xf
	v_fmac_f32_dpp v131, v79, v155 row_shr:1 row_mask:0xf bank_mask:0xf
	v_fma_f32 v138, v134, v162, v138
	v_fmac_f32_dpp v131, v79, v151 row_shr:2 row_mask:0xf bank_mask:0xf
	v_fma_f32 v79, v225, v163, v139
	v_fmac_f32_dpp v131, v225, v155 row_shl:15 row_mask:0xf bank_mask:0xf
	v_fma_f32 v139, v135, v163, v139
	v_fmac_f32_dpp v131, v225, v151 row_shl:14 row_mask:0xf bank_mask:0xf
	v_fmac_f32_dpp v132, v80, v156 row_shr:1 row_mask:0xf bank_mask:0xf
	s_lshl_b32 s50, s50, 7
	v_fmac_f32_dpp v132, v80, v152 row_shr:2 row_mask:0xf bank_mask:0xf
	v_fma_f32 v80, v210, v164, v140
	v_fmac_f32_dpp v132, v210, v156 row_shl:15 row_mask:0xf bank_mask:0xf
	v_fma_f32 v140, v136, v164, v140
	v_fmac_f32_dpp v132, v210, v152 row_shl:14 row_mask:0xf bank_mask:0xf
	v_fmac_f32_dpp v133, v81, v157 row_shr:1 row_mask:0xf bank_mask:0xf
	v_or_b32_e32 v202, s50, v186
	v_fmac_f32_dpp v133, v81, v153 row_shr:2 row_mask:0xf bank_mask:0xf
	v_fma_f32 v81, v211, v165, v141
	v_fmac_f32_dpp v133, v211, v157 row_shl:15 row_mask:0xf bank_mask:0xf
	v_fmac_f32_e32 v141, v137, v165
	v_fmac_f32_dpp v133, v211, v153 row_shl:14 row_mask:0xf bank_mask:0xf
	v_ashrrev_i32_e32 v203, 31, v202
	v_fmac_f32_dpp v78, v224, v154 row_shr:1 row_mask:0xf bank_mask:0xf
	v_lshl_add_u64 v[168:169], s[28:29], 0, v[208:209]
	v_fmac_f32_dpp v78, v224, v150 row_shr:2 row_mask:0xf bank_mask:0xf
	v_lshl_add_u64 v[166:167], v[202:203], 2, v[168:169]
	v_fmac_f32_dpp v78, v134, v154 row_shl:15 row_mask:0xf bank_mask:0xf
	s_nop 0
	v_fmac_f32_dpp v78, v134, v150 row_shl:14 row_mask:0xf bank_mask:0xf
	v_fmac_f32_dpp v79, v225, v155 row_shr:1 row_mask:0xf bank_mask:0xf
	s_nop 0
	v_fmac_f32_dpp v79, v225, v151 row_shr:2 row_mask:0xf bank_mask:0xf
	s_nop 0
	v_fmac_f32_dpp v79, v135, v155 row_shl:15 row_mask:0xf bank_mask:0xf
	s_nop 0
	v_fmac_f32_dpp v79, v135, v151 row_shl:14 row_mask:0xf bank_mask:0xf
	v_fmac_f32_dpp v80, v210, v156 row_shr:1 row_mask:0xf bank_mask:0xf
	s_nop 0
	v_fmac_f32_dpp v80, v210, v152 row_shr:2 row_mask:0xf bank_mask:0xf
	s_nop 0
	v_fmac_f32_dpp v80, v136, v156 row_shl:15 row_mask:0xf bank_mask:0xf
	s_nop 0
	v_fmac_f32_dpp v80, v136, v152 row_shl:14 row_mask:0xf bank_mask:0xf
	v_fmac_f32_dpp v81, v211, v157 row_shr:1 row_mask:0xf bank_mask:0xf
	s_nop 0
	v_fmac_f32_dpp v81, v211, v153 row_shr:2 row_mask:0xf bank_mask:0xf
	s_nop 0
	v_fmac_f32_dpp v81, v137, v157 row_shl:15 row_mask:0xf bank_mask:0xf
	s_nop 0
	v_fmac_f32_dpp v81, v137, v153 row_shl:14 row_mask:0xf bank_mask:0xf
	s_nop 0
	v_fmac_f32_dpp v138, v134, v154 row_shr:1 row_mask:0xf bank_mask:0xf
	s_nop 0
	v_fmac_f32_dpp v138, v134, v150 row_shr:2 row_mask:0xf bank_mask:0xf
	s_nop 0
	v_fmac_f32_dpp v138, v158, v154 row_shl:15 row_mask:0xf bank_mask:0xf
	s_nop 0
	v_fmac_f32_dpp v138, v158, v150 row_shl:14 row_mask:0xf bank_mask:0xf
	v_fmac_f32_dpp v139, v135, v155 row_shr:1 row_mask:0xf bank_mask:0xf
	s_nop 0
	v_fmac_f32_dpp v139, v135, v151 row_shr:2 row_mask:0xf bank_mask:0xf
	s_nop 0
	v_fmac_f32_dpp v139, v159, v155 row_shl:15 row_mask:0xf bank_mask:0xf
	s_nop 0
	v_fmac_f32_dpp v139, v159, v151 row_shl:14 row_mask:0xf bank_mask:0xf
	v_fmac_f32_dpp v140, v136, v156 row_shr:1 row_mask:0xf bank_mask:0xf
	s_nop 0
	v_fmac_f32_dpp v140, v136, v152 row_shr:2 row_mask:0xf bank_mask:0xf
	s_nop 0
	v_fmac_f32_dpp v140, v160, v156 row_shl:15 row_mask:0xf bank_mask:0xf
	s_nop 0
	v_fmac_f32_dpp v140, v160, v152 row_shl:14 row_mask:0xf bank_mask:0xf
	v_fmac_f32_dpp v141, v137, v157 row_shr:1 row_mask:0xf bank_mask:0xf
	s_nop 0
	v_fmac_f32_dpp v141, v137, v153 row_shr:2 row_mask:0xf bank_mask:0xf
	s_nop 0
	v_fmac_f32_dpp v141, v161, v157 row_shl:15 row_mask:0xf bank_mask:0xf
	s_nop 0
	v_fmac_f32_dpp v141, v161, v153 row_shl:14 row_mask:0xf bank_mask:0xf
	s_and_saveexec_b64 s[52:53], s[38:39]
	s_cbranch_execz .LBB0_1327
	v_add_co_u32_e32 v134, vcc, 0x2000, v166
	s_nop 1
	v_addc_co_u32_e32 v135, vcc, 0, v167, vcc
	global_store_dwordx4 v[134:135], v[138:141], off offset:3072
.LBB0_1327:
	s_or_b64 exec, exec, s[52:53]
	s_nop 0
	ds_read_b128 v[150:153], v223
	ds_read_b128 v[154:157], v223 offset:1024
	ds_read_b128 v[162:165], v223 offset:2048
	ds_read_b128 v[134:137], v223 offset:3072
	v_mov_b32_e32 v158, 0
	v_mov_b32_e32 v159, 0
	v_mov_b32_e32 v160, 0
	v_mov_b32_e32 v161, 0
	s_and_saveexec_b64 s[52:53], s[36:37]
	v_add_u32_e32 v158, 0, v215
	v_add_u32_e32 v158, 0x20000, v158
	ds_read_b128 v[158:161], v158
	s_or_b64 exec, exec, s[52:53]
	v_mov_b32_e32 v197, v196
	v_mov_b32_e32 v201, v200
	v_pk_fma_f32 v[210:211], v[62:63], v[196:197], v[118:119]
	v_mov_b32_e32 v62, v198
	v_mov_b32_e32 v63, v198
	v_pk_fma_f32 v[62:63], v[52:53], v[62:63], v[120:121]
	v_pk_fma_f32 v[52:53], v[46:47], v[200:201], v[118:119]
	s_waitcnt lgkmcnt(0)
	v_pk_fma_f32 v[46:47], v[142:143], v[162:163], v[134:135]
	s_nop 4
	v_fmac_f32_dpp v46, v142, v154 row_shr:1 row_mask:0xf bank_mask:0xf
	s_nop 0
	v_fmac_f32_dpp v46, v142, v150 row_shr:2 row_mask:0xf bank_mask:0xf
	v_mov_b32_e32 v199, v198
	v_fmac_f32_dpp v46, v52, v154 row_shl:15 row_mask:0xf bank_mask:0xf
	v_mov_b32_e32 v208, v196
	v_mov_b32_e32 v209, v196
	v_fmac_f32_dpp v46, v52, v150 row_shl:14 row_mask:0xf bank_mask:0xf
	v_fmac_f32_dpp v47, v143, v155 row_shr:1 row_mask:0xf bank_mask:0xf
	v_pk_fma_f32 v[208:209], v[64:65], v[208:209], v[120:121]
	v_pk_fma_f32 v[64:65], v[50:51], v[198:199], v[118:119]
	v_mov_b32_e32 v50, v200
	v_mov_b32_e32 v51, v200
	v_fmac_f32_dpp v47, v143, v151 row_shr:2 row_mask:0xf bank_mask:0xf
	v_pk_fma_f32 v[50:51], v[48:49], v[50:51], v[120:121]
	v_fmac_f32_dpp v47, v53, v155 row_shl:15 row_mask:0xf bank_mask:0xf
	v_pk_fma_f32 v[48:49], v[144:145], v[164:165], v[136:137]
	v_fmac_f32_dpp v47, v53, v151 row_shl:14 row_mask:0xf bank_mask:0xf
	v_fmac_f32_dpp v48, v144, v156 row_shr:1 row_mask:0xf bank_mask:0xf
	s_nop 0
	v_fmac_f32_dpp v48, v144, v152 row_shr:2 row_mask:0xf bank_mask:0xf
	v_mul_f32_e32 v142, 0xbfb8aa3b, v46
	v_fmac_f32_dpp v48, v50, v156 row_shl:15 row_mask:0xf bank_mask:0xf
	v_mul_f32_e32 v143, 0xbfb8aa3b, v47
	v_fmac_f32_dpp v48, v50, v152 row_shl:14 row_mask:0xf bank_mask:0xf
	v_fmac_f32_dpp v49, v145, v157 row_shr:1 row_mask:0xf bank_mask:0xf
	v_exp_f32_e32 v142, v142
	v_fmac_f32_dpp v49, v145, v153 row_shr:2 row_mask:0xf bank_mask:0xf
	v_mul_f32_e32 v144, 0xbfb8aa3b, v48
	v_fmac_f32_dpp v49, v51, v157 row_shl:15 row_mask:0xf bank_mask:0xf
	v_exp_f32_e32 v143, v143
	v_fmac_f32_dpp v49, v51, v153 row_shl:14 row_mask:0xf bank_mask:0xf
	v_exp_f32_e32 v144, v144
	v_mul_f32_e32 v145, 0xbfb8aa3b, v49
	v_exp_f32_e32 v145, v145
	v_add_f32_e32 v142, 1.0, v142
	v_add_f32_e32 v143, 1.0, v143
	v_add_f32_e32 v144, 1.0, v144
	v_add_f32_e32 v145, 1.0, v145
	v_rcp_f32_e32 v142, v142
	v_rcp_f32_e32 v144, v144
	v_rcp_f32_e32 v145, v145
	v_rcp_f32_e32 v143, v143
	v_pk_mul_f32 v[48:49], v[148:149], v[48:49]
	v_pk_mul_f32 v[46:47], v[146:147], v[46:47]
	v_pk_mul_f32 v[48:49], v[48:49], v[144:145]
	v_pk_mul_f32 v[46:47], v[46:47], v[142:143]
	v_pk_fma_f32 v[142:143], v[52:53], v[162:163], v[134:135]
	v_fmac_f32_dpp v142, v52, v154 row_shr:1 row_mask:0xf bank_mask:0xf
	s_nop 0
	v_fmac_f32_dpp v142, v52, v150 row_shr:2 row_mask:0xf bank_mask:0xf
	v_fma_f32 v52, v50, v164, v136
	v_fmac_f32_dpp v142, v64, v154 row_shl:15 row_mask:0xf bank_mask:0xf
	s_nop 0
	v_fmac_f32_dpp v142, v64, v150 row_shl:14 row_mask:0xf bank_mask:0xf
	v_fmac_f32_dpp v143, v53, v155 row_shr:1 row_mask:0xf bank_mask:0xf
	s_nop 0
	v_fmac_f32_dpp v143, v53, v151 row_shr:2 row_mask:0xf bank_mask:0xf
	v_fma_f32 v53, v51, v165, v137
	v_fmac_f32_dpp v143, v65, v155 row_shl:15 row_mask:0xf bank_mask:0xf
	s_nop 0
	v_fmac_f32_dpp v143, v65, v151 row_shl:14 row_mask:0xf bank_mask:0xf
	v_fmac_f32_dpp v52, v50, v156 row_shr:1 row_mask:0xf bank_mask:0xf
	s_nop 0
	v_fmac_f32_dpp v52, v50, v152 row_shr:2 row_mask:0xf bank_mask:0xf
	v_mul_f32_e32 v50, 0xbfb8aa3b, v142
	v_fmac_f32_dpp v52, v62, v156 row_shl:15 row_mask:0xf bank_mask:0xf
	v_exp_f32_e32 v50, v50
	v_fmac_f32_dpp v52, v62, v152 row_shl:14 row_mask:0xf bank_mask:0xf
	v_fmac_f32_dpp v53, v51, v157 row_shr:1 row_mask:0xf bank_mask:0xf
	v_pk_mul_f32 v[130:131], v[130:131], v[142:143]
	v_fmac_f32_dpp v53, v51, v153 row_shr:2 row_mask:0xf bank_mask:0xf
	v_mul_f32_e32 v51, 0xbfb8aa3b, v143
	v_fmac_f32_dpp v53, v63, v157 row_shl:15 row_mask:0xf bank_mask:0xf
	v_mul_f32_e32 v144, 0xbfb8aa3b, v52
	v_fmac_f32_dpp v53, v63, v153 row_shl:14 row_mask:0xf bank_mask:0xf
	v_exp_f32_e32 v51, v51
	v_mul_f32_e32 v145, 0xbfb8aa3b, v53
	v_exp_f32_e32 v144, v144
	v_exp_f32_e32 v145, v145
	v_add_f32_e32 v50, 1.0, v50
	v_add_f32_e32 v51, 1.0, v51
	v_add_f32_e32 v144, 1.0, v144
	v_add_f32_e32 v145, 1.0, v145
	v_rcp_f32_e32 v50, v50
	v_rcp_f32_e32 v144, v144
	v_rcp_f32_e32 v145, v145
	v_rcp_f32_e32 v51, v51
	v_pk_mul_f32 v[52:53], v[132:133], v[52:53]
	v_pk_mul_f32 v[50:51], v[130:131], v[50:51]
	v_pk_mul_f32 v[52:53], v[52:53], v[144:145]
	v_pk_fma_f32 v[130:131], v[64:65], v[162:163], v[134:135]
	v_fmac_f32_dpp v130, v64, v154 row_shr:1 row_mask:0xf bank_mask:0xf
	s_nop 0
	v_fmac_f32_dpp v130, v64, v150 row_shr:2 row_mask:0xf bank_mask:0xf
	v_fma_f32 v64, v62, v164, v136
	v_fmac_f32_dpp v130, v210, v154 row_shl:15 row_mask:0xf bank_mask:0xf
	v_pk_fma_f32 v[134:135], v[210:211], v[162:163], v[134:135]
	v_fmac_f32_dpp v130, v210, v150 row_shl:14 row_mask:0xf bank_mask:0xf
	v_fmac_f32_dpp v131, v65, v155 row_shr:1 row_mask:0xf bank_mask:0xf
	s_nop 0
	v_fmac_f32_dpp v131, v65, v151 row_shr:2 row_mask:0xf bank_mask:0xf
	v_fma_f32 v65, v63, v165, v137
	v_fmac_f32_dpp v131, v211, v155 row_shl:15 row_mask:0xf bank_mask:0xf
	v_pk_fma_f32 v[136:137], v[208:209], v[164:165], v[136:137]
	v_fmac_f32_dpp v131, v211, v151 row_shl:14 row_mask:0xf bank_mask:0xf
	v_fmac_f32_dpp v64, v62, v156 row_shr:1 row_mask:0xf bank_mask:0xf
	s_nop 0
	v_fmac_f32_dpp v64, v62, v152 row_shr:2 row_mask:0xf bank_mask:0xf
	v_mul_f32_e32 v62, 0xbfb8aa3b, v130
	v_fmac_f32_dpp v64, v208, v156 row_shl:15 row_mask:0xf bank_mask:0xf
	v_exp_f32_e32 v62, v62
	v_fmac_f32_dpp v64, v208, v152 row_shl:14 row_mask:0xf bank_mask:0xf
	v_fmac_f32_dpp v65, v63, v157 row_shr:1 row_mask:0xf bank_mask:0xf
	v_pk_mul_f32 v[78:79], v[78:79], v[130:131]
	v_fmac_f32_dpp v65, v63, v153 row_shr:2 row_mask:0xf bank_mask:0xf
	v_mul_f32_e32 v63, 0xbfb8aa3b, v131
	v_fmac_f32_dpp v65, v209, v157 row_shl:15 row_mask:0xf bank_mask:0xf
	v_mul_f32_e32 v132, 0xbfb8aa3b, v64
	v_fmac_f32_dpp v65, v209, v153 row_shl:14 row_mask:0xf bank_mask:0xf
	v_exp_f32_e32 v63, v63
	v_mul_f32_e32 v133, 0xbfb8aa3b, v65
	v_exp_f32_e32 v132, v132
	v_exp_f32_e32 v133, v133
	v_add_f32_e32 v62, 1.0, v62
	v_add_f32_e32 v63, 1.0, v63
	v_add_f32_e32 v132, 1.0, v132
	v_add_f32_e32 v133, 1.0, v133
	v_rcp_f32_e32 v62, v62
	v_rcp_f32_e32 v132, v132
	v_rcp_f32_e32 v133, v133
	v_rcp_f32_e32 v63, v63
	v_pk_mul_f32 v[64:65], v[80:81], v[64:65]
	v_pk_mul_f32 v[62:63], v[78:79], v[62:63]
	v_pk_mul_f32 v[64:65], v[64:65], v[132:133]
	s_nop 0
	v_fmac_f32_dpp v134, v210, v154 row_shr:1 row_mask:0xf bank_mask:0xf
	s_nop 0
	v_fmac_f32_dpp v134, v210, v150 row_shr:2 row_mask:0xf bank_mask:0xf
	s_nop 0
	v_fmac_f32_dpp v134, v158, v154 row_shl:15 row_mask:0xf bank_mask:0xf
	s_nop 0
	v_fmac_f32_dpp v134, v158, v150 row_shl:14 row_mask:0xf bank_mask:0xf
	v_fmac_f32_dpp v135, v211, v155 row_shr:1 row_mask:0xf bank_mask:0xf
	s_nop 0
	v_fmac_f32_dpp v135, v211, v151 row_shr:2 row_mask:0xf bank_mask:0xf
	s_nop 0
	v_fmac_f32_dpp v135, v159, v155 row_shl:15 row_mask:0xf bank_mask:0xf
	s_nop 0
	v_fmac_f32_dpp v135, v159, v151 row_shl:14 row_mask:0xf bank_mask:0xf
	v_fmac_f32_dpp v136, v208, v156 row_shr:1 row_mask:0xf bank_mask:0xf
	s_nop 0
	v_fmac_f32_dpp v136, v208, v152 row_shr:2 row_mask:0xf bank_mask:0xf
	s_nop 0
	v_fmac_f32_dpp v136, v160, v156 row_shl:15 row_mask:0xf bank_mask:0xf
	s_nop 0
	v_fmac_f32_dpp v136, v160, v152 row_shl:14 row_mask:0xf bank_mask:0xf
	v_fmac_f32_dpp v137, v209, v157 row_shr:1 row_mask:0xf bank_mask:0xf
	s_nop 0
	v_fmac_f32_dpp v137, v209, v153 row_shr:2 row_mask:0xf bank_mask:0xf
	s_nop 0
	v_fmac_f32_dpp v137, v161, v157 row_shl:15 row_mask:0xf bank_mask:0xf
	s_nop 0
	v_fmac_f32_dpp v137, v161, v153 row_shl:14 row_mask:0xf bank_mask:0xf
	s_and_saveexec_b64 s[52:53], s[38:39]
	s_cbranch_execz .LBB0_1331
	global_store_dwordx4 v[166:167], v[134:137], off
.LBB0_1331:
	s_or_b64 exec, exec, s[52:53]
	v_mul_f32_e32 v78, 0xbfb8aa3b, v134
	v_mul_f32_e32 v79, 0xbfb8aa3b, v135
	v_mul_f32_e32 v80, 0xbfb8aa3b, v136
	v_mul_f32_e32 v81, 0xbfb8aa3b, v137
	v_exp_f32_e32 v78, v78
	v_exp_f32_e32 v79, v79
	v_exp_f32_e32 v80, v80
	v_exp_f32_e32 v81, v81
	v_add_f32_e32 v78, 1.0, v78
	v_add_f32_e32 v79, 1.0, v79
	v_add_f32_e32 v80, 1.0, v80
	v_add_f32_e32 v81, 1.0, v81
	v_rcp_f32_e32 v78, v78
	v_rcp_f32_e32 v80, v80
	v_rcp_f32_e32 v81, v81
	v_rcp_f32_e32 v79, v79
	v_pk_mul_f32 v[130:131], v[140:141], v[136:137]
	v_pk_mul_f32 v[132:133], v[138:139], v[134:135]
	v_pk_mul_f32 v[80:81], v[130:131], v[80:81]
	v_pk_mul_f32 v[78:79], v[132:133], v[78:79]
	v_mov_b32_e32 v134, 0
	ds_read_b128 v[142:145], v223 offset:512
	ds_read_b128 v[146:149], v223 offset:1536
	ds_read_b128 v[154:157], v223 offset:2560
	ds_read_b128 v[130:133], v223 offset:3584
	v_mov_b32_e32 v150, 0
	v_mov_b32_e32 v151, 0
	v_mov_b32_e32 v152, 0
	v_mov_b32_e32 v153, 0
	s_and_saveexec_b64 s[52:53], s[0:1]
	v_add_u32_e32 v135, s77, v216
	ds_read_b128 v[150:153], v135 offset:512
	s_or_b64 exec, exec, s[52:53]
	v_fmamk_f32 v136, v204, 0x3a800000, v222
	v_rsq_f32_e32 v160, v136
	s_waitcnt lgkmcnt(0)
	v_pk_fma_f32 v[138:139], v[126:127], v[154:155], v[130:131]
	s_nop 4
	v_fmac_f32_dpp v138, v126, v146 row_shr:1 row_mask:0xf bank_mask:0xf
	v_pk_fma_f32 v[102:103], v[102:103], v[160:161], v[122:123] op_sel_hi:[1,0,1]
	v_fmac_f32_dpp v138, v126, v142 row_shr:2 row_mask:0xf bank_mask:0xf
	s_nop 0
	v_fmac_f32_dpp v138, v102, v146 row_shl:15 row_mask:0xf bank_mask:0xf
	v_pk_fma_f32 v[140:141], v[128:129], v[156:157], v[132:133]
	v_fmac_f32_dpp v138, v102, v142 row_shl:14 row_mask:0xf bank_mask:0xf
	v_fmac_f32_dpp v139, v127, v147 row_shr:1 row_mask:0xf bank_mask:0xf
	v_fmamk_f32 v135, v206, 0x3a800000, v222
	v_fmac_f32_dpp v139, v127, v143 row_shr:2 row_mask:0xf bank_mask:0xf
	v_rsq_f32_e32 v158, v135
	v_fmac_f32_dpp v139, v103, v147 row_shl:15 row_mask:0xf bank_mask:0xf
	v_fmamk_f32 v135, v207, 0x3a800000, v222
	v_fmac_f32_dpp v139, v103, v143 row_shl:14 row_mask:0xf bank_mask:0xf
	v_fmac_f32_dpp v140, v128, v148 row_shr:1 row_mask:0xf bank_mask:0xf
	v_rsq_f32_e32 v162, v135
	v_fmac_f32_dpp v140, v128, v144 row_shr:2 row_mask:0xf bank_mask:0xf
	v_pk_fma_f32 v[104:105], v[104:105], v[160:161], v[124:125] op_sel_hi:[1,0,1]
	s_nop 0
	v_fmac_f32_dpp v140, v104, v148 row_shl:15 row_mask:0xf bank_mask:0xf
	v_pk_fma_f32 v[164:165], v[106:107], v[162:163], v[122:123] op_sel_hi:[1,0,1]
	v_fmac_f32_dpp v140, v104, v144 row_shl:14 row_mask:0xf bank_mask:0xf
	v_fmac_f32_dpp v141, v129, v149 row_shr:1 row_mask:0xf bank_mask:0xf
	v_pk_fma_f32 v[106:107], v[102:103], v[154:155], v[130:131]
	v_fmac_f32_dpp v141, v129, v145 row_shr:2 row_mask:0xf bank_mask:0xf
	s_nop 0
	v_fmac_f32_dpp v141, v105, v149 row_shl:15 row_mask:0xf bank_mask:0xf
	v_pk_fma_f32 v[136:137], v[108:109], v[162:163], v[124:125] op_sel_hi:[1,0,1]
	v_fmac_f32_dpp v141, v105, v145 row_shl:14 row_mask:0xf bank_mask:0xf
	v_pk_fma_f32 v[108:109], v[104:105], v[156:157], v[132:133]
	v_fmac_f32_dpp v106, v102, v146 row_shr:1 row_mask:0xf bank_mask:0xf
	s_nop 0
	v_fmac_f32_dpp v106, v102, v142 row_shr:2 row_mask:0xf bank_mask:0xf
	v_fma_f32 v102, v164, v154, v130
	v_fmac_f32_dpp v106, v164, v146 row_shl:15 row_mask:0xf bank_mask:0xf
	v_pk_fma_f32 v[110:111], v[110:111], v[158:159], v[122:123] op_sel_hi:[1,0,1]
	v_fmac_f32_dpp v106, v164, v142 row_shl:14 row_mask:0xf bank_mask:0xf
	v_fmac_f32_dpp v107, v103, v147 row_shr:1 row_mask:0xf bank_mask:0xf
	v_pk_fma_f32 v[112:113], v[112:113], v[158:159], v[124:125] op_sel_hi:[1,0,1]
	v_fmac_f32_dpp v107, v103, v143 row_shr:2 row_mask:0xf bank_mask:0xf
	v_fma_f32 v103, v165, v155, v131
	v_fmac_f32_dpp v107, v165, v147 row_shl:15 row_mask:0xf bank_mask:0xf
	v_pk_fma_f32 v[130:131], v[110:111], v[154:155], v[130:131]
	v_fmac_f32_dpp v107, v165, v143 row_shl:14 row_mask:0xf bank_mask:0xf
	v_fmac_f32_dpp v108, v104, v148 row_shr:1 row_mask:0xf bank_mask:0xf
	s_nop 0
	v_fmac_f32_dpp v108, v104, v144 row_shr:2 row_mask:0xf bank_mask:0xf
	v_fma_f32 v104, v136, v156, v132
	v_fmac_f32_dpp v108, v136, v148 row_shl:15 row_mask:0xf bank_mask:0xf
	v_fma_f32 v132, v112, v156, v132
	v_fmac_f32_dpp v108, v136, v144 row_shl:14 row_mask:0xf bank_mask:0xf
	v_fmac_f32_dpp v109, v105, v149 row_shr:1 row_mask:0xf bank_mask:0xf
	v_mov_b32_e32 v135, 0
	v_fmac_f32_dpp v109, v105, v145 row_shr:2 row_mask:0xf bank_mask:0xf
	v_fma_f32 v105, v137, v157, v133
	v_fmac_f32_dpp v109, v137, v149 row_shl:15 row_mask:0xf bank_mask:0xf
	v_fmac_f32_e32 v133, v113, v157
	v_fmac_f32_dpp v109, v137, v145 row_shl:14 row_mask:0xf bank_mask:0xf
	s_nop 0
	v_fmac_f32_dpp v102, v164, v146 row_shr:1 row_mask:0xf bank_mask:0xf
	s_nop 0
	v_fmac_f32_dpp v102, v164, v142 row_shr:2 row_mask:0xf bank_mask:0xf
	s_nop 0
	v_fmac_f32_dpp v102, v110, v146 row_shl:15 row_mask:0xf bank_mask:0xf
	s_nop 0
	v_fmac_f32_dpp v102, v110, v142 row_shl:14 row_mask:0xf bank_mask:0xf
	v_fmac_f32_dpp v103, v165, v147 row_shr:1 row_mask:0xf bank_mask:0xf
	s_nop 0
	v_fmac_f32_dpp v103, v165, v143 row_shr:2 row_mask:0xf bank_mask:0xf
	s_nop 0
	v_fmac_f32_dpp v103, v111, v147 row_shl:15 row_mask:0xf bank_mask:0xf
	s_nop 0
	v_fmac_f32_dpp v103, v111, v143 row_shl:14 row_mask:0xf bank_mask:0xf
	v_fmac_f32_dpp v104, v136, v148 row_shr:1 row_mask:0xf bank_mask:0xf
	s_nop 0
	v_fmac_f32_dpp v104, v136, v144 row_shr:2 row_mask:0xf bank_mask:0xf
	v_mov_b32_e32 v136, 0
	v_fmac_f32_dpp v104, v112, v148 row_shl:15 row_mask:0xf bank_mask:0xf
	s_nop 0
	v_fmac_f32_dpp v104, v112, v144 row_shl:14 row_mask:0xf bank_mask:0xf
	v_fmac_f32_dpp v105, v137, v149 row_shr:1 row_mask:0xf bank_mask:0xf
	s_nop 0
	v_fmac_f32_dpp v105, v137, v145 row_shr:2 row_mask:0xf bank_mask:0xf
	v_mov_b32_e32 v137, 0
	v_fmac_f32_dpp v105, v113, v149 row_shl:15 row_mask:0xf bank_mask:0xf
	s_nop 0
	v_fmac_f32_dpp v105, v113, v145 row_shl:14 row_mask:0xf bank_mask:0xf
	s_nop 0
	v_fmac_f32_dpp v130, v110, v146 row_shr:1 row_mask:0xf bank_mask:0xf
	s_nop 0
	v_fmac_f32_dpp v130, v110, v142 row_shr:2 row_mask:0xf bank_mask:0xf
	s_nop 0
	v_fmac_f32_dpp v130, v150, v146 row_shl:15 row_mask:0xf bank_mask:0xf
	s_nop 0
	v_fmac_f32_dpp v130, v150, v142 row_shl:14 row_mask:0xf bank_mask:0xf
	v_fmac_f32_dpp v131, v111, v147 row_shr:1 row_mask:0xf bank_mask:0xf
	s_nop 0
	v_fmac_f32_dpp v131, v111, v143 row_shr:2 row_mask:0xf bank_mask:0xf
	s_nop 0
	v_fmac_f32_dpp v131, v151, v147 row_shl:15 row_mask:0xf bank_mask:0xf
	s_nop 0
	v_fmac_f32_dpp v131, v151, v143 row_shl:14 row_mask:0xf bank_mask:0xf
	v_fmac_f32_dpp v132, v112, v148 row_shr:1 row_mask:0xf bank_mask:0xf
	s_nop 0
	v_fmac_f32_dpp v132, v112, v144 row_shr:2 row_mask:0xf bank_mask:0xf
	s_nop 0
	v_fmac_f32_dpp v132, v152, v148 row_shl:15 row_mask:0xf bank_mask:0xf
	s_nop 0
	v_fmac_f32_dpp v132, v152, v144 row_shl:14 row_mask:0xf bank_mask:0xf
	v_fmac_f32_dpp v133, v113, v149 row_shr:1 row_mask:0xf bank_mask:0xf
	s_nop 0
	v_fmac_f32_dpp v133, v113, v145 row_shr:2 row_mask:0xf bank_mask:0xf
	s_nop 0
	v_fmac_f32_dpp v133, v153, v149 row_shl:15 row_mask:0xf bank_mask:0xf
	s_nop 0
	v_fmac_f32_dpp v133, v153, v145 row_shl:14 row_mask:0xf bank_mask:0xf
	s_nop 0
	ds_read_b128 v[122:125], v223
	ds_read_b128 v[126:129], v223 offset:1024
	ds_read_b128 v[142:145], v223 offset:2048
	ds_read_b128 v[110:113], v223 offset:3072
	s_and_saveexec_b64 s[52:53], s[0:1]
	v_add_u32_e32 v134, 0, v216
	v_add_u32_e32 v134, 0x20000, v134
	ds_read_b128 v[134:137], v134
	s_or_b64 exec, exec, s[52:53]
	v_mov_b32_e32 v159, v158
	v_mov_b32_e32 v161, v160
	v_pk_fma_f32 v[148:149], v[94:95], v[158:159], v[118:119]
	v_mov_b32_e32 v94, v162
	v_mov_b32_e32 v95, v162
	v_pk_fma_f32 v[94:95], v[92:93], v[94:95], v[120:121]
	v_pk_fma_f32 v[92:93], v[86:87], v[160:161], v[118:119]
	s_waitcnt lgkmcnt(0)
	v_pk_fma_f32 v[86:87], v[114:115], v[142:143], v[110:111]
	s_nop 4
	v_fmac_f32_dpp v86, v114, v126 row_shr:1 row_mask:0xf bank_mask:0xf
	s_nop 0
	v_fmac_f32_dpp v86, v114, v122 row_shr:2 row_mask:0xf bank_mask:0xf
	v_mov_b32_e32 v163, v162
	v_fmac_f32_dpp v86, v92, v126 row_shl:15 row_mask:0xf bank_mask:0xf
	v_mov_b32_e32 v146, v158
	v_mov_b32_e32 v147, v158
	v_fmac_f32_dpp v86, v92, v122 row_shl:14 row_mask:0xf bank_mask:0xf
	v_fmac_f32_dpp v87, v115, v127 row_shr:1 row_mask:0xf bank_mask:0xf
	v_pk_fma_f32 v[146:147], v[96:97], v[146:147], v[120:121]
	v_pk_fma_f32 v[96:97], v[90:91], v[162:163], v[118:119]
	v_mov_b32_e32 v90, v160
	v_mov_b32_e32 v91, v160
	v_fmac_f32_dpp v87, v115, v123 row_shr:2 row_mask:0xf bank_mask:0xf
	v_pk_fma_f32 v[90:91], v[88:89], v[90:91], v[120:121]
	v_fmac_f32_dpp v87, v93, v127 row_shl:15 row_mask:0xf bank_mask:0xf
	v_pk_fma_f32 v[88:89], v[116:117], v[144:145], v[112:113]
	v_fmac_f32_dpp v87, v93, v123 row_shl:14 row_mask:0xf bank_mask:0xf
	v_fmac_f32_dpp v88, v116, v128 row_shr:1 row_mask:0xf bank_mask:0xf
	s_nop 0
	v_fmac_f32_dpp v88, v116, v124 row_shr:2 row_mask:0xf bank_mask:0xf
	v_mul_f32_e32 v114, 0xbfb8aa3b, v86
	v_fmac_f32_dpp v88, v90, v128 row_shl:15 row_mask:0xf bank_mask:0xf
	v_mul_f32_e32 v115, 0xbfb8aa3b, v87
	v_fmac_f32_dpp v88, v90, v124 row_shl:14 row_mask:0xf bank_mask:0xf
	v_fmac_f32_dpp v89, v117, v129 row_shr:1 row_mask:0xf bank_mask:0xf
	v_exp_f32_e32 v114, v114
	v_fmac_f32_dpp v89, v117, v125 row_shr:2 row_mask:0xf bank_mask:0xf
	v_mul_f32_e32 v116, 0xbfb8aa3b, v88
	v_fmac_f32_dpp v89, v91, v129 row_shl:15 row_mask:0xf bank_mask:0xf
	v_exp_f32_e32 v115, v115
	v_fmac_f32_dpp v89, v91, v125 row_shl:14 row_mask:0xf bank_mask:0xf
	v_exp_f32_e32 v116, v116
	v_mul_f32_e32 v117, 0xbfb8aa3b, v89
	v_exp_f32_e32 v117, v117
	v_add_f32_e32 v114, 1.0, v114
	v_add_f32_e32 v115, 1.0, v115
	v_add_f32_e32 v116, 1.0, v116
	v_add_f32_e32 v117, 1.0, v117
	v_rcp_f32_e32 v114, v114
	v_rcp_f32_e32 v116, v116
	v_rcp_f32_e32 v117, v117
	v_rcp_f32_e32 v115, v115
	v_pk_mul_f32 v[88:89], v[140:141], v[88:89]
	v_pk_mul_f32 v[86:87], v[138:139], v[86:87]
	v_pk_mul_f32 v[88:89], v[88:89], v[116:117]
	v_pk_mul_f32 v[86:87], v[86:87], v[114:115]
	v_pk_fma_f32 v[114:115], v[92:93], v[142:143], v[110:111]
	v_fmac_f32_dpp v114, v92, v126 row_shr:1 row_mask:0xf bank_mask:0xf
	s_nop 0
	v_fmac_f32_dpp v114, v92, v122 row_shr:2 row_mask:0xf bank_mask:0xf
	v_fma_f32 v92, v90, v144, v112
	v_fmac_f32_dpp v114, v96, v126 row_shl:15 row_mask:0xf bank_mask:0xf
	s_nop 0
	v_fmac_f32_dpp v114, v96, v122 row_shl:14 row_mask:0xf bank_mask:0xf
	v_fmac_f32_dpp v115, v93, v127 row_shr:1 row_mask:0xf bank_mask:0xf
	s_nop 0
	v_fmac_f32_dpp v115, v93, v123 row_shr:2 row_mask:0xf bank_mask:0xf
	v_fma_f32 v93, v91, v145, v113
	v_fmac_f32_dpp v115, v97, v127 row_shl:15 row_mask:0xf bank_mask:0xf
	s_nop 0
	v_fmac_f32_dpp v115, v97, v123 row_shl:14 row_mask:0xf bank_mask:0xf
	v_fmac_f32_dpp v92, v90, v128 row_shr:1 row_mask:0xf bank_mask:0xf
	s_nop 0
	v_fmac_f32_dpp v92, v90, v124 row_shr:2 row_mask:0xf bank_mask:0xf
	v_mul_f32_e32 v90, 0xbfb8aa3b, v114
	v_fmac_f32_dpp v92, v94, v128 row_shl:15 row_mask:0xf bank_mask:0xf
	v_exp_f32_e32 v90, v90
	v_fmac_f32_dpp v92, v94, v124 row_shl:14 row_mask:0xf bank_mask:0xf
	v_fmac_f32_dpp v93, v91, v129 row_shr:1 row_mask:0xf bank_mask:0xf
	v_pk_mul_f32 v[106:107], v[106:107], v[114:115]
	v_fmac_f32_dpp v93, v91, v125 row_shr:2 row_mask:0xf bank_mask:0xf
	v_mul_f32_e32 v91, 0xbfb8aa3b, v115
	v_fmac_f32_dpp v93, v95, v129 row_shl:15 row_mask:0xf bank_mask:0xf
	v_mul_f32_e32 v116, 0xbfb8aa3b, v92
	v_fmac_f32_dpp v93, v95, v125 row_shl:14 row_mask:0xf bank_mask:0xf
	v_exp_f32_e32 v91, v91
	v_mul_f32_e32 v117, 0xbfb8aa3b, v93
	v_exp_f32_e32 v116, v116
	v_exp_f32_e32 v117, v117
	v_add_f32_e32 v90, 1.0, v90
	v_add_f32_e32 v91, 1.0, v91
	v_add_f32_e32 v116, 1.0, v116
	v_add_f32_e32 v117, 1.0, v117
	v_rcp_f32_e32 v90, v90
	v_rcp_f32_e32 v116, v116
	v_rcp_f32_e32 v117, v117
	v_rcp_f32_e32 v91, v91
	v_pk_mul_f32 v[92:93], v[108:109], v[92:93]
	v_pk_mul_f32 v[90:91], v[106:107], v[90:91]
	v_pk_mul_f32 v[92:93], v[92:93], v[116:117]
	v_pk_fma_f32 v[106:107], v[96:97], v[142:143], v[110:111]
	v_fmac_f32_dpp v106, v96, v126 row_shr:1 row_mask:0xf bank_mask:0xf
	s_nop 0
	v_fmac_f32_dpp v106, v96, v122 row_shr:2 row_mask:0xf bank_mask:0xf
	v_fma_f32 v96, v94, v144, v112
	v_fmac_f32_dpp v106, v148, v126 row_shl:15 row_mask:0xf bank_mask:0xf
	v_fma_f32 v112, v146, v144, v112
	v_fmac_f32_dpp v106, v148, v122 row_shl:14 row_mask:0xf bank_mask:0xf
	v_fmac_f32_dpp v107, v97, v127 row_shr:1 row_mask:0xf bank_mask:0xf
	s_nop 0
	v_fmac_f32_dpp v107, v97, v123 row_shr:2 row_mask:0xf bank_mask:0xf
	v_fma_f32 v97, v95, v145, v113
	v_fmac_f32_dpp v107, v149, v127 row_shl:15 row_mask:0xf bank_mask:0xf
	v_fmac_f32_e32 v113, v147, v145
	v_fmac_f32_dpp v107, v149, v123 row_shl:14 row_mask:0xf bank_mask:0xf
	v_fmac_f32_dpp v96, v94, v128 row_shr:1 row_mask:0xf bank_mask:0xf
	s_nop 0
	v_fmac_f32_dpp v96, v94, v124 row_shr:2 row_mask:0xf bank_mask:0xf
	v_mul_f32_e32 v94, 0xbfb8aa3b, v106
	v_fmac_f32_dpp v96, v146, v128 row_shl:15 row_mask:0xf bank_mask:0xf
	v_exp_f32_e32 v94, v94
	v_fmac_f32_dpp v96, v146, v124 row_shl:14 row_mask:0xf bank_mask:0xf
	v_fmac_f32_dpp v97, v95, v129 row_shr:1 row_mask:0xf bank_mask:0xf
	v_pk_mul_f32 v[102:103], v[102:103], v[106:107]
	v_fmac_f32_dpp v97, v95, v125 row_shr:2 row_mask:0xf bank_mask:0xf
	v_mul_f32_e32 v95, 0xbfb8aa3b, v107
	v_fmac_f32_dpp v97, v147, v129 row_shl:15 row_mask:0xf bank_mask:0xf
	v_mul_f32_e32 v108, 0xbfb8aa3b, v96
	v_fmac_f32_dpp v97, v147, v125 row_shl:14 row_mask:0xf bank_mask:0xf
	v_exp_f32_e32 v95, v95
	v_mul_f32_e32 v109, 0xbfb8aa3b, v97
	v_exp_f32_e32 v108, v108
	v_exp_f32_e32 v109, v109
	v_add_f32_e32 v94, 1.0, v94
	v_add_f32_e32 v95, 1.0, v95
	v_add_f32_e32 v108, 1.0, v108
	v_add_f32_e32 v109, 1.0, v109
	v_rcp_f32_e32 v94, v94
	v_rcp_f32_e32 v108, v108
	v_rcp_f32_e32 v109, v109
	v_rcp_f32_e32 v95, v95
	v_pk_mul_f32 v[96:97], v[104:105], v[96:97]
	v_pk_mul_f32 v[94:95], v[102:103], v[94:95]
	v_pk_mul_f32 v[96:97], v[96:97], v[108:109]
	v_pk_fma_f32 v[102:103], v[148:149], v[142:143], v[110:111]
	v_fmac_f32_dpp v102, v148, v126 row_shr:1 row_mask:0xf bank_mask:0xf
	s_nop 0
	v_fmac_f32_dpp v102, v148, v122 row_shr:2 row_mask:0xf bank_mask:0xf
	s_nop 0
	v_fmac_f32_dpp v102, v134, v126 row_shl:15 row_mask:0xf bank_mask:0xf
	s_nop 0
	v_fmac_f32_dpp v102, v134, v122 row_shl:14 row_mask:0xf bank_mask:0xf
	v_fmac_f32_dpp v103, v149, v127 row_shr:1 row_mask:0xf bank_mask:0xf
	v_mov_b32_e32 v122, 0
	v_fmac_f32_dpp v103, v149, v123 row_shr:2 row_mask:0xf bank_mask:0xf
	v_mul_f32_e32 v104, 0xbfb8aa3b, v102
	v_fmac_f32_dpp v103, v135, v127 row_shl:15 row_mask:0xf bank_mask:0xf
	v_exp_f32_e32 v104, v104
	v_fmac_f32_dpp v103, v135, v123 row_shl:14 row_mask:0xf bank_mask:0xf
	v_fmac_f32_dpp v112, v146, v128 row_shr:1 row_mask:0xf bank_mask:0xf
	v_mov_b32_e32 v123, 0
	v_fmac_f32_dpp v112, v146, v124 row_shr:2 row_mask:0xf bank_mask:0xf
	v_add_f32_e32 v104, 1.0, v104
	v_fmac_f32_dpp v112, v136, v128 row_shl:15 row_mask:0xf bank_mask:0xf
	v_rcp_f32_e32 v106, v104
	v_fmac_f32_dpp v112, v136, v124 row_shl:14 row_mask:0xf bank_mask:0xf
	v_fmac_f32_dpp v113, v147, v129 row_shr:1 row_mask:0xf bank_mask:0xf
	v_mul_f32_e32 v104, 0xbfb8aa3b, v103
	v_fmac_f32_dpp v113, v147, v125 row_shr:2 row_mask:0xf bank_mask:0xf
	v_mul_f32_e32 v105, 0xbfb8aa3b, v112
	v_fmac_f32_dpp v113, v137, v129 row_shl:15 row_mask:0xf bank_mask:0xf
	v_exp_f32_e32 v104, v104
	v_fmac_f32_dpp v113, v137, v125 row_shl:14 row_mask:0xf bank_mask:0xf
	v_exp_f32_e32 v105, v105
	v_mul_f32_e32 v107, 0xbfb8aa3b, v113
	v_exp_f32_e32 v107, v107
	v_add_f32_e32 v108, 1.0, v104
	v_add_f32_e32 v104, 1.0, v105
	v_rcp_f32_e32 v104, v104
	v_add_f32_e32 v105, 1.0, v107
	v_rcp_f32_e32 v105, v105
	v_rcp_f32_e32 v107, v108
	v_pk_mul_f32 v[108:109], v[132:133], v[112:113]
	v_pk_mul_f32 v[102:103], v[130:131], v[102:103]
	v_pk_mul_f32 v[104:105], v[108:109], v[104:105]
	v_pk_mul_f32 v[102:103], v[102:103], v[106:107]
	v_mov_b32_e32 v124, 0
	ds_read_b128 v[114:117], v223 offset:528
	ds_read_b128 v[118:121], v223 offset:1552
	ds_read_b128 v[126:129], v223 offset:2576
	ds_read_b128 v[106:109], v223 offset:3600
	v_mov_b32_e32 v125, 0
	s_and_saveexec_b64 s[52:53], s[36:37]
	v_add_u32_e32 v110, s77, v217
	ds_read_b128 v[122:125], v110 offset:512
	s_or_b64 exec, exec, s[52:53]
	v_mov_b32_e32 v110, v196
	v_mov_b32_e32 v111, v196
	v_pk_fma_f32 v[76:77], v[76:77], v[110:111], v[56:57]
	v_mov_b32_e32 v110, v198
	v_mov_b32_e32 v111, v198
	v_pk_fma_f32 v[130:131], v[72:73], v[110:111], v[56:57]
	s_waitcnt lgkmcnt(0)
	v_pk_fma_f32 v[110:111], v[98:99], v[126:127], v[106:107]
	s_nop 4
	v_fmac_f32_dpp v110, v98, v118 row_shr:1 row_mask:0xf bank_mask:0xf
	v_pk_fma_f32 v[66:67], v[66:67], v[200:201], v[54:55]
	v_fmac_f32_dpp v110, v98, v114 row_shr:2 row_mask:0xf bank_mask:0xf
	s_nop 0
	v_fmac_f32_dpp v110, v66, v118 row_shl:15 row_mask:0xf bank_mask:0xf
	v_pk_fma_f32 v[112:113], v[100:101], v[128:129], v[108:109]
	v_fmac_f32_dpp v110, v66, v114 row_shl:14 row_mask:0xf bank_mask:0xf
	v_fmac_f32_dpp v111, v99, v119 row_shr:1 row_mask:0xf bank_mask:0xf
	v_pk_fma_f32 v[132:133], v[70:71], v[198:199], v[54:55]
	v_fmac_f32_dpp v111, v99, v115 row_shr:2 row_mask:0xf bank_mask:0xf
	v_mov_b32_e32 v70, v200
	v_fmac_f32_dpp v111, v67, v119 row_shl:15 row_mask:0xf bank_mask:0xf
	v_mov_b32_e32 v71, v200
	v_fmac_f32_dpp v111, v67, v115 row_shl:14 row_mask:0xf bank_mask:0xf
	v_fmac_f32_dpp v112, v100, v120 row_shr:1 row_mask:0xf bank_mask:0xf
	v_pk_fma_f32 v[68:69], v[68:69], v[70:71], v[56:57]
	v_fmac_f32_dpp v112, v100, v116 row_shr:2 row_mask:0xf bank_mask:0xf
	s_nop 0
	v_fmac_f32_dpp v112, v68, v120 row_shl:15 row_mask:0xf bank_mask:0xf
	v_pk_fma_f32 v[70:71], v[66:67], v[126:127], v[106:107]
	v_fmac_f32_dpp v112, v68, v116 row_shl:14 row_mask:0xf bank_mask:0xf
	v_fmac_f32_dpp v113, v101, v121 row_shr:1 row_mask:0xf bank_mask:0xf
	s_nop 0
	v_fmac_f32_dpp v113, v101, v117 row_shr:2 row_mask:0xf bank_mask:0xf
	v_pk_fma_f32 v[72:73], v[68:69], v[128:129], v[108:109]
	v_fmac_f32_dpp v113, v69, v121 row_shl:15 row_mask:0xf bank_mask:0xf
	s_nop 0
	v_fmac_f32_dpp v113, v69, v117 row_shl:14 row_mask:0xf bank_mask:0xf
	v_pk_fma_f32 v[74:75], v[74:75], v[196:197], v[54:55]
	v_fmac_f32_dpp v70, v66, v118 row_shr:1 row_mask:0xf bank_mask:0xf
	s_nop 0
	v_fmac_f32_dpp v70, v66, v114 row_shr:2 row_mask:0xf bank_mask:0xf
	v_fma_f32 v66, v132, v126, v106
	v_fmac_f32_dpp v70, v132, v118 row_shl:15 row_mask:0xf bank_mask:0xf
	v_fma_f32 v106, v74, v126, v106
	v_fmac_f32_dpp v70, v132, v114 row_shl:14 row_mask:0xf bank_mask:0xf
	v_fmac_f32_dpp v71, v67, v119 row_shr:1 row_mask:0xf bank_mask:0xf
	s_nop 0
	v_fmac_f32_dpp v71, v67, v115 row_shr:2 row_mask:0xf bank_mask:0xf
	v_fma_f32 v67, v133, v127, v107
	v_fmac_f32_dpp v71, v133, v119 row_shl:15 row_mask:0xf bank_mask:0xf
	v_fma_f32 v107, v75, v127, v107
	v_fmac_f32_dpp v71, v133, v115 row_shl:14 row_mask:0xf bank_mask:0xf
	v_fmac_f32_dpp v72, v68, v120 row_shr:1 row_mask:0xf bank_mask:0xf
	s_nop 0
	v_fmac_f32_dpp v72, v68, v116 row_shr:2 row_mask:0xf bank_mask:0xf
	v_fma_f32 v68, v130, v128, v108
	v_fmac_f32_dpp v72, v130, v120 row_shl:15 row_mask:0xf bank_mask:0xf
	v_fma_f32 v108, v76, v128, v108
	v_fmac_f32_dpp v72, v130, v116 row_shl:14 row_mask:0xf bank_mask:0xf
	v_fmac_f32_dpp v73, v69, v121 row_shr:1 row_mask:0xf bank_mask:0xf
	s_nop 0
	v_fmac_f32_dpp v73, v69, v117 row_shr:2 row_mask:0xf bank_mask:0xf
	v_fma_f32 v69, v131, v129, v109
	v_fmac_f32_dpp v73, v131, v121 row_shl:15 row_mask:0xf bank_mask:0xf
	v_fmac_f32_e32 v109, v77, v129
	v_fmac_f32_dpp v73, v131, v117 row_shl:14 row_mask:0xf bank_mask:0xf
	s_nop 0
	v_fmac_f32_dpp v66, v132, v118 row_shr:1 row_mask:0xf bank_mask:0xf
	s_nop 0
	v_fmac_f32_dpp v66, v132, v114 row_shr:2 row_mask:0xf bank_mask:0xf
	s_nop 0
	v_fmac_f32_dpp v66, v74, v118 row_shl:15 row_mask:0xf bank_mask:0xf
	s_nop 0
	v_fmac_f32_dpp v66, v74, v114 row_shl:14 row_mask:0xf bank_mask:0xf
	v_fmac_f32_dpp v67, v133, v119 row_shr:1 row_mask:0xf bank_mask:0xf
	s_nop 0
	v_fmac_f32_dpp v67, v133, v115 row_shr:2 row_mask:0xf bank_mask:0xf
	s_nop 0
	v_fmac_f32_dpp v67, v75, v119 row_shl:15 row_mask:0xf bank_mask:0xf
	s_nop 0
	v_fmac_f32_dpp v67, v75, v115 row_shl:14 row_mask:0xf bank_mask:0xf
	v_fmac_f32_dpp v68, v130, v120 row_shr:1 row_mask:0xf bank_mask:0xf
	s_nop 0
	v_fmac_f32_dpp v68, v130, v116 row_shr:2 row_mask:0xf bank_mask:0xf
	s_nop 0
	v_fmac_f32_dpp v68, v76, v120 row_shl:15 row_mask:0xf bank_mask:0xf
	s_nop 0
	v_fmac_f32_dpp v68, v76, v116 row_shl:14 row_mask:0xf bank_mask:0xf
	v_fmac_f32_dpp v69, v131, v121 row_shr:1 row_mask:0xf bank_mask:0xf
	s_nop 0
	v_fmac_f32_dpp v69, v131, v117 row_shr:2 row_mask:0xf bank_mask:0xf
	s_nop 0
	v_fmac_f32_dpp v69, v77, v121 row_shl:15 row_mask:0xf bank_mask:0xf
	s_nop 0
	v_fmac_f32_dpp v69, v77, v117 row_shl:14 row_mask:0xf bank_mask:0xf
	s_nop 0
	v_fmac_f32_dpp v106, v74, v118 row_shr:1 row_mask:0xf bank_mask:0xf
	s_nop 0
	v_fmac_f32_dpp v106, v74, v114 row_shr:2 row_mask:0xf bank_mask:0xf
	s_nop 0
	v_fmac_f32_dpp v106, v122, v118 row_shl:15 row_mask:0xf bank_mask:0xf
	s_nop 0
	v_fmac_f32_dpp v106, v122, v114 row_shl:14 row_mask:0xf bank_mask:0xf
	v_fmac_f32_dpp v107, v75, v119 row_shr:1 row_mask:0xf bank_mask:0xf
	s_nop 0
	v_fmac_f32_dpp v107, v75, v115 row_shr:2 row_mask:0xf bank_mask:0xf
	s_nop 0
	v_fmac_f32_dpp v107, v123, v119 row_shl:15 row_mask:0xf bank_mask:0xf
	s_nop 0
	v_fmac_f32_dpp v107, v123, v115 row_shl:14 row_mask:0xf bank_mask:0xf
	v_fmac_f32_dpp v108, v76, v120 row_shr:1 row_mask:0xf bank_mask:0xf
	s_nop 0
	v_fmac_f32_dpp v108, v76, v116 row_shr:2 row_mask:0xf bank_mask:0xf
	s_nop 0
	v_fmac_f32_dpp v108, v124, v120 row_shl:15 row_mask:0xf bank_mask:0xf
	s_nop 0
	v_fmac_f32_dpp v108, v124, v116 row_shl:14 row_mask:0xf bank_mask:0xf
	v_fmac_f32_dpp v109, v77, v121 row_shr:1 row_mask:0xf bank_mask:0xf
	s_nop 0
	v_fmac_f32_dpp v109, v77, v117 row_shr:2 row_mask:0xf bank_mask:0xf
	s_nop 0
	v_fmac_f32_dpp v109, v125, v121 row_shl:15 row_mask:0xf bank_mask:0xf
	s_nop 0
	v_fmac_f32_dpp v109, v125, v117 row_shl:14 row_mask:0xf bank_mask:0xf
	s_and_saveexec_b64 s[52:53], s[38:39]
	s_cbranch_execz .LBB0_1339
	v_or_b32_e32 v74, 4, v202
	v_ashrrev_i32_e32 v75, 31, v74
	v_lshl_add_u64 v[74:75], v[74:75], 2, v[168:169]
	v_add_co_u32_e32 v74, vcc, 0x2000, v74
	s_nop 1
	v_addc_co_u32_e32 v75, vcc, 0, v75, vcc
	global_store_dwordx4 v[74:75], v[106:109], off offset:3072
.LBB0_1339:
	s_or_b64 exec, exec, s[52:53]
	s_nop 0
	ds_read_b128 v[98:101], v223 offset:16
	ds_read_b128 v[114:117], v223 offset:1040
	ds_read_b128 v[122:125], v223 offset:2064
	ds_read_b128 v[74:77], v223 offset:3088
	v_mov_b32_e32 v118, 0
	v_mov_b32_e32 v119, 0
	v_mov_b32_e32 v120, 0
	v_mov_b32_e32 v121, 0
	s_and_saveexec_b64 s[52:53], s[36:37]
	v_add_u32_e32 v118, 0, v217
	v_add_u32_e32 v118, 0x20000, v118
	ds_read_b128 v[118:121], v118
	s_or_b64 exec, exec, s[52:53]
	v_pk_fma_f32 v[128:129], v[42:43], v[196:197], v[30:31]
	v_mov_b32_e32 v42, v198
	v_mov_b32_e32 v43, v198
	v_pk_fma_f32 v[42:43], v[40:41], v[42:43], v[32:33]
	v_pk_fma_f32 v[40:41], v[34:35], v[200:201], v[30:31]
	s_waitcnt lgkmcnt(0)
	v_pk_fma_f32 v[34:35], v[82:83], v[122:123], v[74:75]
	s_nop 4
	v_fmac_f32_dpp v34, v82, v114 row_shr:1 row_mask:0xf bank_mask:0xf
	s_nop 0
	v_fmac_f32_dpp v34, v82, v98 row_shr:2 row_mask:0xf bank_mask:0xf
	v_mov_b32_e32 v126, v196
	v_fmac_f32_dpp v34, v40, v114 row_shl:15 row_mask:0xf bank_mask:0xf
	v_mov_b32_e32 v127, v196
	v_fmac_f32_dpp v34, v40, v98 row_shl:14 row_mask:0xf bank_mask:0xf
	v_fmac_f32_dpp v35, v83, v115 row_shr:1 row_mask:0xf bank_mask:0xf
	v_pk_fma_f32 v[126:127], v[44:45], v[126:127], v[32:33]
	v_pk_fma_f32 v[44:45], v[38:39], v[198:199], v[30:31]
	v_mov_b32_e32 v38, v200
	v_mov_b32_e32 v39, v200
	v_fmac_f32_dpp v35, v83, v99 row_shr:2 row_mask:0xf bank_mask:0xf
	v_pk_fma_f32 v[38:39], v[36:37], v[38:39], v[32:33]
	v_fmac_f32_dpp v35, v41, v115 row_shl:15 row_mask:0xf bank_mask:0xf
	v_pk_fma_f32 v[36:37], v[84:85], v[124:125], v[76:77]
	v_fmac_f32_dpp v35, v41, v99 row_shl:14 row_mask:0xf bank_mask:0xf
	v_fmac_f32_dpp v36, v84, v116 row_shr:1 row_mask:0xf bank_mask:0xf
	s_nop 0
	v_fmac_f32_dpp v36, v84, v100 row_shr:2 row_mask:0xf bank_mask:0xf
	v_mul_f32_e32 v82, 0xbfb8aa3b, v34
	v_fmac_f32_dpp v36, v38, v116 row_shl:15 row_mask:0xf bank_mask:0xf
	v_mul_f32_e32 v83, 0xbfb8aa3b, v35
	v_fmac_f32_dpp v36, v38, v100 row_shl:14 row_mask:0xf bank_mask:0xf
	v_fmac_f32_dpp v37, v85, v117 row_shr:1 row_mask:0xf bank_mask:0xf
	v_exp_f32_e32 v82, v82
	v_fmac_f32_dpp v37, v85, v101 row_shr:2 row_mask:0xf bank_mask:0xf
	v_mul_f32_e32 v84, 0xbfb8aa3b, v36
	v_fmac_f32_dpp v37, v39, v117 row_shl:15 row_mask:0xf bank_mask:0xf
	v_exp_f32_e32 v83, v83
	v_fmac_f32_dpp v37, v39, v101 row_shl:14 row_mask:0xf bank_mask:0xf
	v_exp_f32_e32 v84, v84
	v_mul_f32_e32 v85, 0xbfb8aa3b, v37
	v_exp_f32_e32 v85, v85
	v_add_f32_e32 v82, 1.0, v82
	v_add_f32_e32 v83, 1.0, v83
	v_add_f32_e32 v84, 1.0, v84
	v_add_f32_e32 v85, 1.0, v85
	v_rcp_f32_e32 v82, v82
	v_rcp_f32_e32 v84, v84
	v_rcp_f32_e32 v85, v85
	v_rcp_f32_e32 v83, v83
	v_pk_mul_f32 v[36:37], v[112:113], v[36:37]
	v_pk_mul_f32 v[34:35], v[110:111], v[34:35]
	v_pk_mul_f32 v[36:37], v[36:37], v[84:85]
	v_pk_mul_f32 v[34:35], v[34:35], v[82:83]
	v_pk_fma_f32 v[82:83], v[40:41], v[122:123], v[74:75]
	v_fmac_f32_dpp v82, v40, v114 row_shr:1 row_mask:0xf bank_mask:0xf
	s_nop 0
	v_fmac_f32_dpp v82, v40, v98 row_shr:2 row_mask:0xf bank_mask:0xf
	v_fma_f32 v40, v38, v124, v76
	v_fmac_f32_dpp v82, v44, v114 row_shl:15 row_mask:0xf bank_mask:0xf
	s_nop 0
	v_fmac_f32_dpp v82, v44, v98 row_shl:14 row_mask:0xf bank_mask:0xf
	v_fmac_f32_dpp v83, v41, v115 row_shr:1 row_mask:0xf bank_mask:0xf
	s_nop 0
	v_fmac_f32_dpp v83, v41, v99 row_shr:2 row_mask:0xf bank_mask:0xf
	v_fma_f32 v41, v39, v125, v77
	v_fmac_f32_dpp v83, v45, v115 row_shl:15 row_mask:0xf bank_mask:0xf
	s_nop 0
	v_fmac_f32_dpp v83, v45, v99 row_shl:14 row_mask:0xf bank_mask:0xf
	v_fmac_f32_dpp v40, v38, v116 row_shr:1 row_mask:0xf bank_mask:0xf
	s_nop 0
	v_fmac_f32_dpp v40, v38, v100 row_shr:2 row_mask:0xf bank_mask:0xf
	v_mul_f32_e32 v38, 0xbfb8aa3b, v82
	v_fmac_f32_dpp v40, v42, v116 row_shl:15 row_mask:0xf bank_mask:0xf
	v_exp_f32_e32 v38, v38
	v_fmac_f32_dpp v40, v42, v100 row_shl:14 row_mask:0xf bank_mask:0xf
	v_fmac_f32_dpp v41, v39, v117 row_shr:1 row_mask:0xf bank_mask:0xf
	v_pk_mul_f32 v[70:71], v[70:71], v[82:83]
	v_fmac_f32_dpp v41, v39, v101 row_shr:2 row_mask:0xf bank_mask:0xf
	v_mul_f32_e32 v39, 0xbfb8aa3b, v83
	v_fmac_f32_dpp v41, v43, v117 row_shl:15 row_mask:0xf bank_mask:0xf
	v_mul_f32_e32 v84, 0xbfb8aa3b, v40
	v_fmac_f32_dpp v41, v43, v101 row_shl:14 row_mask:0xf bank_mask:0xf
	v_exp_f32_e32 v39, v39
	v_mul_f32_e32 v85, 0xbfb8aa3b, v41
	v_exp_f32_e32 v84, v84
	v_exp_f32_e32 v85, v85
	v_add_f32_e32 v38, 1.0, v38
	v_add_f32_e32 v39, 1.0, v39
	v_add_f32_e32 v84, 1.0, v84
	v_add_f32_e32 v85, 1.0, v85
	v_rcp_f32_e32 v38, v38
	v_rcp_f32_e32 v84, v84
	v_rcp_f32_e32 v85, v85
	v_rcp_f32_e32 v39, v39
	v_pk_mul_f32 v[40:41], v[72:73], v[40:41]
	v_pk_mul_f32 v[38:39], v[70:71], v[38:39]
	v_pk_mul_f32 v[40:41], v[40:41], v[84:85]
	v_pk_fma_f32 v[70:71], v[44:45], v[122:123], v[74:75]
	v_fmac_f32_dpp v70, v44, v114 row_shr:1 row_mask:0xf bank_mask:0xf
	s_nop 0
	v_fmac_f32_dpp v70, v44, v98 row_shr:2 row_mask:0xf bank_mask:0xf
	v_fma_f32 v44, v42, v124, v76
	v_fmac_f32_dpp v70, v128, v114 row_shl:15 row_mask:0xf bank_mask:0xf
	v_pk_fma_f32 v[74:75], v[128:129], v[122:123], v[74:75]
	v_fmac_f32_dpp v70, v128, v98 row_shl:14 row_mask:0xf bank_mask:0xf
	v_fmac_f32_dpp v71, v45, v115 row_shr:1 row_mask:0xf bank_mask:0xf
	s_nop 0
	v_fmac_f32_dpp v71, v45, v99 row_shr:2 row_mask:0xf bank_mask:0xf
	v_fma_f32 v45, v43, v125, v77
	v_fmac_f32_dpp v71, v129, v115 row_shl:15 row_mask:0xf bank_mask:0xf
	v_pk_fma_f32 v[76:77], v[126:127], v[124:125], v[76:77]
	v_fmac_f32_dpp v71, v129, v99 row_shl:14 row_mask:0xf bank_mask:0xf
	v_fmac_f32_dpp v44, v42, v116 row_shr:1 row_mask:0xf bank_mask:0xf
	s_nop 0
	v_fmac_f32_dpp v44, v42, v100 row_shr:2 row_mask:0xf bank_mask:0xf
	v_mul_f32_e32 v42, 0xbfb8aa3b, v70
	v_fmac_f32_dpp v44, v126, v116 row_shl:15 row_mask:0xf bank_mask:0xf
	v_exp_f32_e32 v42, v42
	v_fmac_f32_dpp v44, v126, v100 row_shl:14 row_mask:0xf bank_mask:0xf
	v_fmac_f32_dpp v45, v43, v117 row_shr:1 row_mask:0xf bank_mask:0xf
	v_pk_mul_f32 v[66:67], v[66:67], v[70:71]
	v_fmac_f32_dpp v45, v43, v101 row_shr:2 row_mask:0xf bank_mask:0xf
	v_mul_f32_e32 v43, 0xbfb8aa3b, v71
	v_fmac_f32_dpp v45, v127, v117 row_shl:15 row_mask:0xf bank_mask:0xf
	v_mul_f32_e32 v72, 0xbfb8aa3b, v44
	v_fmac_f32_dpp v45, v127, v101 row_shl:14 row_mask:0xf bank_mask:0xf
	v_exp_f32_e32 v43, v43
	v_mul_f32_e32 v73, 0xbfb8aa3b, v45
	v_exp_f32_e32 v72, v72
	v_exp_f32_e32 v73, v73
	v_add_f32_e32 v42, 1.0, v42
	v_add_f32_e32 v43, 1.0, v43
	v_add_f32_e32 v72, 1.0, v72
	v_add_f32_e32 v73, 1.0, v73
	v_rcp_f32_e32 v42, v42
	v_rcp_f32_e32 v72, v72
	v_rcp_f32_e32 v73, v73
	v_rcp_f32_e32 v43, v43
	v_pk_mul_f32 v[44:45], v[68:69], v[44:45]
	v_pk_mul_f32 v[42:43], v[66:67], v[42:43]
	v_pk_mul_f32 v[44:45], v[44:45], v[72:73]
	s_nop 0
	v_fmac_f32_dpp v74, v128, v114 row_shr:1 row_mask:0xf bank_mask:0xf
	s_nop 0
	v_fmac_f32_dpp v74, v128, v98 row_shr:2 row_mask:0xf bank_mask:0xf
	s_nop 0
	v_fmac_f32_dpp v74, v118, v114 row_shl:15 row_mask:0xf bank_mask:0xf
	s_nop 0
	v_fmac_f32_dpp v74, v118, v98 row_shl:14 row_mask:0xf bank_mask:0xf
	v_fmac_f32_dpp v75, v129, v115 row_shr:1 row_mask:0xf bank_mask:0xf
	s_nop 0
	v_fmac_f32_dpp v75, v129, v99 row_shr:2 row_mask:0xf bank_mask:0xf
	s_nop 0
	v_fmac_f32_dpp v75, v119, v115 row_shl:15 row_mask:0xf bank_mask:0xf
	s_nop 0
	v_fmac_f32_dpp v75, v119, v99 row_shl:14 row_mask:0xf bank_mask:0xf
	v_fmac_f32_dpp v76, v126, v116 row_shr:1 row_mask:0xf bank_mask:0xf
	s_nop 0
	v_fmac_f32_dpp v76, v126, v100 row_shr:2 row_mask:0xf bank_mask:0xf
	s_nop 0
	v_fmac_f32_dpp v76, v120, v116 row_shl:15 row_mask:0xf bank_mask:0xf
	s_nop 0
	v_fmac_f32_dpp v76, v120, v100 row_shl:14 row_mask:0xf bank_mask:0xf
	v_fmac_f32_dpp v77, v127, v117 row_shr:1 row_mask:0xf bank_mask:0xf
	s_nop 0
	v_fmac_f32_dpp v77, v127, v101 row_shr:2 row_mask:0xf bank_mask:0xf
	s_nop 0
	v_fmac_f32_dpp v77, v121, v117 row_shl:15 row_mask:0xf bank_mask:0xf
	s_nop 0
	v_fmac_f32_dpp v77, v121, v101 row_shl:14 row_mask:0xf bank_mask:0xf
	s_and_saveexec_b64 s[52:53], s[38:39]
	s_cbranch_execz .LBB0_1343
	global_store_dwordx4 v[166:167], v[74:77], off offset:16
.LBB0_1343:
	s_or_b64 exec, exec, s[52:53]
	v_mul_f32_e32 v66, 0xbfb8aa3b, v74
	v_mul_f32_e32 v67, 0xbfb8aa3b, v75
	v_mul_f32_e32 v68, 0xbfb8aa3b, v76
	v_mul_f32_e32 v69, 0xbfb8aa3b, v77
	v_exp_f32_e32 v66, v66
	v_exp_f32_e32 v67, v67
	v_exp_f32_e32 v68, v68
	v_exp_f32_e32 v69, v69
	v_add_f32_e32 v66, 1.0, v66
	v_add_f32_e32 v67, 1.0, v67
	v_add_f32_e32 v68, 1.0, v68
	v_add_f32_e32 v69, 1.0, v69
	v_rcp_f32_e32 v66, v66
	v_rcp_f32_e32 v68, v68
	v_rcp_f32_e32 v69, v69
	v_rcp_f32_e32 v67, v67
	v_pk_mul_f32 v[70:71], v[108:109], v[76:77]
	v_pk_mul_f32 v[72:73], v[106:107], v[74:75]
	v_pk_mul_f32 v[68:69], v[70:71], v[68:69]
	v_pk_mul_f32 v[66:67], v[72:73], v[66:67]
	v_mov_b32_e32 v74, 0
	ds_read_b128 v[98:101], v223 offset:528
	ds_read_b128 v[106:109], v223 offset:1552
	ds_read_b128 v[114:117], v223 offset:2576
	ds_read_b128 v[70:73], v223 offset:3600
	v_mov_b32_e32 v110, 0
	v_mov_b32_e32 v111, 0
	v_mov_b32_e32 v112, 0
	v_mov_b32_e32 v113, 0
	s_and_saveexec_b64 s[52:53], s[0:1]
	v_add_u32_e32 v75, s77, v218
	ds_read_b128 v[110:113], v75 offset:512
	s_or_b64 exec, exec, s[52:53]
	s_waitcnt lgkmcnt(0)
	v_pk_fma_f32 v[82:83], v[58:59], v[114:115], v[70:71]
	s_nop 4
	v_fmac_f32_dpp v82, v58, v106 row_shr:1 row_mask:0xf bank_mask:0xf
	v_pk_fma_f32 v[14:15], v[14:15], v[160:161], v[54:55]
	v_fmac_f32_dpp v82, v58, v98 row_shr:2 row_mask:0xf bank_mask:0xf
	s_nop 0
	v_fmac_f32_dpp v82, v14, v106 row_shl:15 row_mask:0xf bank_mask:0xf
	v_pk_fma_f32 v[84:85], v[60:61], v[116:117], v[72:73]
	v_fmac_f32_dpp v82, v14, v98 row_shl:14 row_mask:0xf bank_mask:0xf
	v_fmac_f32_dpp v83, v59, v107 row_shr:1 row_mask:0xf bank_mask:0xf
	v_mov_b32_e32 v122, v160
	v_fmac_f32_dpp v83, v59, v99 row_shr:2 row_mask:0xf bank_mask:0xf
	v_mov_b32_e32 v123, v160
	v_fmac_f32_dpp v83, v15, v107 row_shl:15 row_mask:0xf bank_mask:0xf
	v_pk_fma_f32 v[16:17], v[16:17], v[122:123], v[56:57]
	v_fmac_f32_dpp v83, v15, v99 row_shl:14 row_mask:0xf bank_mask:0xf
	v_fmac_f32_dpp v84, v60, v108 row_shr:1 row_mask:0xf bank_mask:0xf
	s_nop 0
	v_fmac_f32_dpp v84, v60, v100 row_shr:2 row_mask:0xf bank_mask:0xf
	v_pk_fma_f32 v[124:125], v[18:19], v[162:163], v[54:55]
	v_fmac_f32_dpp v84, v16, v108 row_shl:15 row_mask:0xf bank_mask:0xf
	v_pk_fma_f32 v[18:19], v[14:15], v[114:115], v[70:71]
	v_fmac_f32_dpp v84, v16, v100 row_shl:14 row_mask:0xf bank_mask:0xf
	v_fmac_f32_dpp v85, v61, v109 row_shr:1 row_mask:0xf bank_mask:0xf
	s_nop 0
	v_fmac_f32_dpp v85, v61, v101 row_shr:2 row_mask:0xf bank_mask:0xf
	v_mov_b32_e32 v120, v162
	v_fmac_f32_dpp v85, v17, v109 row_shl:15 row_mask:0xf bank_mask:0xf
	v_mov_b32_e32 v121, v162
	v_fmac_f32_dpp v85, v17, v101 row_shl:14 row_mask:0xf bank_mask:0xf
	v_pk_fma_f32 v[76:77], v[20:21], v[120:121], v[56:57]
	v_fmac_f32_dpp v18, v14, v106 row_shr:1 row_mask:0xf bank_mask:0xf
	v_pk_fma_f32 v[20:21], v[16:17], v[116:117], v[72:73]
	v_fmac_f32_dpp v18, v14, v98 row_shr:2 row_mask:0xf bank_mask:0xf
	s_nop 0
	v_fmac_f32_dpp v18, v124, v106 row_shl:15 row_mask:0xf bank_mask:0xf
	v_fma_f32 v14, v124, v114, v70
	v_fmac_f32_dpp v18, v124, v98 row_shl:14 row_mask:0xf bank_mask:0xf
	v_fmac_f32_dpp v19, v15, v107 row_shr:1 row_mask:0xf bank_mask:0xf
	v_pk_fma_f32 v[22:23], v[22:23], v[158:159], v[54:55]
	v_fmac_f32_dpp v19, v15, v99 row_shr:2 row_mask:0xf bank_mask:0xf
	v_fma_f32 v15, v125, v115, v71
	v_fmac_f32_dpp v19, v125, v107 row_shl:15 row_mask:0xf bank_mask:0xf
	v_mov_b32_e32 v118, v158
	v_fmac_f32_dpp v19, v125, v99 row_shl:14 row_mask:0xf bank_mask:0xf
	v_fmac_f32_dpp v20, v16, v108 row_shr:1 row_mask:0xf bank_mask:0xf
	v_mov_b32_e32 v119, v158
	v_fmac_f32_dpp v20, v16, v100 row_shr:2 row_mask:0xf bank_mask:0xf
	v_fma_f32 v16, v76, v116, v72
	v_fmac_f32_dpp v20, v76, v108 row_shl:15 row_mask:0xf bank_mask:0xf
	v_pk_fma_f32 v[24:25], v[24:25], v[118:119], v[56:57]
	v_fmac_f32_dpp v20, v76, v100 row_shl:14 row_mask:0xf bank_mask:0xf
	v_fmac_f32_dpp v21, v17, v109 row_shr:1 row_mask:0xf bank_mask:0xf
	v_pk_fma_f32 v[70:71], v[22:23], v[114:115], v[70:71]
	v_fmac_f32_dpp v21, v17, v101 row_shr:2 row_mask:0xf bank_mask:0xf
	v_fma_f32 v17, v77, v117, v73
	v_fmac_f32_dpp v21, v77, v109 row_shl:15 row_mask:0xf bank_mask:0xf
	s_nop 0
	v_fmac_f32_dpp v21, v77, v101 row_shl:14 row_mask:0xf bank_mask:0xf
	v_pk_fma_f32 v[72:73], v[24:25], v[116:117], v[72:73]
	v_fmac_f32_dpp v14, v124, v106 row_shr:1 row_mask:0xf bank_mask:0xf
	s_nop 0
	v_fmac_f32_dpp v14, v124, v98 row_shr:2 row_mask:0xf bank_mask:0xf
	v_mov_b32_e32 v75, 0
	v_fmac_f32_dpp v14, v22, v106 row_shl:15 row_mask:0xf bank_mask:0xf
	s_nop 0
	v_fmac_f32_dpp v14, v22, v98 row_shl:14 row_mask:0xf bank_mask:0xf
	v_fmac_f32_dpp v15, v125, v107 row_shr:1 row_mask:0xf bank_mask:0xf
	s_nop 0
	v_fmac_f32_dpp v15, v125, v99 row_shr:2 row_mask:0xf bank_mask:0xf
	s_nop 0
	v_fmac_f32_dpp v15, v23, v107 row_shl:15 row_mask:0xf bank_mask:0xf
	s_nop 0
	v_fmac_f32_dpp v15, v23, v99 row_shl:14 row_mask:0xf bank_mask:0xf
	v_fmac_f32_dpp v16, v76, v108 row_shr:1 row_mask:0xf bank_mask:0xf
	s_nop 0
	v_fmac_f32_dpp v16, v76, v100 row_shr:2 row_mask:0xf bank_mask:0xf
	v_mov_b32_e32 v76, 0
	v_fmac_f32_dpp v16, v24, v108 row_shl:15 row_mask:0xf bank_mask:0xf
	s_nop 0
	v_fmac_f32_dpp v16, v24, v100 row_shl:14 row_mask:0xf bank_mask:0xf
	v_fmac_f32_dpp v17, v77, v109 row_shr:1 row_mask:0xf bank_mask:0xf
	s_nop 0
	v_fmac_f32_dpp v17, v77, v101 row_shr:2 row_mask:0xf bank_mask:0xf
	v_mov_b32_e32 v77, 0
	v_fmac_f32_dpp v17, v25, v109 row_shl:15 row_mask:0xf bank_mask:0xf
	s_nop 0
	v_fmac_f32_dpp v17, v25, v101 row_shl:14 row_mask:0xf bank_mask:0xf
	s_nop 0
	v_fmac_f32_dpp v70, v22, v106 row_shr:1 row_mask:0xf bank_mask:0xf
	s_nop 0
	v_fmac_f32_dpp v70, v22, v98 row_shr:2 row_mask:0xf bank_mask:0xf
	s_nop 0
	v_fmac_f32_dpp v70, v110, v106 row_shl:15 row_mask:0xf bank_mask:0xf
	s_nop 0
	v_fmac_f32_dpp v70, v110, v98 row_shl:14 row_mask:0xf bank_mask:0xf
	v_fmac_f32_dpp v71, v23, v107 row_shr:1 row_mask:0xf bank_mask:0xf
	s_nop 0
	v_fmac_f32_dpp v71, v23, v99 row_shr:2 row_mask:0xf bank_mask:0xf
	s_nop 0
	v_fmac_f32_dpp v71, v111, v107 row_shl:15 row_mask:0xf bank_mask:0xf
	s_nop 0
	v_fmac_f32_dpp v71, v111, v99 row_shl:14 row_mask:0xf bank_mask:0xf
	v_fmac_f32_dpp v72, v24, v108 row_shr:1 row_mask:0xf bank_mask:0xf
	s_nop 0
	v_fmac_f32_dpp v72, v24, v100 row_shr:2 row_mask:0xf bank_mask:0xf
	s_nop 0
	v_fmac_f32_dpp v72, v112, v108 row_shl:15 row_mask:0xf bank_mask:0xf
	s_nop 0
	v_fmac_f32_dpp v72, v112, v100 row_shl:14 row_mask:0xf bank_mask:0xf
	v_fmac_f32_dpp v73, v25, v109 row_shr:1 row_mask:0xf bank_mask:0xf
	s_nop 0
	v_fmac_f32_dpp v73, v25, v101 row_shr:2 row_mask:0xf bank_mask:0xf
	s_nop 0
	v_fmac_f32_dpp v73, v113, v109 row_shl:15 row_mask:0xf bank_mask:0xf
	s_nop 0
	v_fmac_f32_dpp v73, v113, v101 row_shl:14 row_mask:0xf bank_mask:0xf
	s_nop 0
	ds_read_b128 v[54:57], v223 offset:16
	ds_read_b128 v[58:61], v223 offset:1040
	ds_read_b128 v[98:101], v223 offset:2064
	ds_read_b128 v[22:25], v223 offset:3088
	s_and_saveexec_b64 s[52:53], s[0:1]
	v_add_u32_e32 v74, 0, v218
	v_add_u32_e32 v74, 0x20000, v74
	ds_read_b128 v[74:77], v74
	s_or_b64 exec, exec, s[52:53]
	v_pk_fma_f32 v[106:107], v[8:9], v[120:121], v[32:33]
	v_pk_fma_f32 v[8:9], v[2:3], v[160:161], v[30:31]
	s_waitcnt lgkmcnt(0)
	v_pk_fma_f32 v[2:3], v[26:27], v[98:99], v[22:23]
	s_nop 4
	v_fmac_f32_dpp v2, v26, v58 row_shr:1 row_mask:0xf bank_mask:0xf
	s_nop 0
	v_fmac_f32_dpp v2, v26, v54 row_shr:2 row_mask:0xf bank_mask:0xf
	v_pk_fma_f32 v[108:109], v[6:7], v[162:163], v[30:31]
	v_fmac_f32_dpp v2, v8, v58 row_shl:15 row_mask:0xf bank_mask:0xf
	v_pk_fma_f32 v[6:7], v[4:5], v[122:123], v[32:33]
	v_fmac_f32_dpp v2, v8, v54 row_shl:14 row_mask:0xf bank_mask:0xf
	v_fmac_f32_dpp v3, v27, v59 row_shr:1 row_mask:0xf bank_mask:0xf
	v_pk_fma_f32 v[4:5], v[28:29], v[100:101], v[24:25]
	v_fmac_f32_dpp v3, v27, v55 row_shr:2 row_mask:0xf bank_mask:0xf
	s_nop 0
	v_fmac_f32_dpp v3, v9, v59 row_shl:15 row_mask:0xf bank_mask:0xf
	v_mul_f32_e32 v26, 0xbfb8aa3b, v2
	v_fmac_f32_dpp v3, v9, v55 row_shl:14 row_mask:0xf bank_mask:0xf
	v_fmac_f32_dpp v4, v28, v60 row_shr:1 row_mask:0xf bank_mask:0xf
	v_exp_f32_e32 v26, v26
	v_fmac_f32_dpp v4, v28, v56 row_shr:2 row_mask:0xf bank_mask:0xf
	v_mul_f32_e32 v27, 0xbfb8aa3b, v3
	v_fmac_f32_dpp v4, v6, v60 row_shl:15 row_mask:0xf bank_mask:0xf
	v_exp_f32_e32 v27, v27
	v_fmac_f32_dpp v4, v6, v56 row_shl:14 row_mask:0xf bank_mask:0xf
	v_fmac_f32_dpp v5, v29, v61 row_shr:1 row_mask:0xf bank_mask:0xf
	v_add_f32_e32 v26, 1.0, v26
	v_fmac_f32_dpp v5, v29, v57 row_shr:2 row_mask:0xf bank_mask:0xf
	v_mul_f32_e32 v28, 0xbfb8aa3b, v4
	v_fmac_f32_dpp v5, v7, v61 row_shl:15 row_mask:0xf bank_mask:0xf
	v_exp_f32_e32 v28, v28
	v_fmac_f32_dpp v5, v7, v57 row_shl:14 row_mask:0xf bank_mask:0xf
	v_add_f32_e32 v27, 1.0, v27
	v_mul_f32_e32 v29, 0xbfb8aa3b, v5
	v_exp_f32_e32 v29, v29
	v_add_f32_e32 v28, 1.0, v28
	v_rcp_f32_e32 v26, v26
	v_rcp_f32_e32 v28, v28
	v_add_f32_e32 v29, 1.0, v29
	v_rcp_f32_e32 v29, v29
	v_rcp_f32_e32 v27, v27
	v_pk_mul_f32 v[4:5], v[84:85], v[4:5]
	v_pk_mul_f32 v[2:3], v[82:83], v[2:3]
	v_pk_mul_f32 v[4:5], v[4:5], v[28:29]
	v_pk_mul_f32 v[2:3], v[2:3], v[26:27]
	v_pk_fma_f32 v[26:27], v[8:9], v[98:99], v[22:23]
	v_fmac_f32_dpp v26, v8, v58 row_shr:1 row_mask:0xf bank_mask:0xf
	s_nop 0
	v_fmac_f32_dpp v26, v8, v54 row_shr:2 row_mask:0xf bank_mask:0xf
	v_fma_f32 v8, v6, v100, v24
	v_fmac_f32_dpp v26, v108, v58 row_shl:15 row_mask:0xf bank_mask:0xf
	v_pk_fma_f32 v[10:11], v[10:11], v[158:159], v[30:31]
	v_fmac_f32_dpp v26, v108, v54 row_shl:14 row_mask:0xf bank_mask:0xf
	v_fmac_f32_dpp v27, v9, v59 row_shr:1 row_mask:0xf bank_mask:0xf
	v_pk_fma_f32 v[12:13], v[12:13], v[118:119], v[32:33]
	v_fmac_f32_dpp v27, v9, v55 row_shr:2 row_mask:0xf bank_mask:0xf
	v_fma_f32 v9, v7, v101, v25
	v_fmac_f32_dpp v27, v109, v59 row_shl:15 row_mask:0xf bank_mask:0xf
	s_ashr_i32 s51, s50, 31
	v_fmac_f32_dpp v27, v109, v55 row_shl:14 row_mask:0xf bank_mask:0xf
	v_fmac_f32_dpp v8, v6, v60 row_shr:1 row_mask:0xf bank_mask:0xf
	s_andn2_b64 vcc, exec, s[4:5]
	v_fmac_f32_dpp v8, v6, v56 row_shr:2 row_mask:0xf bank_mask:0xf
	v_mul_f32_e32 v6, 0xbfb8aa3b, v26
	v_fmac_f32_dpp v8, v106, v60 row_shl:15 row_mask:0xf bank_mask:0xf
	v_exp_f32_e32 v6, v6
	v_fmac_f32_dpp v8, v106, v56 row_shl:14 row_mask:0xf bank_mask:0xf
	v_fmac_f32_dpp v9, v7, v61 row_shr:1 row_mask:0xf bank_mask:0xf
	v_pk_mul_f32 v[18:19], v[18:19], v[26:27]
	v_fmac_f32_dpp v9, v7, v57 row_shr:2 row_mask:0xf bank_mask:0xf
	v_mul_f32_e32 v7, 0xbfb8aa3b, v27
	v_fmac_f32_dpp v9, v107, v61 row_shl:15 row_mask:0xf bank_mask:0xf
	v_mul_f32_e32 v28, 0xbfb8aa3b, v8
	v_fmac_f32_dpp v9, v107, v57 row_shl:14 row_mask:0xf bank_mask:0xf
	v_exp_f32_e32 v7, v7
	v_mul_f32_e32 v29, 0xbfb8aa3b, v9
	v_exp_f32_e32 v28, v28
	v_exp_f32_e32 v29, v29
	v_add_f32_e32 v6, 1.0, v6
	v_add_f32_e32 v7, 1.0, v7
	v_add_f32_e32 v28, 1.0, v28
	v_add_f32_e32 v29, 1.0, v29
	v_rcp_f32_e32 v6, v6
	v_rcp_f32_e32 v28, v28
	v_rcp_f32_e32 v29, v29
	v_rcp_f32_e32 v7, v7
	v_pk_mul_f32 v[8:9], v[20:21], v[8:9]
	v_pk_fma_f32 v[20:21], v[106:107], v[100:101], v[24:25]
	v_pk_mul_f32 v[8:9], v[8:9], v[28:29]
	v_pk_mul_f32 v[6:7], v[18:19], v[6:7]
	v_pk_fma_f32 v[18:19], v[108:109], v[98:99], v[22:23]
	v_fmac_f32_dpp v18, v108, v58 row_shr:1 row_mask:0xf bank_mask:0xf
	s_nop 0
	v_fmac_f32_dpp v18, v108, v54 row_shr:2 row_mask:0xf bank_mask:0xf
	s_nop 0
	v_fmac_f32_dpp v18, v10, v58 row_shl:15 row_mask:0xf bank_mask:0xf
	v_pk_fma_f32 v[24:25], v[12:13], v[100:101], v[24:25]
	v_fmac_f32_dpp v18, v10, v54 row_shl:14 row_mask:0xf bank_mask:0xf
	v_fmac_f32_dpp v19, v109, v59 row_shr:1 row_mask:0xf bank_mask:0xf
	s_nop 0
	v_fmac_f32_dpp v19, v109, v55 row_shr:2 row_mask:0xf bank_mask:0xf
	v_mul_f32_e32 v26, 0xbfb8aa3b, v18
	v_fmac_f32_dpp v19, v11, v59 row_shl:15 row_mask:0xf bank_mask:0xf
	v_exp_f32_e32 v26, v26
	v_fmac_f32_dpp v19, v11, v55 row_shl:14 row_mask:0xf bank_mask:0xf
	v_fmac_f32_dpp v20, v106, v60 row_shr:1 row_mask:0xf bank_mask:0xf
	s_mov_b64 s[4:5], -1
	v_fmac_f32_dpp v20, v106, v56 row_shr:2 row_mask:0xf bank_mask:0xf
	v_mul_f32_e32 v27, 0xbfb8aa3b, v19
	v_fmac_f32_dpp v20, v12, v60 row_shl:15 row_mask:0xf bank_mask:0xf
	v_exp_f32_e32 v27, v27
	v_fmac_f32_dpp v20, v12, v56 row_shl:14 row_mask:0xf bank_mask:0xf
	v_fmac_f32_dpp v21, v107, v61 row_shr:1 row_mask:0xf bank_mask:0xf
	v_add_f32_e32 v26, 1.0, v26
	v_fmac_f32_dpp v21, v107, v57 row_shr:2 row_mask:0xf bank_mask:0xf
	v_mul_f32_e32 v28, 0xbfb8aa3b, v20
	v_fmac_f32_dpp v21, v13, v61 row_shl:15 row_mask:0xf bank_mask:0xf
	v_exp_f32_e32 v28, v28
	v_fmac_f32_dpp v21, v13, v57 row_shl:14 row_mask:0xf bank_mask:0xf
	v_add_f32_e32 v27, 1.0, v27
	v_mul_f32_e32 v29, 0xbfb8aa3b, v21
	v_exp_f32_e32 v29, v29
	v_add_f32_e32 v28, 1.0, v28
	v_rcp_f32_e32 v26, v26
	v_rcp_f32_e32 v28, v28
	v_add_f32_e32 v29, 1.0, v29
	v_rcp_f32_e32 v29, v29
	v_rcp_f32_e32 v27, v27
	v_pk_mul_f32 v[16:17], v[16:17], v[20:21]
	v_pk_mul_f32 v[14:15], v[14:15], v[18:19]
	v_pk_mul_f32 v[16:17], v[16:17], v[28:29]
	v_pk_mul_f32 v[14:15], v[14:15], v[26:27]
	v_pk_fma_f32 v[18:19], v[10:11], v[98:99], v[22:23]
	v_fmac_f32_dpp v18, v10, v58 row_shr:1 row_mask:0xf bank_mask:0xf
	s_nop 0
	v_fmac_f32_dpp v18, v10, v54 row_shr:2 row_mask:0xf bank_mask:0xf
	v_lshl_add_u32 v26, s30, 8, v173
	v_fmac_f32_dpp v18, v74, v58 row_shl:15 row_mask:0xf bank_mask:0xf
	v_mov_b64_e32 v[22:23], s[66:67]
	v_fmac_f32_dpp v18, v74, v54 row_shl:14 row_mask:0xf bank_mask:0xf
	v_fmac_f32_dpp v19, v11, v59 row_shr:1 row_mask:0xf bank_mask:0xf
	s_nop 0
	v_fmac_f32_dpp v19, v11, v55 row_shr:2 row_mask:0xf bank_mask:0xf
	v_mul_f32_e32 v10, 0xbfb8aa3b, v18
	v_fmac_f32_dpp v19, v75, v59 row_shl:15 row_mask:0xf bank_mask:0xf
	v_exp_f32_e32 v10, v10
	v_fmac_f32_dpp v19, v75, v55 row_shl:14 row_mask:0xf bank_mask:0xf
	v_fmac_f32_dpp v24, v12, v60 row_shr:1 row_mask:0xf bank_mask:0xf
	s_nop 0
	v_fmac_f32_dpp v24, v12, v56 row_shr:2 row_mask:0xf bank_mask:0xf
	v_mul_f32_e32 v11, 0xbfb8aa3b, v19
	v_fmac_f32_dpp v24, v76, v60 row_shl:15 row_mask:0xf bank_mask:0xf
	v_exp_f32_e32 v11, v11
	v_fmac_f32_dpp v24, v76, v56 row_shl:14 row_mask:0xf bank_mask:0xf
	v_fmac_f32_dpp v25, v13, v61 row_shr:1 row_mask:0xf bank_mask:0xf
	v_add_f32_e32 v10, 1.0, v10
	v_fmac_f32_dpp v25, v13, v57 row_shr:2 row_mask:0xf bank_mask:0xf
	v_mul_f32_e32 v12, 0xbfb8aa3b, v24
	v_fmac_f32_dpp v25, v77, v61 row_shl:15 row_mask:0xf bank_mask:0xf
	v_exp_f32_e32 v12, v12
	v_fmac_f32_dpp v25, v77, v57 row_shl:14 row_mask:0xf bank_mask:0xf
	v_add_f32_e32 v11, 1.0, v11
	v_mul_f32_e32 v13, 0xbfb8aa3b, v25
	v_exp_f32_e32 v13, v13
	v_add_f32_e32 v12, 1.0, v12
	v_rcp_f32_e32 v10, v10
	v_rcp_f32_e32 v12, v12
	v_add_f32_e32 v13, 1.0, v13
	v_rcp_f32_e32 v13, v13
	v_rcp_f32_e32 v11, v11
	v_pk_mul_f32 v[20:21], v[72:73], v[24:25]
	v_mad_i64_i32 v[24:25], s[30:31], v26, s81, v[22:23]
	s_lshl_b64 s[30:31], s[50:51], 1
	v_pk_mul_f32 v[18:19], v[70:71], v[18:19]
	v_lshl_add_u64 v[24:25], v[24:25], 0, s[30:31]
	v_pk_mul_f32 v[12:13], v[20:21], v[12:13]
	v_pk_mul_f32 v[10:11], v[18:19], v[10:11]
	v_lshl_add_u64 v[24:25], v[24:25], 0, v[184:185]
	v_cvt_pk_bf16_f32 v18, v78, v79
	v_cvt_pk_bf16_f32 v19, v80, v81
	v_cvt_pk_bf16_f32 v20, v66, v67
	v_cvt_pk_bf16_f32 v21, v68, v69
	global_store_dwordx4 v[24:25], v[18:21], off
	v_or_b32_e32 v24, 16, v26
	v_mad_i64_i32 v[24:25], s[50:51], v24, s81, v[22:23]
	v_lshl_add_u64 v[24:25], v[24:25], 0, s[30:31]
	v_lshl_add_u64 v[24:25], v[24:25], 0, v[184:185]
	v_cvt_pk_bf16_f32 v18, v62, v63
	v_cvt_pk_bf16_f32 v19, v64, v65
	v_cvt_pk_bf16_f32 v20, v42, v43
	v_cvt_pk_bf16_f32 v21, v44, v45
	global_store_dwordx4 v[24:25], v[18:21], off
	v_or_b32_e32 v24, 32, v26
	v_mad_i64_i32 v[24:25], s[50:51], v24, s81, v[22:23]
	v_lshl_add_u64 v[24:25], v[24:25], 0, s[30:31]
	v_lshl_add_u64 v[24:25], v[24:25], 0, v[184:185]
	v_cvt_pk_bf16_f32 v18, v50, v51
	v_cvt_pk_bf16_f32 v19, v52, v53
	v_cvt_pk_bf16_f32 v20, v38, v39
	v_cvt_pk_bf16_f32 v21, v40, v41
	global_store_dwordx4 v[24:25], v[18:21], off
	v_or_b32_e32 v24, 48, v26
	v_mad_i64_i32 v[24:25], s[50:51], v24, s81, v[22:23]
	v_lshl_add_u64 v[24:25], v[24:25], 0, s[30:31]
	v_lshl_add_u64 v[24:25], v[24:25], 0, v[184:185]
	v_cvt_pk_bf16_f32 v18, v46, v47
	v_cvt_pk_bf16_f32 v19, v48, v49
	v_cvt_pk_bf16_f32 v20, v34, v35
	v_cvt_pk_bf16_f32 v21, v36, v37
	global_store_dwordx4 v[24:25], v[18:21], off
	v_add_u32_e32 v24, 0x80, v26
	s_nop 0
	v_cvt_pk_bf16_f32 v18, v102, v103
	v_cvt_pk_bf16_f32 v19, v104, v105
	v_cvt_pk_bf16_f32 v20, v10, v11
	v_mad_i64_i32 v[10:11], s[50:51], v24, s81, v[22:23]
	v_lshl_add_u64 v[10:11], v[10:11], 0, s[30:31]
	v_lshl_add_u64 v[10:11], v[10:11], 0, v[184:185]
	v_cvt_pk_bf16_f32 v21, v12, v13
	global_store_dwordx4 v[10:11], v[18:21], off
	v_cvt_pk_bf16_f32 v10, v94, v95
	v_cvt_pk_bf16_f32 v11, v96, v97
	v_cvt_pk_bf16_f32 v12, v14, v15
	v_add_u32_e32 v14, 0x90, v26
	v_mad_i64_i32 v[14:15], s[50:51], v14, s81, v[22:23]
	v_lshl_add_u64 v[14:15], v[14:15], 0, s[30:31]
	v_lshl_add_u64 v[14:15], v[14:15], 0, v[184:185]
	v_cvt_pk_bf16_f32 v13, v16, v17
	global_store_dwordx4 v[14:15], v[10:13], off
	s_nop 1
	v_cvt_pk_bf16_f32 v10, v90, v91
	v_cvt_pk_bf16_f32 v11, v92, v93
	v_cvt_pk_bf16_f32 v12, v6, v7
	v_add_u32_e32 v6, 0xa0, v26
	v_mad_i64_i32 v[6:7], s[50:51], v6, s81, v[22:23]
	v_lshl_add_u64 v[6:7], v[6:7], 0, s[30:31]
	v_lshl_add_u64 v[6:7], v[6:7], 0, v[184:185]
	v_cvt_pk_bf16_f32 v13, v8, v9
	global_store_dwordx4 v[6:7], v[10:13], off
	v_cvt_pk_bf16_f32 v6, v86, v87
	v_cvt_pk_bf16_f32 v7, v88, v89
	v_cvt_pk_bf16_f32 v8, v2, v3
	v_add_u32_e32 v2, 0xb0, v26
	v_mad_i64_i32 v[2:3], s[50:51], v2, s81, v[22:23]
	v_lshl_add_u64 v[2:3], v[2:3], 0, s[30:31]
	v_lshl_add_u64 v[2:3], v[2:3], 0, v[184:185]
	v_cvt_pk_bf16_f32 v9, v4, v5
	global_store_dwordx4 v[2:3], v[6:9], off
	s_cbranch_vccnz .LBB0_1313
	s_andn2_b64 vcc, exec, s[20:21]
	s_mov_b32 s43, s44
	s_mov_b64 s[30:31], s[16:17]
	s_mov_b64 s[4:5], s[40:41]
	s_cbranch_vccnz .LBB0_1350
	s_ashr_i32 s4, s44, 5
	s_mul_hi_i32 s5, s4, 0x5800
	s_mulk_i32 s4, 0x5800
	s_add_u32 s30, s3, s4
	s_addc_u32 s31, s6, s5
	s_mov_b32 s43, s42
	s_mov_b64 s[4:5], s[14:15]
